# GEMM loops: per-segment priority flips inverted (load segments prio 1, MFMA clusters prio 0), static contrast restored after each GEMM
# baseline (speedup 1.0000x reference)
; #define PG8_STAGE(bufoff, gbase, voff) do { _Pragma("unroll") for (int _i = 0; _i < 2; ++_i) \
;         __builtin_amdgcn_global_load_lds((const unsigned*)((const char*)(gbase) + (voff)[_i]), (PG8_LAS unsigned*)(lds + (bufoff) + ldsw + _i * 8192), 16, 0, 0); } while (0)
; #define PG8_LDA(dst, b, h) do { _Pragma("unroll") for (int m = 0; m < 4; ++m) _Pragma("unroll") for (int k = 0; k < 2; ++k) dst[m][k] = *(const PG8_LAS bf16x8*)(lds + PG8_SA(b, h) + aoff + m * 2048 + k * 1024); } while (0)
; #define PG8_LDB(dst, b, h) do { _Pragma("unroll") for (int n = 0; n < 2; ++n) _Pragma("unroll") for (int k = 0; k < 2; ++k) dst[n][k] = *(const PG8_LAS bf16x8*)(lds + PG8_SB(b, h) + boff + n * 2048 + k * 1024); } while (0)
; #define PG8_MMA(ai, bj, At, Bt) do { __builtin_amdgcn_s_setprio(1); _Pragma("unroll") for (int m = 0; m < 4; ++m) _Pragma("unroll") for (int n = 0; n < 2; ++n) _Pragma("unroll") for (int k = 0; k < 2; ++k) \
;         acc[ai][bj][m][n] = __builtin_amdgcn_mfma_f32_16x16x32_bf16(Bt[n][k], At[m][k], acc[ai][bj][m][n], 0, 0, 0); __builtin_amdgcn_s_setprio(0); } while (0)
; #define PG8_WAIT_L(n) asm volatile("s_waitcnt lgkmcnt(" #n ")" ::: "memory")
; #define PG8_BAR __builtin_amdgcn_s_barrier()
; #define PG8_SCHED __builtin_amdgcn_sched_barrier(0)
; template <class Epi, class Sched>
; __device__ __forceinline__ void gemm_phase(PG8_LAS unsigned char* lds, const Gemm g, const Sched& S, const Epi& E) {
;     ...
;             PG8_LDB(B0, 0, 0); PG8_SCHED; PG8_LDA(At, 0, 0); PG8_STAGE(PG8_SA(1, 1), a1 + hstep, voffA);
;             PG8_WAIT_L(8); PG8_BAR; PG8_WAIT_L(0); PG8_MMA(0, 0, At, B0); PG8_BAR; PG8_SCHED;
;             PG8_LDB(B1, 0, 1); PG8_STAGE(PG8_SB(0, 0), b2, voffB);
;             PG8_BAR; PG8_WAIT_L(0); PG8_MMA(0, 1, At, B1); PG8_BAR;
;             PG8_LDA(At, 0, 1); PG8_STAGE(PG8_SA(0, 0), a2, voffA);
;             PG8_BAR; PG8_WAIT_L(0); PG8_MMA(1, 0, At, B0); PG8_BAR; PG8_SCHED;
.LBB0_185:
	s_add_u32 s16, s14, 0xfffc0080
	s_addc_u32 s17, s15, -1
	s_add_i32 s80, 0, 0x10000
	v_add_u32_e32 v140, s80, v231
	ds_read_b128 v[128:131], v140
	ds_read_b128 v[132:135], v140 offset:1024
	ds_read_b128 v[136:139], v140 offset:2048
	ds_read_b128 v[140:143], v140 offset:3072
	s_cmp_eq_u32 s79, 12
	s_cselect_b32 s19, s7, s17
	s_cselect_b32 s18, s13, s16
	s_cselect_b32 s17, s1, s78
	s_cselect_b32 s16, s76, s77
	v_lshl_add_u64 v[176:177], s[14:15], 0, v[200:201]
	s_add_i32 m0, s46, 0xc000
	ds_read_b128 v[144:147], v232
	ds_read_b128 v[148:151], v232 offset:1024
	ds_read_b128 v[152:155], v232 offset:2048
	ds_read_b128 v[156:159], v232 offset:3072
	ds_read_b128 v[160:163], v232 offset:4096
	ds_read_b128 v[164:167], v232 offset:5120
	ds_read_b128 v[168:171], v232 offset:6144
	ds_read_b128 v[172:175], v232 offset:7168
	global_load_lds_dwordx4 v[176:177], off
	v_lshl_add_u64 v[176:177], s[14:15], 0, v[202:203]
	s_add_i32 m0, s46, 0xe000
	s_nop 0
	global_load_lds_dwordx4 v[176:177], off
	s_waitcnt lgkmcnt(8)
	s_barrier
	s_waitcnt lgkmcnt(0)
	s_setprio 0
	s_waitcnt lgkmcnt(0)
	v_mfma_f32_16x16x32_bf16 v[124:127], v[128:131], v[144:147], v[124:127]
	v_mfma_f32_16x16x32_bf16 v[116:119], v[136:139], v[144:147], v[116:119]
	v_mfma_f32_16x16x32_bf16 v[108:111], v[128:131], v[152:155], v[108:111]
	v_mfma_f32_16x16x32_bf16 v[100:103], v[136:139], v[152:155], v[100:103]
	v_mfma_f32_16x16x32_bf16 v[92:95], v[128:131], v[160:163], v[92:95]
	v_mfma_f32_16x16x32_bf16 v[84:87], v[136:139], v[160:163], v[84:87]
	v_mfma_f32_16x16x32_bf16 v[76:79], v[128:131], v[168:171], v[76:79]
	v_mfma_f32_16x16x32_bf16 v[68:71], v[136:139], v[168:171], v[68:71]
	v_mfma_f32_16x16x32_bf16 v[124:127], v[132:135], v[148:151], v[124:127]
	v_mfma_f32_16x16x32_bf16 v[116:119], v[140:143], v[148:151], v[116:119]
	v_mfma_f32_16x16x32_bf16 v[108:111], v[132:135], v[156:159], v[108:111]
	v_mfma_f32_16x16x32_bf16 v[100:103], v[140:143], v[156:159], v[100:103]
	v_mfma_f32_16x16x32_bf16 v[92:95], v[132:135], v[164:167], v[92:95]
	v_mfma_f32_16x16x32_bf16 v[84:87], v[140:143], v[164:167], v[84:87]
	v_mfma_f32_16x16x32_bf16 v[76:79], v[132:135], v[172:175], v[76:79]
	v_mfma_f32_16x16x32_bf16 v[68:71], v[140:143], v[172:175], v[68:71]
	s_setprio 1
	s_barrier
	s_add_i32 s82, 0, 0x14000
	s_add_i32 s80, s80, s21
	v_add_u32_e32 v180, s82, v231
	v_lshl_add_u64 v[218:219], s[16:17], 0, v[188:189]
	s_mov_b32 m0, s80
	ds_read_b128 v[176:179], v180
	ds_read_b128 v[206:209], v180 offset:1024
	ds_read_b128 v[210:213], v180 offset:2048
	ds_read_b128 v[214:217], v180 offset:3072
	global_load_lds_dwordx4 v[218:219], off
	v_lshl_add_u64 v[220:221], s[16:17], 0, v[184:185]
	s_add_i32 m0, s80, 0x2000
	s_nop 0
	global_load_lds_dwordx4 v[220:221], off
	s_barrier
	s_waitcnt lgkmcnt(0)
	s_setprio 0
	s_waitcnt lgkmcnt(0)
	v_mfma_f32_16x16x32_bf16 v[120:123], v[176:179], v[144:147], v[120:123]
	v_mfma_f32_16x16x32_bf16 v[112:115], v[210:213], v[144:147], v[112:115]
	v_mfma_f32_16x16x32_bf16 v[104:107], v[176:179], v[152:155], v[104:107]
	v_mfma_f32_16x16x32_bf16 v[96:99], v[210:213], v[152:155], v[96:99]
	v_mfma_f32_16x16x32_bf16 v[88:91], v[176:179], v[160:163], v[88:91]
	v_mfma_f32_16x16x32_bf16 v[80:83], v[210:213], v[160:163], v[80:83]
	v_mfma_f32_16x16x32_bf16 v[72:75], v[176:179], v[168:171], v[72:75]
	v_mfma_f32_16x16x32_bf16 v[64:67], v[210:213], v[168:171], v[64:67]
	v_mfma_f32_16x16x32_bf16 v[120:123], v[206:209], v[148:151], v[120:123]
	v_mfma_f32_16x16x32_bf16 v[112:115], v[214:217], v[148:151], v[112:115]
	v_mfma_f32_16x16x32_bf16 v[104:107], v[206:209], v[156:159], v[104:107]
	v_mfma_f32_16x16x32_bf16 v[96:99], v[214:217], v[156:159], v[96:99]
	v_mfma_f32_16x16x32_bf16 v[88:91], v[206:209], v[164:167], v[88:91]
	v_mfma_f32_16x16x32_bf16 v[80:83], v[214:217], v[164:167], v[80:83]
	v_mfma_f32_16x16x32_bf16 v[72:75], v[206:209], v[172:175], v[72:75]
	v_mfma_f32_16x16x32_bf16 v[64:67], v[214:217], v[172:175], v[64:67]
	s_setprio 1
	s_mov_b32 m0, s46
	v_lshl_add_u64 v[222:223], s[18:19], 0, v[190:191]
	s_barrier
	ds_read_b128 v[144:147], v232 offset:16384
	ds_read_b128 v[148:151], v232 offset:17408
	ds_read_b128 v[152:155], v232 offset:18432
	ds_read_b128 v[156:159], v232 offset:19456
	ds_read_b128 v[160:163], v232 offset:20480
	ds_read_b128 v[164:167], v232 offset:21504
	ds_read_b128 v[168:171], v232 offset:22528
	ds_read_b128 v[172:175], v232 offset:23552
	global_load_lds_dwordx4 v[222:223], off
	v_lshl_add_u64 v[224:225], s[18:19], 0, v[186:187]
	s_mov_b32 m0, s47
	s_nop 0
	global_load_lds_dwordx4 v[224:225], off
	s_barrier
	s_waitcnt lgkmcnt(0)
	s_setprio 0
	s_waitcnt lgkmcnt(0)
	v_mfma_f32_16x16x32_bf16 v[60:63], v[128:131], v[144:147], v[60:63]
	v_mfma_f32_16x16x32_bf16 v[52:55], v[136:139], v[144:147], v[52:55]
	v_mfma_f32_16x16x32_bf16 v[44:47], v[128:131], v[152:155], v[44:47]
	v_mfma_f32_16x16x32_bf16 v[36:39], v[136:139], v[152:155], v[36:39]
	v_mfma_f32_16x16x32_bf16 v[28:31], v[128:131], v[160:163], v[28:31]
	v_mfma_f32_16x16x32_bf16 v[20:23], v[136:139], v[160:163], v[20:23]
	v_mfma_f32_16x16x32_bf16 v[12:15], v[128:131], v[168:171], v[12:15]
	v_mfma_f32_16x16x32_bf16 v[4:7], v[136:139], v[168:171], v[4:7]
	v_mfma_f32_16x16x32_bf16 v[60:63], v[132:135], v[148:151], v[60:63]
	v_mfma_f32_16x16x32_bf16 v[52:55], v[140:143], v[148:151], v[52:55]
	v_mfma_f32_16x16x32_bf16 v[44:47], v[132:135], v[156:159], v[44:47]
	v_mfma_f32_16x16x32_bf16 v[36:39], v[140:143], v[156:159], v[36:39]
	v_mfma_f32_16x16x32_bf16 v[28:31], v[132:135], v[164:167], v[28:31]
	v_mfma_f32_16x16x32_bf16 v[20:23], v[140:143], v[164:167], v[20:23]
	v_mfma_f32_16x16x32_bf16 v[12:15], v[132:135], v[172:175], v[12:15]
	v_mfma_f32_16x16x32_bf16 v[4:7], v[140:143], v[172:175], v[4:7]
	s_setprio 1
	s_barrier
; #define PG8_STAGE(bufoff, gbase, voff) do { _Pragma("unroll") for (int _i = 0; _i < 2; ++_i) \
;         __builtin_amdgcn_global_load_lds((const unsigned*)((const char*)(gbase) + (voff)[_i]), (PG8_LAS unsigned*)(lds + (bufoff) + ldsw + _i * 8192), 16, 0, 0); } while (0)
; #define PG8_LDA(dst, b, h) do { _Pragma("unroll") for (int m = 0; m < 4; ++m) _Pragma("unroll") for (int k = 0; k < 2; ++k) dst[m][k] = *(const PG8_LAS bf16x8*)(lds + PG8_SA(b, h) + aoff + m * 2048 + k * 1024); } while (0)
; #define PG8_LDB(dst, b, h) do { _Pragma("unroll") for (int n = 0; n < 2; ++n) _Pragma("unroll") for (int k = 0; k < 2; ++k) dst[n][k] = *(const PG8_LAS bf16x8*)(lds + PG8_SB(b, h) + boff + n * 2048 + k * 1024); } while (0)
; #define PG8_MMA(ai, bj, At, Bt) do { __builtin_amdgcn_s_setprio(1); _Pragma("unroll") for (int m = 0; m < 4; ++m) _Pragma("unroll") for (int n = 0; n < 2; ++n) _Pragma("unroll") for (int k = 0; k < 2; ++k) \
;         acc[ai][bj][m][n] = __builtin_amdgcn_mfma_f32_16x16x32_bf16(Bt[n][k], At[m][k], acc[ai][bj][m][n], 0, 0, 0); __builtin_amdgcn_s_setprio(0); } while (0)
; #define PG8_WAIT_V(n) asm volatile("s_waitcnt vmcnt(" #n ")" ::: "memory")
; #define PG8_WAIT_L(n) asm volatile("s_waitcnt lgkmcnt(" #n ")" ::: "memory")
; #define PG8_BAR __builtin_amdgcn_s_barrier()
; #define PG8_SCHED __builtin_amdgcn_sched_barrier(0)
; template <class Epi, class Sched>
; __device__ __forceinline__ void gemm_phase(PG8_LAS unsigned char* lds, const Gemm g, const Sched& S, const Epi& E) {
;     ...
;             PG8_STAGE(PG8_SB(0, 1), b2 + hstep, voffB);
;             PG8_WAIT_V(6); PG8_BAR; PG8_MMA(1, 1, At, B1); PG8_BAR;
;             PG8_LDB(B0, 1, 0); PG8_SCHED; PG8_LDA(At, 1, 0); PG8_STAGE(PG8_SA(0, 1), a2 + hstep, voffA);
;             PG8_WAIT_L(8); PG8_BAR; PG8_WAIT_L(0); PG8_MMA(0, 0, At, B0); PG8_BAR; PG8_SCHED;
;             PG8_LDB(B1, 1, 1); PG8_STAGE(PG8_SB(1, 0), b3, voffB);
;             PG8_BAR; PG8_WAIT_L(0); PG8_MMA(0, 1, At, B1); PG8_BAR;
;             PG8_LDA(At, 1, 1); PG8_STAGE(PG8_SA(1, 0), a3, voffA);
	s_add_u32 s80, s16, 0x40000
	s_addc_u32 s81, s17, 0
	s_add_i32 s82, s82, s21
	v_lshl_add_u64 v[128:129], s[80:81], 0, v[188:189]
	s_mov_b32 m0, s82
	s_nop 0
	global_load_lds_dwordx4 v[128:129], off
	v_lshl_add_u64 v[128:129], s[80:81], 0, v[184:185]
	s_add_i32 m0, s82, 0x2000
	s_nop 0
	global_load_lds_dwordx4 v[128:129], off
	s_waitcnt vmcnt(6)
	s_barrier
	s_setprio 0
	v_mfma_f32_16x16x32_bf16 v[56:59], v[176:179], v[144:147], v[56:59]
	v_mfma_f32_16x16x32_bf16 v[48:51], v[210:213], v[144:147], v[48:51]
	v_mfma_f32_16x16x32_bf16 v[40:43], v[176:179], v[152:155], v[40:43]
	v_mfma_f32_16x16x32_bf16 v[32:35], v[210:213], v[152:155], v[32:35]
	v_mfma_f32_16x16x32_bf16 v[24:27], v[176:179], v[160:163], v[24:27]
	v_mfma_f32_16x16x32_bf16 v[16:19], v[210:213], v[160:163], v[16:19]
	v_mfma_f32_16x16x32_bf16 v[8:11], v[176:179], v[168:171], v[8:11]
	v_mfma_f32_16x16x32_bf16 v[0:3], v[210:213], v[168:171], v[0:3]
	v_mfma_f32_16x16x32_bf16 v[56:59], v[206:209], v[148:151], v[56:59]
	v_mfma_f32_16x16x32_bf16 v[48:51], v[214:217], v[148:151], v[48:51]
	v_mfma_f32_16x16x32_bf16 v[40:43], v[206:209], v[156:159], v[40:43]
	v_mfma_f32_16x16x32_bf16 v[32:35], v[214:217], v[156:159], v[32:35]
	v_mfma_f32_16x16x32_bf16 v[24:27], v[206:209], v[164:167], v[24:27]
	v_mfma_f32_16x16x32_bf16 v[16:19], v[214:217], v[164:167], v[16:19]
	v_mfma_f32_16x16x32_bf16 v[8:11], v[206:209], v[172:175], v[8:11]
	v_mfma_f32_16x16x32_bf16 v[0:3], v[214:217], v[172:175], v[0:3]
	s_setprio 1
	s_add_i32 s80, 0, 0x18000
	v_add_u32_e32 v140, s80, v231
	s_barrier
	ds_read_b128 v[128:131], v140
	ds_read_b128 v[132:135], v140 offset:1024
	ds_read_b128 v[136:139], v140 offset:2048
	ds_read_b128 v[140:143], v140 offset:3072
	s_add_u32 s18, s18, 0x40000
	s_addc_u32 s19, s19, 0
	s_mov_b32 m0, s70
	v_lshl_add_u64 v[176:177], s[18:19], 0, v[190:191]
	ds_read_b128 v[144:147], v232 offset:32768
	ds_read_b128 v[148:151], v232 offset:33792
	ds_read_b128 v[152:155], v232 offset:34816
	ds_read_b128 v[156:159], v232 offset:35840
	ds_read_b128 v[160:163], v232 offset:36864
	ds_read_b128 v[164:167], v232 offset:37888
	ds_read_b128 v[168:171], v232 offset:38912
	ds_read_b128 v[172:175], v232 offset:39936
	global_load_lds_dwordx4 v[176:177], off
	v_lshl_add_u64 v[176:177], s[18:19], 0, v[186:187]
	s_mov_b32 m0, s71
	s_nop 0
	global_load_lds_dwordx4 v[176:177], off
	s_waitcnt lgkmcnt(8)
	s_barrier
	s_waitcnt lgkmcnt(0)
	s_setprio 0
	s_waitcnt lgkmcnt(0)
	v_mfma_f32_16x16x32_bf16 v[124:127], v[128:131], v[144:147], v[124:127]
	v_mfma_f32_16x16x32_bf16 v[116:119], v[136:139], v[144:147], v[116:119]
	v_mfma_f32_16x16x32_bf16 v[108:111], v[128:131], v[152:155], v[108:111]
	v_mfma_f32_16x16x32_bf16 v[100:103], v[136:139], v[152:155], v[100:103]
	v_mfma_f32_16x16x32_bf16 v[92:95], v[128:131], v[160:163], v[92:95]
	v_mfma_f32_16x16x32_bf16 v[84:87], v[136:139], v[160:163], v[84:87]
	v_mfma_f32_16x16x32_bf16 v[76:79], v[128:131], v[168:171], v[76:79]
	v_mfma_f32_16x16x32_bf16 v[68:71], v[136:139], v[168:171], v[68:71]
	v_mfma_f32_16x16x32_bf16 v[124:127], v[132:135], v[148:151], v[124:127]
	v_mfma_f32_16x16x32_bf16 v[116:119], v[140:143], v[148:151], v[116:119]
	v_mfma_f32_16x16x32_bf16 v[108:111], v[132:135], v[156:159], v[108:111]
	v_mfma_f32_16x16x32_bf16 v[100:103], v[140:143], v[156:159], v[100:103]
	v_mfma_f32_16x16x32_bf16 v[92:95], v[132:135], v[164:167], v[92:95]
	v_mfma_f32_16x16x32_bf16 v[84:87], v[140:143], v[164:167], v[84:87]
	v_mfma_f32_16x16x32_bf16 v[76:79], v[132:135], v[172:175], v[76:79]
	v_mfma_f32_16x16x32_bf16 v[68:71], v[140:143], v[172:175], v[68:71]
	s_setprio 1
	s_barrier
	s_add_i32 s18, 0, 0x1c000
	s_add_i32 s19, s80, s21
	v_add_u32_e32 v180, s18, v231
	v_lshl_add_u64 v[218:219], v[218:219], 0, s[38:39]
	s_mov_b32 m0, s19
	ds_read_b128 v[176:179], v180
	ds_read_b128 v[206:209], v180 offset:1024
	ds_read_b128 v[210:213], v180 offset:2048
	ds_read_b128 v[214:217], v180 offset:3072
	global_load_lds_dwordx4 v[218:219], off
	v_lshl_add_u64 v[218:219], v[220:221], 0, s[38:39]
	s_add_i32 m0, s19, 0x2000
	s_nop 0
	global_load_lds_dwordx4 v[218:219], off
	s_barrier
	s_waitcnt lgkmcnt(0)
	s_setprio 0
	s_waitcnt lgkmcnt(0)
	v_mfma_f32_16x16x32_bf16 v[120:123], v[176:179], v[144:147], v[120:123]
	v_mfma_f32_16x16x32_bf16 v[112:115], v[210:213], v[144:147], v[112:115]
	v_mfma_f32_16x16x32_bf16 v[104:107], v[176:179], v[152:155], v[104:107]
	v_mfma_f32_16x16x32_bf16 v[96:99], v[210:213], v[152:155], v[96:99]
	v_mfma_f32_16x16x32_bf16 v[88:91], v[176:179], v[160:163], v[88:91]
	v_mfma_f32_16x16x32_bf16 v[80:83], v[210:213], v[160:163], v[80:83]
	v_mfma_f32_16x16x32_bf16 v[72:75], v[176:179], v[168:171], v[72:75]
	v_mfma_f32_16x16x32_bf16 v[64:67], v[210:213], v[168:171], v[64:67]
	v_mfma_f32_16x16x32_bf16 v[120:123], v[206:209], v[148:151], v[120:123]
	v_mfma_f32_16x16x32_bf16 v[112:115], v[214:217], v[148:151], v[112:115]
	v_mfma_f32_16x16x32_bf16 v[104:107], v[206:209], v[156:159], v[104:107]
	v_mfma_f32_16x16x32_bf16 v[96:99], v[214:217], v[156:159], v[96:99]
	v_mfma_f32_16x16x32_bf16 v[88:91], v[206:209], v[164:167], v[88:91]
	v_mfma_f32_16x16x32_bf16 v[80:83], v[214:217], v[164:167], v[80:83]
	v_mfma_f32_16x16x32_bf16 v[72:75], v[206:209], v[172:175], v[72:75]
	v_mfma_f32_16x16x32_bf16 v[64:67], v[214:217], v[172:175], v[64:67]
	s_setprio 1
	s_mov_b32 m0, s72
	v_lshl_add_u64 v[218:219], v[222:223], 0, s[38:39]
	s_barrier
	ds_read_b128 v[144:147], v232 offset:49152
	ds_read_b128 v[148:151], v232 offset:50176
	ds_read_b128 v[152:155], v232 offset:51200
	ds_read_b128 v[156:159], v232 offset:52224
	ds_read_b128 v[160:163], v232 offset:53248
	ds_read_b128 v[164:167], v232 offset:54272
	ds_read_b128 v[168:171], v232 offset:55296
	ds_read_b128 v[172:175], v232 offset:56320
	global_load_lds_dwordx4 v[218:219], off
	v_lshl_add_u64 v[218:219], v[224:225], 0, s[38:39]
	s_mov_b32 m0, s73
	s_nop 0
	global_load_lds_dwordx4 v[218:219], off
	s_barrier
; #define PG8_STAGE(bufoff, gbase, voff) do { _Pragma("unroll") for (int _i = 0; _i < 2; ++_i) \
;         __builtin_amdgcn_global_load_lds((const unsigned*)((const char*)(gbase) + (voff)[_i]), (PG8_LAS unsigned*)(lds + (bufoff) + ldsw + _i * 8192), 16, 0, 0); } while (0)
; #define PG8_MMA(ai, bj, At, Bt) do { __builtin_amdgcn_s_setprio(1); _Pragma("unroll") for (int m = 0; m < 4; ++m) _Pragma("unroll") for (int n = 0; n < 2; ++n) _Pragma("unroll") for (int k = 0; k < 2; ++k) \
;         acc[ai][bj][m][n] = __builtin_amdgcn_mfma_f32_16x16x32_bf16(Bt[n][k], At[m][k], acc[ai][bj][m][n], 0, 0, 0); __builtin_amdgcn_s_setprio(0); } while (0)
; #define PG8_WAIT_V(n) asm volatile("s_waitcnt vmcnt(" #n ")" ::: "memory")
; #define PG8_WAIT_L(n) asm volatile("s_waitcnt lgkmcnt(" #n ")" ::: "memory")
; #define PG8_BAR __builtin_amdgcn_s_barrier()
; #define PG8_SCHED __builtin_amdgcn_sched_barrier(0)
; template <class Epi, class Sched>
; __device__ __forceinline__ void gemm_phase(PG8_LAS unsigned char* lds, const Gemm g, const Sched& S, const Epi& E) {
;     ...
;             PG8_BAR; PG8_WAIT_L(0); PG8_MMA(1, 0, At, B0); PG8_BAR; PG8_SCHED;
;             PG8_STAGE(PG8_SB(1, 1), b3 + hstep, voffB);
;             PG8_WAIT_V(6); PG8_BAR; PG8_MMA(1, 1, At, B1); PG8_BAR;
;         }
;         E(acc, cur, wr, wc, fr, fq); S.done(cur);
;         if (!has_next) break;
	s_waitcnt lgkmcnt(0)
	s_setprio 0
	s_waitcnt lgkmcnt(0)
	v_mfma_f32_16x16x32_bf16 v[60:63], v[128:131], v[144:147], v[60:63]
	v_mfma_f32_16x16x32_bf16 v[52:55], v[136:139], v[144:147], v[52:55]
	v_mfma_f32_16x16x32_bf16 v[44:47], v[128:131], v[152:155], v[44:47]
	v_mfma_f32_16x16x32_bf16 v[36:39], v[136:139], v[152:155], v[36:39]
	v_mfma_f32_16x16x32_bf16 v[28:31], v[128:131], v[160:163], v[28:31]
	v_mfma_f32_16x16x32_bf16 v[20:23], v[136:139], v[160:163], v[20:23]
	v_mfma_f32_16x16x32_bf16 v[12:15], v[128:131], v[168:171], v[12:15]
	v_mfma_f32_16x16x32_bf16 v[4:7], v[136:139], v[168:171], v[4:7]
	v_mfma_f32_16x16x32_bf16 v[60:63], v[132:135], v[148:151], v[60:63]
	v_mfma_f32_16x16x32_bf16 v[52:55], v[140:143], v[148:151], v[52:55]
	v_mfma_f32_16x16x32_bf16 v[44:47], v[132:135], v[156:159], v[44:47]
	v_mfma_f32_16x16x32_bf16 v[36:39], v[140:143], v[156:159], v[36:39]
	v_mfma_f32_16x16x32_bf16 v[28:31], v[132:135], v[164:167], v[28:31]
	v_mfma_f32_16x16x32_bf16 v[20:23], v[140:143], v[164:167], v[20:23]
	v_mfma_f32_16x16x32_bf16 v[12:15], v[132:135], v[172:175], v[12:15]
	v_mfma_f32_16x16x32_bf16 v[4:7], v[140:143], v[172:175], v[4:7]
	s_setprio 1
	s_barrier
	s_add_u32 s16, s16, 0x40080
	s_addc_u32 s17, s17, 0
	s_add_i32 s18, s18, s21
	v_lshl_add_u64 v[128:129], s[16:17], 0, v[188:189]
	s_mov_b32 m0, s18
	s_nop 0
	global_load_lds_dwordx4 v[128:129], off
	v_lshl_add_u64 v[128:129], s[16:17], 0, v[184:185]
	s_add_i32 m0, s18, 0x2000
	s_nop 0
	global_load_lds_dwordx4 v[128:129], off
	s_waitcnt vmcnt(6)
	s_barrier
	s_setprio 0
	v_mfma_f32_16x16x32_bf16 v[56:59], v[176:179], v[144:147], v[56:59]
	v_mfma_f32_16x16x32_bf16 v[48:51], v[210:213], v[144:147], v[48:51]
	v_mfma_f32_16x16x32_bf16 v[40:43], v[176:179], v[152:155], v[40:43]
	v_mfma_f32_16x16x32_bf16 v[32:35], v[210:213], v[152:155], v[32:35]
	v_mfma_f32_16x16x32_bf16 v[24:27], v[176:179], v[160:163], v[24:27]
	v_mfma_f32_16x16x32_bf16 v[16:19], v[210:213], v[160:163], v[16:19]
	v_mfma_f32_16x16x32_bf16 v[8:11], v[176:179], v[168:171], v[8:11]
	v_mfma_f32_16x16x32_bf16 v[0:3], v[210:213], v[168:171], v[0:3]
	v_mfma_f32_16x16x32_bf16 v[56:59], v[206:209], v[148:151], v[56:59]
	v_mfma_f32_16x16x32_bf16 v[48:51], v[214:217], v[148:151], v[48:51]
	v_mfma_f32_16x16x32_bf16 v[40:43], v[206:209], v[156:159], v[40:43]
	v_mfma_f32_16x16x32_bf16 v[32:35], v[214:217], v[156:159], v[32:35]
	v_mfma_f32_16x16x32_bf16 v[24:27], v[206:209], v[164:167], v[24:27]
	v_mfma_f32_16x16x32_bf16 v[16:19], v[214:217], v[164:167], v[16:19]
	v_mfma_f32_16x16x32_bf16 v[8:11], v[206:209], v[172:175], v[8:11]
	v_mfma_f32_16x16x32_bf16 v[0:3], v[214:217], v[172:175], v[0:3]
	s_setprio 1
	s_add_i32 s79, s79, 2
	s_add_u32 s14, s14, 0x100
	s_addc_u32 s15, s15, 0
	s_add_u32 s77, s77, 0x100
	s_addc_u32 s78, s78, 0
	s_cmp_gt_u32 s79, 13
	s_barrier
	s_cbranch_scc0 .LBB0_185
	s_cmp_gt_i32 s75, 7
	s_mov_b64 s[14:15], -1
	s_cbranch_scc0 .LBB0_188
; DI void store8(bf16_t* p, f32x4 a, f32x4 b) { u32x4 w = {cvt_pk_bf16(a[0], a[1]), cvt_pk_bf16(a[2], a[3]), cvt_pk_bf16(b[0], b[1]), cvt_pk_bf16(b[2], b[3])}; *(u32x4*)p = w; }
;     DI void operator()(const AccT& acc, const pg8::Unit& u, int wr, int wc, int fr, int fq) const {
;     ...
;         } else {
;             bf16_t* dst = v + (pn - 8) * 256 + cl;
; #pragma unroll
;             for (int ai = 0; ai < 2; ++ai)
; #pragma unroll
;                 for (int m = 0; m < 4; ++m) { const size_t row = (size_t)pm * 256 + lrow0 + ai * 128 + m * 16;
; #pragma unroll
;                     for (int bj = 0; bj < 2; ++bj) store8(dst + row * 2048 + bj * 128, acc[ai][bj][m][0], acc[ai][bj][m][1]); }
;         }
	s_lshl_b32 s14, s75, 9
	s_mov_b32 s15, s68
	s_ashr_i32 s13, s12, 31
	v_lshl_add_u64 v[128:129], v[196:197], 0, s[14:15]
	s_lshl_b64 s[14:15], s[12:13], 20
	v_lshl_add_u64 v[128:129], v[128:129], 0, s[14:15]
	v_lshl_add_u64 v[128:129], v[128:129], 0, v[194:195]
	v_cvt_pk_bf16_f32 v130, v124, v125
	v_cvt_pk_bf16_f32 v131, v126, v127
	v_cvt_pk_bf16_f32 v132, v116, v117
	v_cvt_pk_bf16_f32 v133, v118, v119
	s_mov_b32 s1, 0xf000
	global_store_dwordx4 v[128:129], v[130:133], off offset:-4096
	v_add_co_u32_e32 v134, vcc, s1, v128
	s_nop 0
	v_cvt_pk_bf16_f32 v130, v120, v121
	v_cvt_pk_bf16_f32 v131, v122, v123
	v_cvt_pk_bf16_f32 v132, v112, v113
	v_cvt_pk_bf16_f32 v133, v114, v115
	global_store_dwordx4 v[128:129], v[130:133], off offset:-3840
	v_addc_co_u32_e32 v135, vcc, 0, v129, vcc
	s_nop 0
	v_cvt_pk_bf16_f32 v130, v108, v109
	v_cvt_pk_bf16_f32 v131, v110, v111
	v_cvt_pk_bf16_f32 v132, v100, v101
	v_cvt_pk_bf16_f32 v133, v102, v103
	s_mov_b32 s1, 0x1f000
	global_store_dwordx4 v[134:135], v[130:133], off
	s_mov_b64 s[14:15], 0
	s_nop 0
	v_cvt_pk_bf16_f32 v130, v104, v105
	v_cvt_pk_bf16_f32 v131, v106, v107
	v_cvt_pk_bf16_f32 v132, v96, v97
	v_cvt_pk_bf16_f32 v133, v98, v99
	global_store_dwordx4 v[134:135], v[130:133], off offset:256
	v_add_co_u32_e32 v134, vcc, s1, v128
	s_nop 0
	v_cvt_pk_bf16_f32 v130, v92, v93
	v_cvt_pk_bf16_f32 v131, v94, v95
	v_cvt_pk_bf16_f32 v132, v84, v85
	v_cvt_pk_bf16_f32 v133, v86, v87
	s_nop 0
	v_addc_co_u32_e32 v135, vcc, 0, v129, vcc
	s_mov_b32 s1, 0x2f000
	global_store_dwordx4 v[134:135], v[130:133], off
	s_nop 1
	v_cvt_pk_bf16_f32 v130, v88, v89
	v_cvt_pk_bf16_f32 v131, v90, v91
	v_cvt_pk_bf16_f32 v132, v80, v81
	v_cvt_pk_bf16_f32 v133, v82, v83
	global_store_dwordx4 v[134:135], v[130:133], off offset:256
	v_add_co_u32_e32 v134, vcc, s1, v128
	s_nop 0
	v_cvt_pk_bf16_f32 v130, v76, v77
	v_cvt_pk_bf16_f32 v131, v78, v79
	v_cvt_pk_bf16_f32 v132, v68, v69
	v_cvt_pk_bf16_f32 v133, v70, v71
	s_nop 0
	v_addc_co_u32_e32 v135, vcc, 0, v129, vcc
	s_mov_b32 s1, 0x7f000
	global_store_dwordx4 v[134:135], v[130:133], off
	s_nop 1
	v_cvt_pk_bf16_f32 v130, v72, v73
	v_cvt_pk_bf16_f32 v131, v74, v75
	v_cvt_pk_bf16_f32 v132, v64, v65
	v_cvt_pk_bf16_f32 v133, v66, v67
	global_store_dwordx4 v[134:135], v[130:133], off offset:256
	v_add_co_u32_e32 v134, vcc, s1, v128
	s_nop 0
	v_cvt_pk_bf16_f32 v130, v60, v61
	v_cvt_pk_bf16_f32 v131, v62, v63
	v_cvt_pk_bf16_f32 v132, v52, v53
	v_cvt_pk_bf16_f32 v133, v54, v55
	s_nop 0
	v_addc_co_u32_e32 v135, vcc, 0, v129, vcc
	s_mov_b32 s1, 0x8f000
	global_store_dwordx4 v[134:135], v[130:133], off
	s_nop 1
	v_cvt_pk_bf16_f32 v130, v56, v57
	v_cvt_pk_bf16_f32 v131, v58, v59
	v_cvt_pk_bf16_f32 v132, v48, v49
	v_cvt_pk_bf16_f32 v133, v50, v51
	global_store_dwordx4 v[134:135], v[130:133], off offset:256
	v_add_co_u32_e32 v134, vcc, s1, v128
	s_nop 0
	v_cvt_pk_bf16_f32 v130, v44, v45
	v_cvt_pk_bf16_f32 v131, v46, v47
	v_cvt_pk_bf16_f32 v132, v36, v37
	v_cvt_pk_bf16_f32 v133, v38, v39
	s_nop 0
	v_addc_co_u32_e32 v135, vcc, 0, v129, vcc
	s_mov_b32 s1, 0x9f000
	global_store_dwordx4 v[134:135], v[130:133], off
	s_nop 1
	v_cvt_pk_bf16_f32 v130, v40, v41
	v_cvt_pk_bf16_f32 v131, v42, v43
	v_cvt_pk_bf16_f32 v132, v32, v33
	v_cvt_pk_bf16_f32 v133, v34, v35
	global_store_dwordx4 v[134:135], v[130:133], off offset:256
	v_add_co_u32_e32 v134, vcc, s1, v128
	s_nop 0
	v_cvt_pk_bf16_f32 v130, v28, v29
	v_cvt_pk_bf16_f32 v131, v30, v31
	v_cvt_pk_bf16_f32 v132, v20, v21
	v_cvt_pk_bf16_f32 v133, v22, v23
	s_nop 0
	v_addc_co_u32_e32 v135, vcc, 0, v129, vcc
	s_mov_b32 s1, 0xaf000
	global_store_dwordx4 v[134:135], v[130:133], off
	s_nop 1
	v_cvt_pk_bf16_f32 v130, v24, v25
	v_cvt_pk_bf16_f32 v131, v26, v27
	v_cvt_pk_bf16_f32 v132, v16, v17
	v_cvt_pk_bf16_f32 v133, v18, v19
	global_store_dwordx4 v[134:135], v[130:133], off offset:256
	v_add_co_u32_e32 v134, vcc, s1, v128
	s_nop 0
	v_cvt_pk_bf16_f32 v130, v12, v13
	v_cvt_pk_bf16_f32 v131, v14, v15
	v_cvt_pk_bf16_f32 v132, v4, v5
	v_cvt_pk_bf16_f32 v133, v6, v7
	s_nop 0
	v_addc_co_u32_e32 v135, vcc, 0, v129, vcc
	global_store_dwordx4 v[134:135], v[130:133], off
	v_cvt_pk_bf16_f32 v128, v8, v9
	v_cvt_pk_bf16_f32 v129, v10, v11
	s_nop 1
	v_cvt_pk_bf16_f32 v130, v0, v1
	v_cvt_pk_bf16_f32 v131, v2, v3
	global_store_dwordx4 v[134:135], v[128:131], off offset:256

; #define PG8_WAIT_V(n) asm volatile("s_waitcnt vmcnt(" #n ")" ::: "memory")
; #define PG8_BAR __builtin_amdgcn_s_barrier()
; template <class Epi, class Sched>
; __device__ __forceinline__ void gemm_phase(PG8_LAS unsigned char* lds, const Gemm g, const Sched& S, const Epi& E) {
;     ...
;     PG8_WAIT_V(0);
;     if (wr == 0) PG8_BAR;
;     PG8_BAR;
.LBB0_193:
	s_setprio 0
	v_readfirstlane_b32 s100, v252
	s_nop 3
	s_lshr_b32 s100, s100, 6
	s_cmp_ge_u32 s100, 4
	s_cbranch_scc0 .Lprio_done_g0
	s_setprio 1

; #define PG8_STAGE(bufoff, gbase, voff) do { _Pragma("unroll") for (int _i = 0; _i < 2; ++_i) \
;         __builtin_amdgcn_global_load_lds((const unsigned*)((const char*)(gbase) + (voff)[_i]), (PG8_LAS unsigned*)(lds + (bufoff) + ldsw + _i * 8192), 16, 0, 0); } while (0)
; #define PG8_LDA(dst, b, h) do { _Pragma("unroll") for (int m = 0; m < 4; ++m) _Pragma("unroll") for (int k = 0; k < 2; ++k) dst[m][k] = *(const PG8_LAS bf16x8*)(lds + PG8_SA(b, h) + aoff + m * 2048 + k * 1024); } while (0)
; #define PG8_LDB(dst, b, h) do { _Pragma("unroll") for (int n = 0; n < 2; ++n) _Pragma("unroll") for (int k = 0; k < 2; ++k) dst[n][k] = *(const PG8_LAS bf16x8*)(lds + PG8_SB(b, h) + boff + n * 2048 + k * 1024); } while (0)
; #define PG8_MMA(ai, bj, At, Bt) do { __builtin_amdgcn_s_setprio(1); _Pragma("unroll") for (int m = 0; m < 4; ++m) _Pragma("unroll") for (int n = 0; n < 2; ++n) _Pragma("unroll") for (int k = 0; k < 2; ++k) \
;         acc[ai][bj][m][n] = __builtin_amdgcn_mfma_f32_16x16x32_bf16(Bt[n][k], At[m][k], acc[ai][bj][m][n], 0, 0, 0); __builtin_amdgcn_s_setprio(0); } while (0)
; #define PG8_WAIT_L(n) asm volatile("s_waitcnt lgkmcnt(" #n ")" ::: "memory")
; #define PG8_BAR __builtin_amdgcn_s_barrier()
; #define PG8_SCHED __builtin_amdgcn_sched_barrier(0)
; template <class Epi, class Sched>
; __device__ __forceinline__ void gemm_phase(PG8_LAS unsigned char* lds, const Gemm g, const Sched& S, const Epi& E) {
;     ...
;             PG8_LDB(B0, 0, 0); PG8_SCHED; PG8_LDA(At, 0, 0); PG8_STAGE(PG8_SA(1, 1), a1 + hstep, voffA);
;             PG8_WAIT_L(8); PG8_BAR; PG8_WAIT_L(0); PG8_MMA(0, 0, At, B0); PG8_BAR; PG8_SCHED;
;             PG8_LDB(B1, 0, 1); PG8_STAGE(PG8_SB(0, 0), b2, voffB);
;             PG8_BAR; PG8_WAIT_L(0); PG8_MMA(0, 1, At, B1); PG8_BAR;
;             PG8_LDA(At, 0, 1); PG8_STAGE(PG8_SA(0, 0), a2, voffA);
;             PG8_BAR; PG8_WAIT_L(0); PG8_MMA(1, 0, At, B0); PG8_BAR; PG8_SCHED;
.LBB0_516:
	s_add_u32 s70, s20, 0xfffc0080
	s_addc_u32 s71, s21, -1
	s_add_i32 vcc_lo, 0, 0x10000
	v_add_u32_e32 v68, vcc_lo, v206
	ds_read_b128 v[48:51], v68
	ds_read_b128 v[56:59], v68 offset:1024
	ds_read_b128 v[60:63], v68 offset:2048
	ds_read_b128 v[68:71], v68 offset:3072
	s_cmp_eq_u32 s89, 12
	s_cselect_b32 s73, s11, s71
	s_cselect_b32 s72, s17, s70
	s_cselect_b32 s71, s9, s88
	s_cselect_b32 s70, s82, s83
	v_lshl_add_u64 v[192:193], s[20:21], 0, v[176:177]
	s_add_i32 m0, s19, 0xc000
	ds_read_b128 v[128:131], v208
	ds_read_b128 v[140:143], v208 offset:1024
	ds_read_b128 v[148:151], v208 offset:2048
	ds_read_b128 v[156:159], v208 offset:3072
	ds_read_b128 v[160:163], v208 offset:4096
	ds_read_b128 v[164:167], v208 offset:5120
	ds_read_b128 v[184:187], v208 offset:6144
	ds_read_b128 v[188:191], v208 offset:7168
	global_load_lds_dwordx4 v[192:193], off
	v_lshl_add_u64 v[192:193], s[20:21], 0, v[178:179]
	s_add_i32 m0, s19, 0xe000
	s_nop 0
	global_load_lds_dwordx4 v[192:193], off
	s_waitcnt lgkmcnt(8)
	s_barrier
	s_waitcnt lgkmcnt(0)
	s_setprio 0
	s_waitcnt lgkmcnt(0)
	v_mfma_f32_16x16x32_bf16 v[152:155], v[48:51], v[128:131], v[152:155]
	v_mfma_f32_16x16x32_bf16 v[144:147], v[60:63], v[128:131], v[144:147]
	v_mfma_f32_16x16x32_bf16 v[124:127], v[48:51], v[148:151], v[124:127]
	v_mfma_f32_16x16x32_bf16 v[120:123], v[60:63], v[148:151], v[120:123]
	v_mfma_f32_16x16x32_bf16 v[108:111], v[48:51], v[160:163], v[108:111]
	v_mfma_f32_16x16x32_bf16 v[104:107], v[60:63], v[160:163], v[104:107]
	v_mfma_f32_16x16x32_bf16 v[92:95], v[48:51], v[184:187], v[92:95]
	v_mfma_f32_16x16x32_bf16 v[88:91], v[60:63], v[184:187], v[88:91]
	v_mfma_f32_16x16x32_bf16 v[152:155], v[56:59], v[140:143], v[152:155]
	v_mfma_f32_16x16x32_bf16 v[144:147], v[68:71], v[140:143], v[144:147]
	v_mfma_f32_16x16x32_bf16 v[124:127], v[56:59], v[156:159], v[124:127]
	v_mfma_f32_16x16x32_bf16 v[120:123], v[68:71], v[156:159], v[120:123]
	v_mfma_f32_16x16x32_bf16 v[108:111], v[56:59], v[164:167], v[108:111]
	v_mfma_f32_16x16x32_bf16 v[104:107], v[68:71], v[164:167], v[104:107]
	v_mfma_f32_16x16x32_bf16 v[92:95], v[56:59], v[188:191], v[92:95]
	v_mfma_f32_16x16x32_bf16 v[88:91], v[68:71], v[188:191], v[88:91]
	s_setprio 1
	s_barrier
	s_add_i32 s69, 0, 0x14000
	v_add_u32_e32 v204, s69, v206
	s_add_i32 vcc_lo, vcc_lo, s74
	ds_read_b128 v[192:195], v204
	ds_read_b128 v[196:199], v204 offset:1024
	ds_read_b128 v[200:203], v204 offset:2048
	ds_read_b128 v[210:213], v204 offset:3072
	v_lshl_add_u64 v[204:205], s[70:71], 0, v[180:181]
	s_mov_b32 m0, vcc_lo
	v_lshl_add_u64 v[214:215], s[70:71], 0, v[168:169]
	global_load_lds_dwordx4 v[204:205], off
	s_add_i32 m0, vcc_lo, 0x2000
	s_nop 0
	global_load_lds_dwordx4 v[214:215], off
	s_barrier
	s_waitcnt lgkmcnt(0)
	s_setprio 0
	s_waitcnt lgkmcnt(0)
	v_mfma_f32_16x16x32_bf16 v[136:139], v[192:195], v[128:131], v[136:139]
	v_mfma_f32_16x16x32_bf16 v[116:119], v[192:195], v[148:151], v[116:119]
	v_mfma_f32_16x16x32_bf16 v[112:115], v[200:203], v[148:151], v[112:115]
	v_mfma_f32_16x16x32_bf16 v[100:103], v[192:195], v[160:163], v[100:103]
	v_mfma_f32_16x16x32_bf16 v[96:99], v[200:203], v[160:163], v[96:99]
	v_mfma_f32_16x16x32_bf16 v[84:87], v[192:195], v[184:187], v[84:87]
	v_mfma_f32_16x16x32_bf16 v[80:83], v[200:203], v[184:187], v[80:83]
	v_mfma_f32_16x16x32_bf16 v[136:139], v[196:199], v[140:143], v[136:139]
	v_mfma_f32_16x16x32_bf16 v[128:131], v[200:203], v[128:131], v[132:135]
	v_mfma_f32_16x16x32_bf16 v[116:119], v[196:199], v[156:159], v[116:119]
	v_mfma_f32_16x16x32_bf16 v[112:115], v[210:213], v[156:159], v[112:115]
	v_mfma_f32_16x16x32_bf16 v[100:103], v[196:199], v[164:167], v[100:103]
	v_mfma_f32_16x16x32_bf16 v[96:99], v[210:213], v[164:167], v[96:99]
	v_mfma_f32_16x16x32_bf16 v[84:87], v[196:199], v[188:191], v[84:87]
	v_mfma_f32_16x16x32_bf16 v[80:83], v[210:213], v[188:191], v[80:83]
	v_mfma_f32_16x16x32_bf16 v[128:131], v[210:213], v[140:143], v[128:131]
	s_setprio 1
	s_mov_b32 m0, s19
	v_lshl_add_u64 v[216:217], s[72:73], 0, v[172:173]
	s_barrier
	ds_read_b128 v[132:135], v208 offset:16384
	ds_read_b128 v[140:143], v208 offset:17408
	ds_read_b128 v[148:151], v208 offset:18432
	ds_read_b128 v[156:159], v208 offset:19456
	ds_read_b128 v[160:163], v208 offset:20480
	ds_read_b128 v[164:167], v208 offset:21504
	ds_read_b128 v[184:187], v208 offset:22528
	ds_read_b128 v[188:191], v208 offset:23552
	global_load_lds_dwordx4 v[216:217], off
	v_lshl_add_u64 v[218:219], s[72:73], 0, v[170:171]
	s_mov_b32 m0, s76
	s_nop 0
	global_load_lds_dwordx4 v[218:219], off
	s_barrier
	s_waitcnt lgkmcnt(0)
	s_setprio 0
	s_waitcnt lgkmcnt(0)
	v_mfma_f32_16x16x32_bf16 v[76:79], v[48:51], v[132:135], v[76:79]
	v_mfma_f32_16x16x32_bf16 v[72:75], v[60:63], v[132:135], v[72:75]
	v_mfma_f32_16x16x32_bf16 v[44:47], v[48:51], v[148:151], v[44:47]
	v_mfma_f32_16x16x32_bf16 v[40:43], v[60:63], v[148:151], v[40:43]
	v_mfma_f32_16x16x32_bf16 v[28:31], v[48:51], v[160:163], v[28:31]
	v_mfma_f32_16x16x32_bf16 v[24:27], v[60:63], v[160:163], v[24:27]
	v_mfma_f32_16x16x32_bf16 v[12:15], v[48:51], v[184:187], v[12:15]
	v_mfma_f32_16x16x32_bf16 v[8:11], v[60:63], v[184:187], v[8:11]
	v_mfma_f32_16x16x32_bf16 v[76:79], v[56:59], v[140:143], v[76:79]
	v_mfma_f32_16x16x32_bf16 v[72:75], v[68:71], v[140:143], v[72:75]
	v_mfma_f32_16x16x32_bf16 v[44:47], v[56:59], v[156:159], v[44:47]
	v_mfma_f32_16x16x32_bf16 v[40:43], v[68:71], v[156:159], v[40:43]
	v_mfma_f32_16x16x32_bf16 v[28:31], v[56:59], v[164:167], v[28:31]
	v_mfma_f32_16x16x32_bf16 v[24:27], v[68:71], v[164:167], v[24:27]
	v_mfma_f32_16x16x32_bf16 v[12:15], v[56:59], v[188:191], v[12:15]
	v_mfma_f32_16x16x32_bf16 v[8:11], v[68:71], v[188:191], v[8:11]
	s_setprio 1
	s_barrier
; #define PG8_STAGE(bufoff, gbase, voff) do { _Pragma("unroll") for (int _i = 0; _i < 2; ++_i) \
;         __builtin_amdgcn_global_load_lds((const unsigned*)((const char*)(gbase) + (voff)[_i]), (PG8_LAS unsigned*)(lds + (bufoff) + ldsw + _i * 8192), 16, 0, 0); } while (0)
; #define PG8_LDA(dst, b, h) do { _Pragma("unroll") for (int m = 0; m < 4; ++m) _Pragma("unroll") for (int k = 0; k < 2; ++k) dst[m][k] = *(const PG8_LAS bf16x8*)(lds + PG8_SA(b, h) + aoff + m * 2048 + k * 1024); } while (0)
; #define PG8_LDB(dst, b, h) do { _Pragma("unroll") for (int n = 0; n < 2; ++n) _Pragma("unroll") for (int k = 0; k < 2; ++k) dst[n][k] = *(const PG8_LAS bf16x8*)(lds + PG8_SB(b, h) + boff + n * 2048 + k * 1024); } while (0)
; #define PG8_MMA(ai, bj, At, Bt) do { __builtin_amdgcn_s_setprio(1); _Pragma("unroll") for (int m = 0; m < 4; ++m) _Pragma("unroll") for (int n = 0; n < 2; ++n) _Pragma("unroll") for (int k = 0; k < 2; ++k) \
;         acc[ai][bj][m][n] = __builtin_amdgcn_mfma_f32_16x16x32_bf16(Bt[n][k], At[m][k], acc[ai][bj][m][n], 0, 0, 0); __builtin_amdgcn_s_setprio(0); } while (0)
; #define PG8_WAIT_V(n) asm volatile("s_waitcnt vmcnt(" #n ")" ::: "memory")
; #define PG8_WAIT_L(n) asm volatile("s_waitcnt lgkmcnt(" #n ")" ::: "memory")
; #define PG8_BAR __builtin_amdgcn_s_barrier()
; #define PG8_SCHED __builtin_amdgcn_sched_barrier(0)
; template <class Epi, class Sched>
; __device__ __forceinline__ void gemm_phase(PG8_LAS unsigned char* lds, const Gemm g, const Sched& S, const Epi& E) {
;     ...
;             PG8_STAGE(PG8_SB(0, 1), b2 + hstep, voffB);
;             PG8_WAIT_V(6); PG8_BAR; PG8_MMA(1, 1, At, B1); PG8_BAR;
;             PG8_LDB(B0, 1, 0); PG8_SCHED; PG8_LDA(At, 1, 0); PG8_STAGE(PG8_SA(0, 1), a2 + hstep, voffA);
;             PG8_WAIT_L(8); PG8_BAR; PG8_WAIT_L(0); PG8_MMA(0, 0, At, B0); PG8_BAR; PG8_SCHED;
;             PG8_LDB(B1, 1, 1); PG8_STAGE(PG8_SB(1, 0), b3, voffB);
;             PG8_BAR; PG8_WAIT_L(0); PG8_MMA(0, 1, At, B1); PG8_BAR;
;             PG8_LDA(At, 1, 1); PG8_STAGE(PG8_SA(1, 0), a3, voffA);
	s_add_u32 vcc_lo, s70, 0x40000
	s_addc_u32 vcc_hi, s71, 0
	s_add_i32 s69, s69, s74
	v_lshl_add_u64 v[48:49], vcc, 0, v[180:181]
	s_mov_b32 m0, s69
	s_nop 0
	global_load_lds_dwordx4 v[48:49], off
	v_lshl_add_u64 v[48:49], vcc, 0, v[168:169]
	s_add_i32 m0, s69, 0x2000
	s_nop 0
	global_load_lds_dwordx4 v[48:49], off
	s_waitcnt vmcnt(6)
	s_barrier
	s_setprio 0
	v_mfma_f32_16x16x32_bf16 v[52:55], v[200:203], v[132:135], v[52:55]
	v_mfma_f32_16x16x32_bf16 v[36:39], v[192:195], v[148:151], v[36:39]
	v_mfma_f32_16x16x32_bf16 v[32:35], v[200:203], v[148:151], v[32:35]
	v_mfma_f32_16x16x32_bf16 v[20:23], v[192:195], v[160:163], v[20:23]
	v_mfma_f32_16x16x32_bf16 v[16:19], v[200:203], v[160:163], v[16:19]
	v_mfma_f32_16x16x32_bf16 v[4:7], v[192:195], v[184:187], v[4:7]
	v_mfma_f32_16x16x32_bf16 v[0:3], v[200:203], v[184:187], v[0:3]
	v_mfma_f32_16x16x32_bf16 v[48:51], v[192:195], v[132:135], v[64:67]
	v_mfma_f32_16x16x32_bf16 v[52:55], v[210:213], v[140:143], v[52:55]
	v_mfma_f32_16x16x32_bf16 v[36:39], v[196:199], v[156:159], v[36:39]
	v_mfma_f32_16x16x32_bf16 v[32:35], v[210:213], v[156:159], v[32:35]
	v_mfma_f32_16x16x32_bf16 v[20:23], v[196:199], v[164:167], v[20:23]
	v_mfma_f32_16x16x32_bf16 v[16:19], v[210:213], v[164:167], v[16:19]
	v_mfma_f32_16x16x32_bf16 v[4:7], v[196:199], v[188:191], v[4:7]
	v_mfma_f32_16x16x32_bf16 v[0:3], v[210:213], v[188:191], v[0:3]
	v_mfma_f32_16x16x32_bf16 v[48:51], v[196:199], v[140:143], v[48:51]
	s_setprio 1
	s_add_i32 s69, 0, 0x18000
	v_add_u32_e32 v68, s69, v206
	s_barrier
	ds_read_b128 v[56:59], v68
	ds_read_b128 v[60:63], v68 offset:1024
	ds_read_b128 v[64:67], v68 offset:2048
	ds_read_b128 v[68:71], v68 offset:3072
	s_add_u32 s72, s72, 0x40000
	s_addc_u32 s73, s73, 0
	s_mov_b32 m0, s77
	v_lshl_add_u64 v[192:193], s[72:73], 0, v[172:173]
	ds_read_b128 v[132:135], v208 offset:32768
	ds_read_b128 v[140:143], v208 offset:33792
	ds_read_b128 v[148:151], v208 offset:34816
	ds_read_b128 v[156:159], v208 offset:35840
	ds_read_b128 v[160:163], v208 offset:36864
	ds_read_b128 v[164:167], v208 offset:37888
	ds_read_b128 v[184:187], v208 offset:38912
	ds_read_b128 v[188:191], v208 offset:39936
	global_load_lds_dwordx4 v[192:193], off
	v_lshl_add_u64 v[192:193], s[72:73], 0, v[170:171]
	s_mov_b32 m0, s78
	s_nop 0
	global_load_lds_dwordx4 v[192:193], off
	s_waitcnt lgkmcnt(8)
	s_barrier
	s_waitcnt lgkmcnt(0)
	s_setprio 0
	s_waitcnt lgkmcnt(0)
	v_mfma_f32_16x16x32_bf16 v[152:155], v[56:59], v[132:135], v[152:155]
	v_mfma_f32_16x16x32_bf16 v[144:147], v[64:67], v[132:135], v[144:147]
	v_mfma_f32_16x16x32_bf16 v[124:127], v[56:59], v[148:151], v[124:127]
	v_mfma_f32_16x16x32_bf16 v[120:123], v[64:67], v[148:151], v[120:123]
	v_mfma_f32_16x16x32_bf16 v[108:111], v[56:59], v[160:163], v[108:111]
	v_mfma_f32_16x16x32_bf16 v[104:107], v[64:67], v[160:163], v[104:107]
	v_mfma_f32_16x16x32_bf16 v[92:95], v[56:59], v[184:187], v[92:95]
	v_mfma_f32_16x16x32_bf16 v[88:91], v[64:67], v[184:187], v[88:91]
	v_mfma_f32_16x16x32_bf16 v[152:155], v[60:63], v[140:143], v[152:155]
	v_mfma_f32_16x16x32_bf16 v[144:147], v[68:71], v[140:143], v[144:147]
	v_mfma_f32_16x16x32_bf16 v[124:127], v[60:63], v[156:159], v[124:127]
	v_mfma_f32_16x16x32_bf16 v[120:123], v[68:71], v[156:159], v[120:123]
	v_mfma_f32_16x16x32_bf16 v[108:111], v[60:63], v[164:167], v[108:111]
	v_mfma_f32_16x16x32_bf16 v[104:107], v[68:71], v[164:167], v[104:107]
	v_mfma_f32_16x16x32_bf16 v[92:95], v[60:63], v[188:191], v[92:95]
	v_mfma_f32_16x16x32_bf16 v[88:91], v[68:71], v[188:191], v[88:91]
	s_setprio 1
	s_barrier
	s_add_i32 s72, 0, 0x1c000
	s_add_i32 s69, s69, s74
	v_add_u32_e32 v209, s72, v206
	v_lshl_add_u64 v[204:205], v[204:205], 0, s[38:39]
	s_mov_b32 m0, s69
	ds_read_b128 v[192:195], v209
	ds_read_b128 v[196:199], v209 offset:1024
	ds_read_b128 v[200:203], v209 offset:2048
	ds_read_b128 v[210:213], v209 offset:3072
	global_load_lds_dwordx4 v[204:205], off
	v_lshl_add_u64 v[204:205], v[214:215], 0, s[38:39]
	s_add_i32 m0, s69, 0x2000
	s_nop 0
	global_load_lds_dwordx4 v[204:205], off
	s_barrier
	s_waitcnt lgkmcnt(0)
	s_setprio 0
	s_waitcnt lgkmcnt(0)
	v_mfma_f32_16x16x32_bf16 v[136:139], v[192:195], v[132:135], v[136:139]
	v_mfma_f32_16x16x32_bf16 v[128:131], v[200:203], v[132:135], v[128:131]
	v_mfma_f32_16x16x32_bf16 v[116:119], v[192:195], v[148:151], v[116:119]
	v_mfma_f32_16x16x32_bf16 v[112:115], v[200:203], v[148:151], v[112:115]
	v_mfma_f32_16x16x32_bf16 v[100:103], v[192:195], v[160:163], v[100:103]
	v_mfma_f32_16x16x32_bf16 v[96:99], v[200:203], v[160:163], v[96:99]
	v_mfma_f32_16x16x32_bf16 v[84:87], v[192:195], v[184:187], v[84:87]
	v_mfma_f32_16x16x32_bf16 v[80:83], v[200:203], v[184:187], v[80:83]
	v_mfma_f32_16x16x32_bf16 v[136:139], v[196:199], v[140:143], v[136:139]
	v_mfma_f32_16x16x32_bf16 v[132:135], v[210:213], v[140:143], v[128:131]
	v_mfma_f32_16x16x32_bf16 v[116:119], v[196:199], v[156:159], v[116:119]
	v_mfma_f32_16x16x32_bf16 v[112:115], v[210:213], v[156:159], v[112:115]
	v_mfma_f32_16x16x32_bf16 v[100:103], v[196:199], v[164:167], v[100:103]
	v_mfma_f32_16x16x32_bf16 v[96:99], v[210:213], v[164:167], v[96:99]
	v_mfma_f32_16x16x32_bf16 v[84:87], v[196:199], v[188:191], v[84:87]
	v_mfma_f32_16x16x32_bf16 v[80:83], v[210:213], v[188:191], v[80:83]
	s_setprio 1
	s_mov_b32 m0, s79
	v_lshl_add_u64 v[204:205], v[216:217], 0, s[38:39]
	s_barrier
	ds_read_b128 v[128:131], v208 offset:49152
	ds_read_b128 v[140:143], v208 offset:50176
	ds_read_b128 v[148:151], v208 offset:51200
	ds_read_b128 v[156:159], v208 offset:52224
	ds_read_b128 v[160:163], v208 offset:53248
	ds_read_b128 v[164:167], v208 offset:54272
	ds_read_b128 v[184:187], v208 offset:55296
	ds_read_b128 v[188:191], v208 offset:56320
	global_load_lds_dwordx4 v[204:205], off
	v_lshl_add_u64 v[204:205], v[218:219], 0, s[38:39]
	s_mov_b32 m0, s80
	s_nop 0
	global_load_lds_dwordx4 v[204:205], off
	s_barrier
; #define PG8_STAGE(bufoff, gbase, voff) do { _Pragma("unroll") for (int _i = 0; _i < 2; ++_i) \
;         __builtin_amdgcn_global_load_lds((const unsigned*)((const char*)(gbase) + (voff)[_i]), (PG8_LAS unsigned*)(lds + (bufoff) + ldsw + _i * 8192), 16, 0, 0); } while (0)
; #define PG8_MMA(ai, bj, At, Bt) do { __builtin_amdgcn_s_setprio(1); _Pragma("unroll") for (int m = 0; m < 4; ++m) _Pragma("unroll") for (int n = 0; n < 2; ++n) _Pragma("unroll") for (int k = 0; k < 2; ++k) \
;         acc[ai][bj][m][n] = __builtin_amdgcn_mfma_f32_16x16x32_bf16(Bt[n][k], At[m][k], acc[ai][bj][m][n], 0, 0, 0); __builtin_amdgcn_s_setprio(0); } while (0)
; #define PG8_WAIT_V(n) asm volatile("s_waitcnt vmcnt(" #n ")" ::: "memory")
; #define PG8_WAIT_L(n) asm volatile("s_waitcnt lgkmcnt(" #n ")" ::: "memory")
; #define PG8_BAR __builtin_amdgcn_s_barrier()
; #define PG8_SCHED __builtin_amdgcn_sched_barrier(0)
; template <class Epi, class Sched>
; __device__ __forceinline__ void gemm_phase(PG8_LAS unsigned char* lds, const Gemm g, const Sched& S, const Epi& E) {
;     ...
;             PG8_BAR; PG8_WAIT_L(0); PG8_MMA(1, 0, At, B0); PG8_BAR; PG8_SCHED;
;             PG8_STAGE(PG8_SB(1, 1), b3 + hstep, voffB);
;             PG8_WAIT_V(6); PG8_BAR; PG8_MMA(1, 1, At, B1); PG8_BAR;
;         }
;         E(acc, cur, wr, wc, fr, fq); S.done(cur);
;     DI void operator()(const AccT& acc, const pg8::Unit& u, int wr, int wc, int fr, int fq) const {
;         const int col0 = u.pn * 256 + wc * 32 + 8 * fq, head = u.pn >> 1;
;         f32x4 g0[2], g1[2];
; #pragma unroll
;         for (int bj = 0; bj < 2; ++bj) { g0[bj] = *(const f32x4*)(gn + col0 + bj * 128); g1[bj] = *(const f32x4*)(gn + col0 + bj * 128 + 4); }
; #pragma unroll
;         for (int ai = 0; ai < 2; ++ai) {
;             float2 st[4]; u32x4 ov[4][2];
; #pragma unroll
;             for (int m = 0; m < 4; ++m) { const size_t row = (size_t)u.pm * 256 + wr * 64 + fr + ai * 128 + m * 16;
;                 st[m] = *(const float2*)(stats + (row * 4 + head) * 2);
; #pragma unroll
;                 for (int bj = 0; bj < 2; ++bj) ov[m][bj] = *(const u32x4*)(o + row * 2048 + col0 + bj * 128); }
	s_waitcnt lgkmcnt(0)
	s_setprio 0
	s_waitcnt lgkmcnt(0)
	v_mfma_f32_16x16x32_bf16 v[76:79], v[56:59], v[128:131], v[76:79]
	v_mfma_f32_16x16x32_bf16 v[72:75], v[64:67], v[128:131], v[72:75]
	v_mfma_f32_16x16x32_bf16 v[44:47], v[56:59], v[148:151], v[44:47]
	v_mfma_f32_16x16x32_bf16 v[40:43], v[64:67], v[148:151], v[40:43]
	v_mfma_f32_16x16x32_bf16 v[28:31], v[56:59], v[160:163], v[28:31]
	v_mfma_f32_16x16x32_bf16 v[24:27], v[64:67], v[160:163], v[24:27]
	v_mfma_f32_16x16x32_bf16 v[12:15], v[56:59], v[184:187], v[12:15]
	v_mfma_f32_16x16x32_bf16 v[8:11], v[64:67], v[184:187], v[8:11]
	v_mfma_f32_16x16x32_bf16 v[76:79], v[60:63], v[140:143], v[76:79]
	v_mfma_f32_16x16x32_bf16 v[72:75], v[68:71], v[140:143], v[72:75]
	v_mfma_f32_16x16x32_bf16 v[44:47], v[60:63], v[156:159], v[44:47]
	v_mfma_f32_16x16x32_bf16 v[40:43], v[68:71], v[156:159], v[40:43]
	v_mfma_f32_16x16x32_bf16 v[28:31], v[60:63], v[164:167], v[28:31]
	v_mfma_f32_16x16x32_bf16 v[24:27], v[68:71], v[164:167], v[24:27]
	v_mfma_f32_16x16x32_bf16 v[12:15], v[60:63], v[188:191], v[12:15]
	v_mfma_f32_16x16x32_bf16 v[8:11], v[68:71], v[188:191], v[8:11]
	s_setprio 1
	s_barrier
	s_add_u32 s70, s70, 0x40080
	s_addc_u32 s71, s71, 0
	s_add_i32 s69, s72, s74
	v_lshl_add_u64 v[56:57], s[70:71], 0, v[180:181]
	s_mov_b32 m0, s69
	s_nop 0
	global_load_lds_dwordx4 v[56:57], off
	v_lshl_add_u64 v[56:57], s[70:71], 0, v[168:169]
	s_add_i32 m0, s69, 0x2000
	s_nop 0
	global_load_lds_dwordx4 v[56:57], off
	s_waitcnt vmcnt(6)
	s_barrier
	s_setprio 0
	v_mfma_f32_16x16x32_bf16 v[48:51], v[192:195], v[128:131], v[48:51]
	v_mfma_f32_16x16x32_bf16 v[64:67], v[196:199], v[140:143], v[48:51]
	v_mfma_f32_16x16x32_bf16 v[48:51], v[200:203], v[128:131], v[52:55]
	v_mfma_f32_16x16x32_bf16 v[36:39], v[192:195], v[148:151], v[36:39]
	v_mfma_f32_16x16x32_bf16 v[32:35], v[200:203], v[148:151], v[32:35]
	v_mfma_f32_16x16x32_bf16 v[20:23], v[192:195], v[160:163], v[20:23]
	v_mfma_f32_16x16x32_bf16 v[16:19], v[200:203], v[160:163], v[16:19]
	v_mfma_f32_16x16x32_bf16 v[4:7], v[192:195], v[184:187], v[4:7]
	v_mfma_f32_16x16x32_bf16 v[0:3], v[200:203], v[184:187], v[0:3]
	v_mfma_f32_16x16x32_bf16 v[52:55], v[210:213], v[140:143], v[48:51]
	v_mfma_f32_16x16x32_bf16 v[36:39], v[196:199], v[156:159], v[36:39]
	v_mfma_f32_16x16x32_bf16 v[32:35], v[210:213], v[156:159], v[32:35]
	v_mfma_f32_16x16x32_bf16 v[20:23], v[196:199], v[164:167], v[20:23]
	v_mfma_f32_16x16x32_bf16 v[16:19], v[210:213], v[164:167], v[16:19]
	v_mfma_f32_16x16x32_bf16 v[4:7], v[196:199], v[188:191], v[4:7]
	v_mfma_f32_16x16x32_bf16 v[0:3], v[210:213], v[188:191], v[0:3]
	s_setprio 1
	s_add_i32 s89, s89, 2
	s_add_u32 s20, s20, 0x100
	s_addc_u32 s21, s21, 0
	s_add_u32 s83, s83, 0x100
	s_addc_u32 s88, s88, 0
	s_cmp_gt_u32 s89, 13
	s_barrier
	s_cbranch_scc0 .LBB0_516
	v_lshl_or_b32 v48, s18, 8, v207
	s_ashr_i32 s20, s18, 1
	s_ashr_i32 s17, s16, 31
	v_ashrrev_i32_e32 v49, 31, v48
	s_lshl_b64 s[16:17], s[16:17], 8
	s_ashr_i32 s21, s20, 31
	v_lshl_add_u64 v[188:189], s[16:17], 0, v[174:175]
	s_lshl_b64 s[16:17], s[20:21], 3
	v_lshlrev_b64 v[184:185], 1, v[48:49]
	s_add_u32 s16, s60, s16
	v_lshl_add_u64 v[186:187], s[96:97], 0, v[184:185]
	v_lshlrev_b64 v[128:129], 12, v[188:189]
	v_lshl_add_u64 v[56:57], v[48:49], 2, s[6:7]
	s_addc_u32 s17, s61, s17
	v_lshlrev_b64 v[48:49], 5, v[188:189]
	v_lshl_add_u64 v[130:131], v[186:187], 0, v[128:129]
	global_load_dwordx4 v[60:63], v[56:57], off
	v_lshl_add_u64 v[48:49], s[16:17], 0, v[48:49]
	global_load_dwordx4 v[210:213], v[130:131], off
	global_load_dwordx2 v[204:205], v[48:49], off
	v_mul_f32_e32 v48, 0xbfb8aa3b, v152
	v_mul_f32_e32 v49, 0xbfb8aa3b, v153
	v_mul_f32_e32 v50, 0xbfb8aa3b, v154
	v_mul_f32_e32 v51, 0xbfb8aa3b, v155
	v_mul_f32_e32 v58, 0xbfb8aa3b, v144
	v_mul_f32_e32 v59, 0xbfb8aa3b, v145
	v_mul_f32_e32 v68, 0xbfb8aa3b, v146
	v_mul_f32_e32 v69, 0xbfb8aa3b, v147
	v_mov_b32_e32 v214, v152
	v_exp_f32_e32 v152, v48
	v_exp_f32_e32 v156, v49
	v_exp_f32_e32 v157, v50
	v_exp_f32_e32 v158, v51
	v_exp_f32_e32 v159, v58
	v_exp_f32_e32 v160, v59
	v_exp_f32_e32 v161, v68
	v_exp_f32_e32 v162, v69
	global_load_dwordx4 v[68:71], v[56:57], off offset:16
	global_load_dwordx4 v[48:51], v[56:57], off offset:528
	s_nop 0
	global_load_dwordx4 v[56:59], v[56:57], off offset:512
	v_add_f32_e32 v209, 1.0, v156
	global_load_dwordx4 v[164:167], v[130:131], off offset:256
	v_rcp_f32_e32 v220, v209
	v_or_b32_e32 v140, 16, v188
	v_mov_b32_e32 v141, v189
	v_or_b32_e32 v148, 48, v188
	v_mov_b32_e32 v149, v189
	v_or_b32_e32 v142, 32, v188
	v_mov_b32_e32 v143, v189
	v_lshlrev_b64 v[202:203], 12, v[140:141]
	v_lshlrev_b64 v[190:191], 12, v[148:149]
	v_lshlrev_b64 v[150:151], 5, v[140:141]
	v_lshlrev_b64 v[140:141], 5, v[142:143]
	v_lshlrev_b64 v[196:197], 12, v[142:143]
	v_lshlrev_b64 v[142:143], 5, v[148:149]
	v_lshl_add_u64 v[128:129], s[96:97], 0, v[128:129]
	v_lshl_add_u64 v[130:131], v[186:187], 0, v[202:203]
	v_lshl_add_u64 v[218:219], v[186:187], 0, v[190:191]
	v_add_f32_e32 v152, 1.0, v152
	v_lshl_add_u64 v[216:217], s[16:17], 0, v[150:151]
	v_lshl_add_u64 v[198:199], s[16:17], 0, v[140:141]
	v_lshl_add_u64 v[200:201], v[186:187], 0, v[196:197]
	v_lshl_add_u64 v[194:195], s[16:17], 0, v[142:143]
	v_lshl_add_u64 v[192:193], v[128:129], 0, v[184:185]
	v_add_f32_e32 v215, 1.0, v157
	v_add_f32_e32 v221, 1.0, v158
	v_add_f32_e32 v223, 1.0, v159
	v_add_f32_e32 v225, 1.0, v160
	v_add_f32_e32 v227, 1.0, v161
	v_add_f32_e32 v229, 1.0, v162
	global_load_dwordx4 v[160:163], v[130:131], off
	global_load_dwordx4 v[156:159], v[130:131], off offset:256
	global_load_dwordx4 v[148:151], v[200:201], off offset:256
	global_load_dwordx4 v[140:143], v[218:219], off
	s_nop 0
	global_load_dwordx4 v[128:131], v[218:219], off offset:256
	v_rcp_f32_e32 v218, v152
	v_rcp_f32_e32 v224, v221
	v_rcp_f32_e32 v226, v223
	v_rcp_f32_e32 v228, v225
	v_rcp_f32_e32 v232, v227
	v_rcp_f32_e32 v234, v229
	v_rcp_f32_e32 v222, v215
	s_mov_b64 s[20:21], 0x90
	s_mov_b32 s18, s8
	s_mov_b64 s[70:71], s[14:15]
	s_waitcnt vmcnt(0)
; DI float bflo(unsigned w) { return __uint_as_float(w << 16); }
; DI float bfhi(unsigned w) { return __uint_as_float(w & 0xffff0000u); }
; DI void store8(bf16_t* p, f32x4 a, f32x4 b) { u32x4 w = {cvt_pk_bf16(a[0], a[1]), cvt_pk_bf16(a[2], a[3]), cvt_pk_bf16(b[0], b[1]), cvt_pk_bf16(b[2], b[3])}; *(u32x4*)p = w; }
; DI f32x4 silu4(f32x4 v) { f32x4 r; r[0] = silu_f(v[0]); r[1] = silu_f(v[1]); r[2] = silu_f(v[2]); r[3] = silu_f(v[3]); return r; }
;     DI void operator()(const AccT& acc, const pg8::Unit& u, int wr, int wc, int fr, int fq) const {
;     ...
; #pragma unroll
;             for (int m = 0; m < 4; ++m) { const size_t row = (size_t)u.pm * 256 + wr * 64 + fr + ai * 128 + m * 16;
;                 const float mean = st[m].x * (1.f / 512.f), var = fmaxf(st[m].y * (1.f / 512.f) - mean * mean, 0.f), rstd = rsqrtf(var + 1e-5f);
; #pragma unroll
;                 for (int bj = 0; bj < 2; ++bj) { bf16_t* op = o + row * 2048 + col0 + bj * 128; const u32x4 w = ov[m][bj];
;                     const f32x4 s0 = silu4(acc[ai][bj][m][0]), s1 = silu4(acc[ai][bj][m][1]);
;                     f32x4 y0, y1;
;                     y0[0] = (bflo(w[0]) - mean) * rstd * g0[bj][0] * s0[0]; y0[1] = (bfhi(w[0]) - mean) * rstd * g0[bj][1] * s0[1];
;                     y0[2] = (bflo(w[1]) - mean) * rstd * g0[bj][2] * s0[2]; y0[3] = (bfhi(w[1]) - mean) * rstd * g0[bj][3] * s0[3];
;                     y1[0] = (bflo(w[2]) - mean) * rstd * g1[bj][0] * s1[0]; y1[1] = (bfhi(w[2]) - mean) * rstd * g1[bj][1] * s1[1];
;                     y1[2] = (bflo(w[3]) - mean) * rstd * g1[bj][2] * s1[2]; y1[3] = (bfhi(w[3]) - mean) * rstd * g1[bj][3] * s1[3];
;                     store8(op, y0, y1); } } }
	v_mov_b32_e32 v215, v60
	v_lshlrev_b32_e32 v152, 16, v210
	v_pk_mul_f32 v[204:205], v[204:205], s[54:55] op_sel_hi:[1,0]
	s_nop 0
	v_fma_f32 v205, -v204, v204, v205
	v_max_f32_e32 v205, 0, v205
	v_add_f32_e32 v205, 0x3727c5ac, v205
	v_mul_f32_e32 v209, 0x4b800000, v205
	v_cmp_gt_f32_e32 vcc, s94, v205
	v_sub_f32_e32 v152, v152, v204
	s_nop 0
	v_cndmask_b32_e32 v205, v205, v209, vcc
	v_rsq_f32_e32 v205, v205
	v_and_b32_e32 v209, 0xffff0000, v210
	v_sub_f32_e32 v209, v209, v204
	v_mul_f32_e32 v210, 0x45800000, v205
	v_cndmask_b32_e32 v205, v205, v210, vcc
	v_mul_f32_e32 v221, v209, v205
	v_lshlrev_b32_e32 v209, 16, v211
	v_sub_f32_e32 v209, v209, v204
	v_mul_f32_e32 v223, v209, v205
	v_and_b32_e32 v209, 0xffff0000, v211
	v_sub_f32_e32 v209, v209, v204
	v_mul_f32_e32 v225, v209, v205
	v_lshlrev_b32_e32 v209, 16, v212
	v_sub_f32_e32 v209, v209, v204
	v_mul_f32_e32 v227, v209, v205
	v_and_b32_e32 v209, 0xffff0000, v212
	v_sub_f32_e32 v209, v209, v204
	v_mul_f32_e32 v229, v209, v205
	v_lshlrev_b32_e32 v209, 16, v213
	v_sub_f32_e32 v209, v209, v204
	v_mul_f32_e32 v233, v209, v205
	v_and_b32_e32 v209, 0xffff0000, v213
	global_load_dwordx2 v[212:213], v[216:217], off
	v_mov_b32_e32 v210, v155
	v_mov_b32_e32 v211, v63
	v_pk_mul_f32 v[210:211], v[210:211], v[224:225]
	v_sub_f32_e32 v209, v209, v204
	v_mul_f32_e32 v155, v210, v211
	v_mov_b32_e32 v210, v144
	v_mov_b32_e32 v211, v68
	v_pk_mul_f32 v[210:211], v[210:211], v[226:227]
	v_mul_f32_e32 v235, v209, v205
	v_mul_f32_e32 v144, v210, v211
	v_mov_b32_e32 v210, v145
	v_mov_b32_e32 v211, v69
	v_pk_mul_f32 v[210:211], v[210:211], v[228:229]
	v_mul_f32_e32 v219, v152, v205
	v_mul_f32_e32 v145, v210, v211
	v_mov_b32_e32 v210, v146
	v_mov_b32_e32 v211, v70
	v_pk_mul_f32 v[210:211], v[210:211], v[232:233]
	v_pk_mul_f32 v[214:215], v[214:215], v[218:219]
	v_mul_f32_e32 v146, v210, v211
	v_mov_b32_e32 v210, v147
	v_mov_b32_e32 v211, v71
	v_pk_mul_f32 v[210:211], v[210:211], v[234:235]
	v_mul_f32_e32 v147, 0xbfb8aa3b, v136
	v_exp_f32_e32 v209, v147
	v_mul_f32_e32 v147, v210, v211
	v_mul_f32_e32 v210, 0xbfb8aa3b, v137
	v_exp_f32_e32 v211, v210
	v_mul_f32_e32 v152, v214, v215
	v_mov_b32_e32 v214, v153
	v_mov_b32_e32 v215, v61
	v_pk_mul_f32 v[214:215], v[214:215], v[220:221]
	v_add_f32_e32 v209, 1.0, v209
	v_mul_f32_e32 v153, v214, v215
	v_mov_b32_e32 v214, v154
	v_mov_b32_e32 v215, v62
	v_pk_mul_f32 v[214:215], v[214:215], v[222:223]
	v_rcp_f32_e32 v210, v209
	v_add_f32_e32 v209, 1.0, v211
	v_mul_f32_e32 v211, 0xbfb8aa3b, v138
	v_mul_f32_e32 v154, v214, v215
	v_exp_f32_e32 v211, v211
	v_mul_f32_e32 v214, 0xbfb8aa3b, v139
	v_exp_f32_e32 v215, v214
	v_rcp_f32_e32 v214, v209
	v_add_f32_e32 v209, 1.0, v211
	v_mul_f32_e32 v211, 0xbfb8aa3b, v132
	v_rcp_f32_e32 v216, v209
	v_add_f32_e32 v209, 1.0, v215
	v_exp_f32_e32 v211, v211
	v_mul_f32_e32 v215, 0xbfb8aa3b, v133
	v_exp_f32_e32 v215, v215
	v_rcp_f32_e32 v218, v209
	v_add_f32_e32 v209, 1.0, v211
	v_mul_f32_e32 v211, 0xbfb8aa3b, v134
	v_rcp_f32_e32 v220, v209
	v_add_f32_e32 v209, 1.0, v215
	v_exp_f32_e32 v211, v211
	v_mul_f32_e32 v215, 0xbfb8aa3b, v135
	v_exp_f32_e32 v215, v215
	v_rcp_f32_e32 v222, v209
	v_add_f32_e32 v209, 1.0, v211
	v_rcp_f32_e32 v224, v209
	v_add_f32_e32 v209, 1.0, v215
	v_rcp_f32_e32 v226, v209
	v_lshlrev_b32_e32 v209, 16, v164
	v_and_b32_e32 v164, 0xffff0000, v164
	v_sub_f32_e32 v164, v164, v204
	v_mul_f32_e32 v215, v164, v205
	v_lshlrev_b32_e32 v164, 16, v165
	v_sub_f32_e32 v164, v164, v204
	v_mul_f32_e32 v217, v164, v205
	v_and_b32_e32 v164, 0xffff0000, v165
	v_sub_f32_e32 v164, v164, v204
	v_mul_f32_e32 v219, v164, v205
	v_mov_b32_e32 v164, v139
	v_mov_b32_e32 v165, v59
	v_pk_mul_f32 v[164:165], v[164:165], v[218:219]
	v_sub_f32_e32 v209, v209, v204
	v_mul_f32_e32 v139, v164, v165
	v_lshlrev_b32_e32 v164, 16, v166
	v_sub_f32_e32 v164, v164, v204
	v_mul_f32_e32 v221, v164, v205
	v_mov_b32_e32 v164, v132
	v_and_b32_e32 v132, 0xffff0000, v166
	v_sub_f32_e32 v132, v132, v204
	v_mov_b32_e32 v165, v48
	v_mul_f32_e32 v223, v132, v205
	v_mov_b32_e32 v132, v133
	v_mov_b32_e32 v133, v49
	v_pk_mul_f32 v[164:165], v[164:165], v[220:221]
	v_pk_mul_f32 v[132:133], v[132:133], v[222:223]
	v_mul_f32_e32 v164, v164, v165
	v_mul_f32_e32 v165, v132, v133
	v_lshlrev_b32_e32 v132, 16, v167
	v_sub_f32_e32 v132, v132, v204
	v_mul_f32_e32 v225, v132, v205
	v_mov_b32_e32 v132, v134
	v_mov_b32_e32 v133, v50
	v_pk_mul_f32 v[132:133], v[132:133], v[224:225]
	v_mul_f32_e32 v211, v209, v205
	v_mul_f32_e32 v166, v132, v133
	v_and_b32_e32 v132, 0xffff0000, v167
	v_sub_f32_e32 v132, v132, v204
	v_mul_f32_e32 v227, v132, v205
	v_mov_b32_e32 v132, v135
	s_waitcnt vmcnt(0)
; DI float bflo(unsigned w) { return __uint_as_float(w << 16); }
; DI float bfhi(unsigned w) { return __uint_as_float(w & 0xffff0000u); }
; DI void store8(bf16_t* p, f32x4 a, f32x4 b) { u32x4 w = {cvt_pk_bf16(a[0], a[1]), cvt_pk_bf16(a[2], a[3]), cvt_pk_bf16(b[0], b[1]), cvt_pk_bf16(b[2], b[3])}; *(u32x4*)p = w; }
; DI f32x4 silu4(f32x4 v) { f32x4 r; r[0] = silu_f(v[0]); r[1] = silu_f(v[1]); r[2] = silu_f(v[2]); r[3] = silu_f(v[3]); return r; }
;     DI void operator()(const AccT& acc, const pg8::Unit& u, int wr, int wc, int fr, int fq) const {
;     ...
;             for (int m = 0; m < 4; ++m) { const size_t row = (size_t)u.pm * 256 + wr * 64 + fr + ai * 128 + m * 16;
;                 st[m] = *(const float2*)(stats + (row * 4 + head) * 2);
; #pragma unroll
;                 for (int bj = 0; bj < 2; ++bj) ov[m][bj] = *(const u32x4*)(o + row * 2048 + col0 + bj * 128); }
; #pragma unroll
;             for (int m = 0; m < 4; ++m) { const size_t row = (size_t)u.pm * 256 + wr * 64 + fr + ai * 128 + m * 16;
;                 const float mean = st[m].x * (1.f / 512.f), var = fmaxf(st[m].y * (1.f / 512.f) - mean * mean, 0.f), rstd = rsqrtf(var + 1e-5f);
; #pragma unroll
;                 for (int bj = 0; bj < 2; ++bj) { bf16_t* op = o + row * 2048 + col0 + bj * 128; const u32x4 w = ov[m][bj];
;                     const f32x4 s0 = silu4(acc[ai][bj][m][0]), s1 = silu4(acc[ai][bj][m][1]);
;                     f32x4 y0, y1;
;                     y0[0] = (bflo(w[0]) - mean) * rstd * g0[bj][0] * s0[0]; y0[1] = (bfhi(w[0]) - mean) * rstd * g0[bj][1] * s0[1];
;                     y0[2] = (bflo(w[1]) - mean) * rstd * g0[bj][2] * s0[2]; y0[3] = (bfhi(w[1]) - mean) * rstd * g0[bj][3] * s0[3];
;                     y1[0] = (bflo(w[2]) - mean) * rstd * g1[bj][0] * s1[0]; y1[1] = (bfhi(w[2]) - mean) * rstd * g1[bj][1] * s1[1];
;                     y1[2] = (bflo(w[3]) - mean) * rstd * g1[bj][2] * s1[2]; y1[3] = (bfhi(w[3]) - mean) * rstd * g1[bj][3] * s1[3];
;                     store8(op, y0, y1); } } }
	v_pk_mul_f32 v[134:135], v[212:213], s[54:55] op_sel_hi:[1,0]
	v_mov_b32_e32 v228, v136
	v_fma_f32 v133, -v134, v134, v135
	v_max_f32_e32 v133, 0, v133
	v_add_f32_e32 v133, 0x3727c5ac, v133
	v_mul_f32_e32 v135, 0x4b800000, v133
	v_cmp_gt_f32_e32 vcc, s94, v133
	v_mov_b32_e32 v229, v56
	v_mul_f32_e32 v204, 0xbfb8aa3b, v126
	v_cndmask_b32_e32 v133, v133, v135, vcc
	v_rsq_f32_e32 v167, v133
	v_mov_b32_e32 v133, v51
	v_pk_mul_f32 v[132:133], v[132:133], v[226:227]
	v_pk_mul_f32 v[210:211], v[228:229], v[210:211]
	v_mul_f32_e32 v135, v132, v133
	v_mul_f32_e32 v132, 0x45800000, v167
	v_cndmask_b32_e32 v167, v167, v132, vcc
	v_lshl_add_u64 v[132:133], s[96:97], 0, v[202:203]
	v_mul_f32_e32 v203, 0xbfb8aa3b, v125
	v_exp_f32_e32 v203, v203
	v_exp_f32_e32 v205, v204
	v_mul_f32_e32 v204, 0xbfb8aa3b, v127
	v_mul_f32_e32 v136, v210, v211
	v_mov_b32_e32 v210, v137
	v_mov_b32_e32 v211, v57
	v_exp_f32_e32 v209, v204
	v_pk_mul_f32 v[210:211], v[210:211], v[214:215]
	v_add_f32_e32 v203, 1.0, v203
	v_mul_f32_e32 v137, v210, v211
	v_mov_b32_e32 v210, v138
	v_mov_b32_e32 v211, v58
	v_pk_mul_f32 v[210:211], v[210:211], v[216:217]
	v_rcp_f32_e32 v204, v203
	v_add_f32_e32 v203, 1.0, v205
	v_mul_f32_e32 v205, 0xbfb8aa3b, v120
	v_mul_f32_e32 v138, v210, v211
	v_rcp_f32_e32 v210, v203
	v_add_f32_e32 v203, 1.0, v209
	v_exp_f32_e32 v205, v205
	v_mul_f32_e32 v209, 0xbfb8aa3b, v121
	v_exp_f32_e32 v209, v209
	v_rcp_f32_e32 v212, v203
	v_add_f32_e32 v203, 1.0, v205
	v_mul_f32_e32 v205, 0xbfb8aa3b, v122
	v_rcp_f32_e32 v214, v203
	v_add_f32_e32 v203, 1.0, v209
	v_exp_f32_e32 v205, v205
	v_mul_f32_e32 v209, 0xbfb8aa3b, v123
	v_exp_f32_e32 v209, v209
	v_rcp_f32_e32 v216, v203
	v_add_f32_e32 v203, 1.0, v205
	v_rcp_f32_e32 v218, v203
	v_add_f32_e32 v203, 1.0, v209
	v_rcp_f32_e32 v220, v203
	v_lshlrev_b32_e32 v203, 16, v160
	v_and_b32_e32 v160, 0xffff0000, v160
	v_sub_f32_e32 v160, v160, v134
	v_mul_f32_e32 v205, v160, v167
	v_lshlrev_b32_e32 v160, 16, v161
	v_sub_f32_e32 v160, v160, v134
	v_mul_f32_e32 v211, v160, v167
	v_and_b32_e32 v160, 0xffff0000, v161
	v_sub_f32_e32 v160, v160, v134
	v_mul_f32_e32 v213, v160, v167
	v_mov_b32_e32 v160, v127
	v_mov_b32_e32 v161, v63
	v_pk_mul_f32 v[160:161], v[160:161], v[212:213]
	v_mul_f32_e32 v202, 0xbfb8aa3b, v124
	v_mul_f32_e32 v127, v160, v161
	v_lshlrev_b32_e32 v160, 16, v162
	v_sub_f32_e32 v160, v160, v134
	v_exp_f32_e32 v202, v202
	v_mul_f32_e32 v215, v160, v167
	v_mov_b32_e32 v160, v120
	v_and_b32_e32 v120, 0xffff0000, v162
	v_sub_f32_e32 v120, v120, v134
	v_mov_b32_e32 v161, v68
	v_mul_f32_e32 v217, v120, v167
	v_mov_b32_e32 v120, v121
	v_mov_b32_e32 v121, v69
	v_pk_mul_f32 v[160:161], v[160:161], v[214:215]
	v_pk_mul_f32 v[120:121], v[120:121], v[216:217]
	v_add_f32_e32 v202, 1.0, v202
	v_mul_f32_e32 v160, v160, v161
	v_mul_f32_e32 v161, v120, v121
	v_lshlrev_b32_e32 v120, 16, v163
	v_rcp_f32_e32 v202, v202
	v_sub_f32_e32 v120, v120, v134
	v_mul_f32_e32 v219, v120, v167
	v_mov_b32_e32 v120, v122
	v_mov_b32_e32 v121, v70
	v_sub_f32_e32 v203, v203, v134
	v_pk_mul_f32 v[120:121], v[120:121], v[218:219]
	v_mul_f32_e32 v203, v203, v167
	v_mov_b32_e32 v222, v124
	v_mov_b32_e32 v223, v60
	v_mul_f32_e32 v162, v120, v121
	v_mul_f32_e32 v121, 0xbfb8aa3b, v116
	v_pk_mul_f32 v[202:203], v[222:223], v[202:203]
	v_and_b32_e32 v120, 0xffff0000, v163
	v_exp_f32_e32 v122, v121
	v_mul_f32_e32 v124, v202, v203
	v_mov_b32_e32 v202, v125
	v_mov_b32_e32 v203, v61
	v_sub_f32_e32 v120, v120, v134
	v_pk_mul_f32 v[202:203], v[202:203], v[204:205]
	v_mul_f32_e32 v221, v120, v167
	v_mov_b32_e32 v120, v123
	v_mov_b32_e32 v121, v71
	v_mul_f32_e32 v125, v202, v203
	v_mov_b32_e32 v202, v126
	v_mov_b32_e32 v203, v62
	v_pk_mul_f32 v[120:121], v[120:121], v[220:221]
	v_pk_mul_f32 v[202:203], v[202:203], v[210:211]
	v_mul_f32_e32 v163, v120, v121
	v_add_f32_e32 v120, 1.0, v122
	v_mul_f32_e32 v121, 0xbfb8aa3b, v117
	v_mul_f32_e32 v126, v202, v203
	v_exp_f32_e32 v203, v121
	v_rcp_f32_e32 v202, v120
	global_load_dwordx4 v[120:123], v[200:201], off
	s_nop 0
	global_load_dwordx2 v[198:199], v[198:199], off
	v_mul_f32_e32 v201, 0xbfb8aa3b, v118
	v_add_f32_e32 v200, 1.0, v203
	v_exp_f32_e32 v201, v201
	v_mul_f32_e32 v203, 0xbfb8aa3b, v119
	v_exp_f32_e32 v203, v203
	v_mul_f32_e32 v205, 0xbfb8aa3b, v113
	v_add_f32_e32 v201, 1.0, v201
	v_rcp_f32_e32 v204, v201
	v_add_f32_e32 v201, 1.0, v203
	v_mul_f32_e32 v203, 0xbfb8aa3b, v112
	v_exp_f32_e32 v203, v203
	v_exp_f32_e32 v205, v205
	v_rcp_f32_e32 v210, v201
	v_rcp_f32_e32 v200, v200
	v_add_f32_e32 v201, 1.0, v203
	v_mul_f32_e32 v203, 0xbfb8aa3b, v114
	v_rcp_f32_e32 v212, v201
	v_add_f32_e32 v201, 1.0, v205
	v_exp_f32_e32 v203, v203
	v_mul_f32_e32 v205, 0xbfb8aa3b, v115
	v_exp_f32_e32 v205, v205
	v_rcp_f32_e32 v214, v201
	v_add_f32_e32 v201, 1.0, v203
	v_rcp_f32_e32 v216, v201
	v_add_f32_e32 v201, 1.0, v205
	v_rcp_f32_e32 v218, v201
	v_lshlrev_b32_e32 v201, 16, v156
	v_mov_b32_e32 v220, v116
	v_and_b32_e32 v116, 0xffff0000, v156
	v_sub_f32_e32 v201, v201, v134
	v_sub_f32_e32 v116, v116, v134
	v_mul_f32_e32 v203, v201, v167
	v_mul_f32_e32 v201, v116, v167
	v_mov_b32_e32 v116, v117
	v_mov_b32_e32 v117, v57
	v_mov_b32_e32 v221, v56
	v_pk_mul_f32 v[116:117], v[116:117], v[200:201]
	v_pk_mul_f32 v[202:203], v[220:221], v[202:203]
	v_mul_f32_e32 v220, v116, v117
	v_lshlrev_b32_e32 v116, 16, v157
	v_sub_f32_e32 v116, v116, v134
	v_mul_f32_e32 v205, v116, v167
	v_mov_b32_e32 v116, v118
	v_mov_b32_e32 v117, v58
	v_pk_mul_f32 v[116:117], v[116:117], v[204:205]
	v_mul_f32_e32 v118, 0xbfb8aa3b, v110
	v_mul_f32_e32 v221, v116, v117
	v_and_b32_e32 v116, 0xffff0000, v157
	v_sub_f32_e32 v116, v116, v134
	v_mul_f32_e32 v211, v116, v167
	v_mov_b32_e32 v116, v119
	v_mov_b32_e32 v117, v59
	v_pk_mul_f32 v[116:117], v[116:117], v[210:211]
	v_exp_f32_e32 v119, v118
	v_mul_f32_e32 v210, v116, v117
	v_lshlrev_b32_e32 v116, 16, v158
	v_sub_f32_e32 v116, v116, v134
	v_mul_f32_e32 v213, v116, v167
	v_mov_b32_e32 v116, v112
	v_and_b32_e32 v112, 0xffff0000, v158
	v_sub_f32_e32 v112, v112, v134
	v_mul_f32_e32 v215, v112, v167
	v_mov_b32_e32 v112, v113
	v_mov_b32_e32 v113, v49
	v_mov_b32_e32 v117, v48
	v_pk_mul_f32 v[112:113], v[112:113], v[214:215]
	v_pk_mul_f32 v[116:117], v[116:117], v[212:213]
	v_mul_f32_e32 v212, v112, v113
	v_lshlrev_b32_e32 v112, 16, v159
	v_sub_f32_e32 v112, v112, v134
	v_mul_f32_e32 v217, v112, v167
	v_mov_b32_e32 v112, v114
	v_mov_b32_e32 v113, v50
	v_pk_mul_f32 v[112:113], v[112:113], v[216:217]
	v_mul_f32_e32 v211, v116, v117
	v_mul_f32_e32 v213, v112, v113
	v_and_b32_e32 v112, 0xffff0000, v159
	v_sub_f32_e32 v112, v112, v134
	v_mul_f32_e32 v117, 0xbfb8aa3b, v109
	v_mul_f32_e32 v219, v112, v167
	v_mov_b32_e32 v112, v115
	s_waitcnt vmcnt(0)
; DI float bflo(unsigned w) { return __uint_as_float(w << 16); }
; DI float bfhi(unsigned w) { return __uint_as_float(w & 0xffff0000u); }
; DI void store8(bf16_t* p, f32x4 a, f32x4 b) { u32x4 w = {cvt_pk_bf16(a[0], a[1]), cvt_pk_bf16(a[2], a[3]), cvt_pk_bf16(b[0], b[1]), cvt_pk_bf16(b[2], b[3])}; *(u32x4*)p = w; }
; DI f32x4 silu4(f32x4 v) { f32x4 r; r[0] = silu_f(v[0]); r[1] = silu_f(v[1]); r[2] = silu_f(v[2]); r[3] = silu_f(v[3]); return r; }
;     DI void operator()(const AccT& acc, const pg8::Unit& u, int wr, int wc, int fr, int fq) const {
;     ...
; #pragma unroll
;             for (int m = 0; m < 4; ++m) { const size_t row = (size_t)u.pm * 256 + wr * 64 + fr + ai * 128 + m * 16;
;                 const float mean = st[m].x * (1.f / 512.f), var = fmaxf(st[m].y * (1.f / 512.f) - mean * mean, 0.f), rstd = rsqrtf(var + 1e-5f);
; #pragma unroll
;                 for (int bj = 0; bj < 2; ++bj) { bf16_t* op = o + row * 2048 + col0 + bj * 128; const u32x4 w = ov[m][bj];
;                     const f32x4 s0 = silu4(acc[ai][bj][m][0]), s1 = silu4(acc[ai][bj][m][1]);
;                     f32x4 y0, y1;
;                     y0[0] = (bflo(w[0]) - mean) * rstd * g0[bj][0] * s0[0]; y0[1] = (bfhi(w[0]) - mean) * rstd * g0[bj][1] * s0[1];
;                     y0[2] = (bflo(w[1]) - mean) * rstd * g0[bj][2] * s0[2]; y0[3] = (bfhi(w[1]) - mean) * rstd * g0[bj][3] * s0[3];
;                     y1[0] = (bflo(w[2]) - mean) * rstd * g1[bj][0] * s1[0]; y1[1] = (bfhi(w[2]) - mean) * rstd * g1[bj][1] * s1[1];
;                     y1[2] = (bflo(w[3]) - mean) * rstd * g1[bj][2] * s1[2]; y1[3] = (bfhi(w[3]) - mean) * rstd * g1[bj][3] * s1[3];
;                     store8(op, y0, y1); } } }
	v_pk_mul_f32 v[114:115], v[198:199], s[54:55] op_sel_hi:[1,0]
	v_exp_f32_e32 v117, v117
	v_fma_f32 v113, -v114, v114, v115
	v_mul_f32_e32 v118, 0xbfb8aa3b, v111
	v_max_f32_e32 v113, 0, v113
	v_exp_f32_e32 v157, v118
	v_add_f32_e32 v113, 0x3727c5ac, v113
	v_mul_f32_e32 v115, 0x4b800000, v113
	v_cmp_gt_f32_e32 vcc, s94, v113
	v_add_f32_e32 v117, 1.0, v117
	v_rcp_f32_e32 v118, v117
	v_cndmask_b32_e32 v113, v113, v115, vcc
	v_add_f32_e32 v117, 1.0, v119
	v_mul_f32_e32 v119, 0xbfb8aa3b, v104
	v_rsq_f32_e32 v115, v113
	v_rcp_f32_e32 v156, v117
	v_add_f32_e32 v117, 1.0, v157
	v_exp_f32_e32 v119, v119
	v_mul_f32_e32 v157, 0xbfb8aa3b, v105
	v_exp_f32_e32 v157, v157
	v_mov_b32_e32 v113, v51
	v_pk_mul_f32 v[112:113], v[112:113], v[218:219]
	v_mul_f32_e32 v116, 0xbfb8aa3b, v108
	v_mul_f32_e32 v134, v112, v113
	v_mul_f32_e32 v112, 0x45800000, v115
	v_rcp_f32_e32 v158, v117
	v_add_f32_e32 v117, 1.0, v119
	v_mul_f32_e32 v119, 0xbfb8aa3b, v106
	v_cndmask_b32_e32 v115, v115, v112, vcc
	v_lshl_add_u64 v[112:113], s[96:97], 0, v[196:197]
	v_exp_f32_e32 v116, v116
	v_rcp_f32_e32 v196, v117
	v_add_f32_e32 v117, 1.0, v157
	v_exp_f32_e32 v119, v119
	v_mul_f32_e32 v157, 0xbfb8aa3b, v107
	v_exp_f32_e32 v157, v157
	v_add_f32_e32 v116, 1.0, v116
	v_rcp_f32_e32 v198, v117
	v_add_f32_e32 v117, 1.0, v119
	v_rcp_f32_e32 v116, v116
	v_rcp_f32_e32 v200, v117
	v_add_f32_e32 v117, 1.0, v157
	v_mov_b32_e32 v204, v108
	v_and_b32_e32 v108, 0xffff0000, v120
	v_mul_f32_e32 v209, v202, v203
	v_rcp_f32_e32 v202, v117
	v_lshlrev_b32_e32 v117, 16, v120
	v_sub_f32_e32 v108, v108, v114
	v_sub_f32_e32 v117, v117, v114
	v_mul_f32_e32 v119, v108, v115
	v_mov_b32_e32 v108, v109
	v_mov_b32_e32 v109, v61
	v_mul_f32_e32 v117, v117, v115
	v_mov_b32_e32 v205, v60
	v_pk_mul_f32 v[108:109], v[108:109], v[118:119]
	v_pk_mul_f32 v[116:117], v[204:205], v[116:117]
	v_mul_f32_e32 v204, v108, v109
	v_lshlrev_b32_e32 v108, 16, v121
	v_sub_f32_e32 v108, v108, v114
	v_mul_f32_e32 v157, v108, v115
	v_mov_b32_e32 v108, v110
	v_mov_b32_e32 v109, v62
	v_pk_mul_f32 v[108:109], v[108:109], v[156:157]
	global_load_dwordx2 v[156:157], v[194:195], off
	v_mul_f32_e32 v205, v108, v109
	v_and_b32_e32 v108, 0xffff0000, v121
	v_sub_f32_e32 v108, v108, v114
	v_mul_f32_e32 v159, v108, v115
	v_mov_b32_e32 v108, v111
	v_mov_b32_e32 v109, v63
	v_pk_mul_f32 v[108:109], v[108:109], v[158:159]
	v_mul_f32_e32 v167, v116, v117
	v_mul_f32_e32 v214, v108, v109
	v_lshlrev_b32_e32 v108, 16, v122
	v_sub_f32_e32 v108, v108, v114
	v_mul_f32_e32 v197, v108, v115
	v_mov_b32_e32 v108, v104
	v_and_b32_e32 v104, 0xffff0000, v122
	v_sub_f32_e32 v104, v104, v114
	v_mul_f32_e32 v199, v104, v115
	v_mov_b32_e32 v104, v105
	v_mov_b32_e32 v105, v69
	v_mov_b32_e32 v109, v68
	v_pk_mul_f32 v[104:105], v[104:105], v[198:199]
	v_pk_mul_f32 v[108:109], v[108:109], v[196:197]
	v_mul_f32_e32 v197, v104, v105
	v_lshlrev_b32_e32 v104, 16, v123
	v_sub_f32_e32 v104, v104, v114
	v_mul_f32_e32 v201, v104, v115
	v_mov_b32_e32 v104, v106
	v_mov_b32_e32 v105, v70
	v_pk_mul_f32 v[104:105], v[104:105], v[200:201]
	v_mul_f32_e32 v106, 0xbfb8aa3b, v100
	v_mul_f32_e32 v198, v104, v105
	v_and_b32_e32 v104, 0xffff0000, v123
	v_sub_f32_e32 v104, v104, v114
	v_mul_f32_e32 v203, v104, v115
	v_mov_b32_e32 v104, v107
	v_exp_f32_e32 v106, v106
	v_mul_f32_e32 v107, 0xbfb8aa3b, v101
	v_exp_f32_e32 v107, v107
	v_mov_b32_e32 v105, v71
	v_pk_mul_f32 v[104:105], v[104:105], v[202:203]
	v_mul_f32_e32 v196, v108, v109
	v_mul_f32_e32 v199, v104, v105
	v_add_f32_e32 v104, 1.0, v106
	v_mul_f32_e32 v106, 0xbfb8aa3b, v102
	v_add_f32_e32 v105, 1.0, v107
	v_exp_f32_e32 v107, v106
	v_mul_f32_e32 v106, 0xbfb8aa3b, v103
	v_exp_f32_e32 v109, v106
	v_rcp_f32_e32 v106, v105
	v_add_f32_e32 v105, 1.0, v107
	v_mul_f32_e32 v107, 0xbfb8aa3b, v96
	v_rcp_f32_e32 v108, v105
	v_add_f32_e32 v105, 1.0, v109
	v_exp_f32_e32 v107, v107
	v_mul_f32_e32 v109, 0xbfb8aa3b, v97
	v_exp_f32_e32 v109, v109
	v_rcp_f32_e32 v110, v105
	v_add_f32_e32 v105, 1.0, v107
	v_mul_f32_e32 v107, 0xbfb8aa3b, v98
	v_rcp_f32_e32 v116, v105
	v_add_f32_e32 v105, 1.0, v109
	v_exp_f32_e32 v107, v107
	v_mul_f32_e32 v109, 0xbfb8aa3b, v99
	v_exp_f32_e32 v109, v109
	v_rcp_f32_e32 v118, v105
	v_add_f32_e32 v105, 1.0, v107
	v_rcp_f32_e32 v104, v104
	v_rcp_f32_e32 v120, v105
	v_add_f32_e32 v105, 1.0, v109
	v_rcp_f32_e32 v122, v105
	v_lshlrev_b32_e32 v105, 16, v148
	v_mov_b32_e32 v158, v100
	v_and_b32_e32 v100, 0xffff0000, v148
	v_sub_f32_e32 v105, v105, v114
	v_sub_f32_e32 v100, v100, v114
	v_mul_f32_e32 v105, v105, v115
	v_mov_b32_e32 v159, v56
	v_mul_f32_e32 v107, v100, v115
	v_mov_b32_e32 v100, v101
	v_mov_b32_e32 v101, v57
	v_pk_mul_f32 v[104:105], v[158:159], v[104:105]
	v_pk_mul_f32 v[100:101], v[100:101], v[106:107]
	v_mul_f32_e32 v104, v104, v105
	v_mul_f32_e32 v105, v100, v101
	v_lshlrev_b32_e32 v100, 16, v149
	v_sub_f32_e32 v100, v100, v114
	v_mul_f32_e32 v109, v100, v115
	v_mov_b32_e32 v100, v102
	v_mov_b32_e32 v101, v58
	v_pk_mul_f32 v[100:101], v[100:101], v[108:109]
	v_lshl_add_u64 v[132:133], v[132:133], 0, v[184:185]
	v_mul_f32_e32 v102, v100, v101
	v_and_b32_e32 v100, 0xffff0000, v149
	v_sub_f32_e32 v100, v100, v114
	v_mul_f32_e32 v111, v100, v115
	v_mov_b32_e32 v100, v103
	v_mov_b32_e32 v101, v59
	v_pk_mul_f32 v[100:101], v[100:101], v[110:111]
	v_lshl_add_u64 v[112:113], v[112:113], 0, v[184:185]
	v_mul_f32_e32 v103, v100, v101
	v_lshlrev_b32_e32 v100, 16, v150
	v_sub_f32_e32 v100, v100, v114
	v_mul_f32_e32 v117, v100, v115
	v_mov_b32_e32 v100, v96
	v_and_b32_e32 v96, 0xffff0000, v150
	v_sub_f32_e32 v96, v96, v114
	v_mov_b32_e32 v101, v48
	v_mul_f32_e32 v119, v96, v115
	v_mov_b32_e32 v96, v97
	v_mov_b32_e32 v97, v49
; DI float bflo(unsigned w) { return __uint_as_float(w << 16); }
; DI float bfhi(unsigned w) { return __uint_as_float(w & 0xffff0000u); }
; DI void store8(bf16_t* p, f32x4 a, f32x4 b) { u32x4 w = {cvt_pk_bf16(a[0], a[1]), cvt_pk_bf16(a[2], a[3]), cvt_pk_bf16(b[0], b[1]), cvt_pk_bf16(b[2], b[3])}; *(u32x4*)p = w; }
;     DI void operator()(const AccT& acc, const pg8::Unit& u, int wr, int wc, int fr, int fq) const {
;         const int col0 = u.pn * 256 + wc * 32 + 8 * fq, head = u.pn >> 1;
;         f32x4 g0[2], g1[2];
; #pragma unroll
;         for (int bj = 0; bj < 2; ++bj) { g0[bj] = *(const f32x4*)(gn + col0 + bj * 128); g1[bj] = *(const f32x4*)(gn + col0 + bj * 128 + 4); }
; #pragma unroll
;         for (int ai = 0; ai < 2; ++ai) {
;             float2 st[4]; u32x4 ov[4][2];
; #pragma unroll
;             for (int m = 0; m < 4; ++m) { const size_t row = (size_t)u.pm * 256 + wr * 64 + fr + ai * 128 + m * 16;
;                 st[m] = *(const float2*)(stats + (row * 4 + head) * 2);
; #pragma unroll
;                 for (int bj = 0; bj < 2; ++bj) ov[m][bj] = *(const u32x4*)(o + row * 2048 + col0 + bj * 128); }
; #pragma unroll
;             for (int m = 0; m < 4; ++m) { const size_t row = (size_t)u.pm * 256 + wr * 64 + fr + ai * 128 + m * 16;
;                 const float mean = st[m].x * (1.f / 512.f), var = fmaxf(st[m].y * (1.f / 512.f) - mean * mean, 0.f), rstd = rsqrtf(var + 1e-5f);
; #pragma unroll
;                 for (int bj = 0; bj < 2; ++bj) { bf16_t* op = o + row * 2048 + col0 + bj * 128; const u32x4 w = ov[m][bj];
;                     const f32x4 s0 = silu4(acc[ai][bj][m][0]), s1 = silu4(acc[ai][bj][m][1]);
;                     f32x4 y0, y1;
;                     y0[0] = (bflo(w[0]) - mean) * rstd * g0[bj][0] * s0[0]; y0[1] = (bfhi(w[0]) - mean) * rstd * g0[bj][1] * s0[1];
;                     y0[2] = (bflo(w[1]) - mean) * rstd * g0[bj][2] * s0[2]; y0[3] = (bfhi(w[1]) - mean) * rstd * g0[bj][3] * s0[3];
;                     y1[0] = (bflo(w[2]) - mean) * rstd * g1[bj][0] * s1[0]; y1[1] = (bfhi(w[2]) - mean) * rstd * g1[bj][1] * s1[1];
;                     y1[2] = (bflo(w[3]) - mean) * rstd * g1[bj][2] * s1[2]; y1[3] = (bfhi(w[3]) - mean) * rstd * g1[bj][3] * s1[3];
;                     store8(op, y0, y1); } } }
	v_pk_mul_f32 v[100:101], v[100:101], v[116:117]
	v_pk_mul_f32 v[96:97], v[96:97], v[118:119]
	v_mul_f32_e32 v100, v100, v101
	v_mul_f32_e32 v101, v96, v97
	v_lshlrev_b32_e32 v96, 16, v151
	v_sub_f32_e32 v96, v96, v114
	v_mul_f32_e32 v121, v96, v115
	v_mov_b32_e32 v96, v98
	v_mov_b32_e32 v97, v50
	v_pk_mul_f32 v[96:97], v[96:97], v[120:121]
	v_mov_b32_e32 v116, v92
	v_mul_f32_e32 v106, v96, v97
	v_and_b32_e32 v96, 0xffff0000, v151
	v_sub_f32_e32 v96, v96, v114
	v_mul_f32_e32 v123, v96, v115
	v_mov_b32_e32 v96, v99
	v_mov_b32_e32 v97, v51
	v_pk_mul_f32 v[96:97], v[96:97], v[122:123]
	v_mov_b32_e32 v117, v60
	v_mul_f32_e32 v107, v96, v97
	v_cvt_pk_bf16_f32 v96, v152, v153
	v_cvt_pk_bf16_f32 v97, v154, v155
	v_cvt_pk_bf16_f32 v98, v144, v145
	v_cvt_pk_bf16_f32 v99, v146, v147
	global_store_dwordx4 v[192:193], v[96:99], off
	s_nop 1
	v_cvt_pk_bf16_f32 v96, v136, v137
	v_cvt_pk_bf16_f32 v97, v138, v139
	v_cvt_pk_bf16_f32 v98, v164, v165
	v_cvt_pk_bf16_f32 v99, v166, v135
	global_store_dwordx4 v[192:193], v[96:99], off offset:256
	s_nop 1
	v_cvt_pk_bf16_f32 v96, v124, v125
	v_cvt_pk_bf16_f32 v97, v126, v127
	v_cvt_pk_bf16_f32 v98, v160, v161
	v_cvt_pk_bf16_f32 v99, v162, v163
	global_store_dwordx4 v[132:133], v[96:99], off
	v_mul_f32_e32 v127, 0xbfb8aa3b, v77
	v_exp_f32_e32 v127, v127
	v_cvt_pk_bf16_f32 v96, v209, v220
	v_cvt_pk_bf16_f32 v97, v221, v210
	v_cvt_pk_bf16_f32 v98, v211, v212
	v_cvt_pk_bf16_f32 v99, v213, v134
	global_store_dwordx4 v[132:133], v[96:99], off offset:256
	v_add_f32_e32 v127, 1.0, v127
	s_nop 0
	v_cvt_pk_bf16_f32 v96, v167, v204
	v_cvt_pk_bf16_f32 v97, v205, v214
	v_cvt_pk_bf16_f32 v98, v196, v197
	v_cvt_pk_bf16_f32 v99, v198, v199
	global_store_dwordx4 v[112:113], v[96:99], off
	s_waitcnt vmcnt(0)
	s_nop 0
	v_pk_mul_f32 v[96:97], v[156:157], s[54:55] op_sel_hi:[1,0]
	v_cvt_pk_bf16_f32 v98, v104, v105
	v_cvt_pk_bf16_f32 v99, v102, v103
	v_cvt_pk_bf16_f32 v100, v100, v101
	v_cvt_pk_bf16_f32 v101, v106, v107
	global_store_dwordx4 v[112:113], v[98:101], off offset:256
	v_fma_f32 v97, -v96, v96, v97
	v_max_f32_e32 v97, 0, v97
	v_add_f32_e32 v97, 0x3727c5ac, v97
	v_mul_f32_e32 v102, 0x4b800000, v97
	v_cmp_gt_f32_e32 vcc, s94, v97
	v_mul_f32_e32 v101, 0xbfb8aa3b, v93
	v_exp_f32_e32 v101, v101
	v_cndmask_b32_e32 v97, v97, v102, vcc
	v_mul_f32_e32 v102, 0xbfb8aa3b, v94
	v_exp_f32_e32 v103, v102
	v_mul_f32_e32 v102, 0xbfb8aa3b, v95
	v_exp_f32_e32 v105, v102
	v_add_f32_e32 v101, 1.0, v101
	v_rcp_f32_e32 v102, v101
	v_add_f32_e32 v101, 1.0, v103
	v_mul_f32_e32 v103, 0xbfb8aa3b, v88
	v_rcp_f32_e32 v104, v101
	v_add_f32_e32 v101, 1.0, v105
	v_exp_f32_e32 v103, v103
	v_mul_f32_e32 v105, 0xbfb8aa3b, v89
	v_exp_f32_e32 v105, v105
	v_mul_f32_e32 v100, 0xbfb8aa3b, v92
	v_rcp_f32_e32 v106, v101
	v_add_f32_e32 v101, 1.0, v103
	v_mul_f32_e32 v103, 0xbfb8aa3b, v90
	v_exp_f32_e32 v100, v100
	v_rcp_f32_e32 v108, v101
	v_add_f32_e32 v101, 1.0, v105
	v_exp_f32_e32 v103, v103
	v_mul_f32_e32 v105, 0xbfb8aa3b, v91
	v_exp_f32_e32 v105, v105
	v_rsq_f32_e32 v97, v97
	v_add_f32_e32 v100, 1.0, v100
	v_rcp_f32_e32 v110, v101
	v_add_f32_e32 v101, 1.0, v103
	v_rcp_f32_e32 v100, v100
	v_rcp_f32_e32 v112, v101
	v_add_f32_e32 v101, 1.0, v105
	v_mul_f32_e32 v98, 0x45800000, v97
	v_rcp_f32_e32 v114, v101
	v_lshlrev_b32_e32 v101, 16, v140
	v_and_b32_e32 v92, 0xffff0000, v140
	v_cndmask_b32_e32 v97, v97, v98, vcc
	v_sub_f32_e32 v101, v101, v96
	v_sub_f32_e32 v92, v92, v96
	v_mul_f32_e32 v101, v101, v97
	v_mul_f32_e32 v103, v92, v97
	v_mov_b32_e32 v92, v93
	v_mov_b32_e32 v93, v61
	v_pk_mul_f32 v[100:101], v[116:117], v[100:101]
	v_pk_mul_f32 v[92:93], v[92:93], v[102:103]
	v_mul_f32_e32 v100, v100, v101
	v_mul_f32_e32 v101, v92, v93
	v_lshlrev_b32_e32 v92, 16, v141
	v_sub_f32_e32 v92, v92, v96
	v_mul_f32_e32 v105, v92, v97
	v_mov_b32_e32 v92, v94
	v_mov_b32_e32 v93, v62
	v_pk_mul_f32 v[92:93], v[92:93], v[104:105]
	v_lshl_add_u64 v[98:99], s[96:97], 0, v[190:191]
	v_mul_f32_e32 v94, v92, v93
	v_and_b32_e32 v92, 0xffff0000, v141
	v_sub_f32_e32 v92, v92, v96
	v_mul_f32_e32 v107, v92, v97
	v_mov_b32_e32 v92, v95
	v_mov_b32_e32 v93, v63
	v_pk_mul_f32 v[92:93], v[92:93], v[106:107]
	v_lshl_add_u64 v[98:99], v[98:99], 0, v[184:185]
	v_mul_f32_e32 v95, v92, v93
	v_lshlrev_b32_e32 v92, 16, v142
	v_sub_f32_e32 v92, v92, v96
	v_mul_f32_e32 v109, v92, v97
	v_mov_b32_e32 v92, v88
	v_and_b32_e32 v88, 0xffff0000, v142
	v_sub_f32_e32 v88, v88, v96
	v_mov_b32_e32 v93, v68
	v_mul_f32_e32 v111, v88, v97
	v_mov_b32_e32 v88, v89
	v_mov_b32_e32 v89, v69
	v_pk_mul_f32 v[92:93], v[92:93], v[108:109]
	v_pk_mul_f32 v[88:89], v[88:89], v[110:111]
	v_mul_f32_e32 v92, v92, v93
	v_mul_f32_e32 v93, v88, v89
	v_lshlrev_b32_e32 v88, 16, v143
	v_sub_f32_e32 v88, v88, v96
	v_mul_f32_e32 v113, v88, v97
	v_mov_b32_e32 v88, v90
	v_mov_b32_e32 v89, v70
	v_pk_mul_f32 v[88:89], v[88:89], v[112:113]
	v_mov_b32_e32 v108, v84
	v_mul_f32_e32 v102, v88, v89
	v_and_b32_e32 v88, 0xffff0000, v143
	v_sub_f32_e32 v88, v88, v96
	v_mul_f32_e32 v115, v88, v97
	v_mov_b32_e32 v88, v91
	v_mov_b32_e32 v89, v71
	v_pk_mul_f32 v[88:89], v[88:89], v[114:115]
	v_mov_b32_e32 v109, v56
	v_mul_f32_e32 v91, v88, v89
	v_cvt_pk_bf16_f32 v88, v100, v101
	v_cvt_pk_bf16_f32 v89, v94, v95
	v_cvt_pk_bf16_f32 v90, v92, v93
	v_mul_f32_e32 v93, 0xbfb8aa3b, v85
	v_exp_f32_e32 v93, v93
	v_cvt_pk_bf16_f32 v91, v102, v91
	global_store_dwordx4 v[98:99], v[88:91], off
	v_mul_f32_e32 v92, 0xbfb8aa3b, v84
	v_exp_f32_e32 v92, v92
	v_mul_f32_e32 v90, 0xbfb8aa3b, v86
	v_exp_f32_e32 v91, v90
	v_mul_f32_e32 v90, 0xbfb8aa3b, v87
	v_add_f32_e32 v89, 1.0, v93
	v_exp_f32_e32 v93, v90
	v_rcp_f32_e32 v90, v89
	v_add_f32_e32 v89, 1.0, v91
; DI float bflo(unsigned w) { return __uint_as_float(w << 16); }
; DI float bfhi(unsigned w) { return __uint_as_float(w & 0xffff0000u); }
; DI void store8(bf16_t* p, f32x4 a, f32x4 b) { u32x4 w = {cvt_pk_bf16(a[0], a[1]), cvt_pk_bf16(a[2], a[3]), cvt_pk_bf16(b[0], b[1]), cvt_pk_bf16(b[2], b[3])}; *(u32x4*)p = w; }
; DI f32x4 silu4(f32x4 v) { f32x4 r; r[0] = silu_f(v[0]); r[1] = silu_f(v[1]); r[2] = silu_f(v[2]); r[3] = silu_f(v[3]); return r; }
;     DI void operator()(const AccT& acc, const pg8::Unit& u, int wr, int wc, int fr, int fq) const {
;     ...
;             for (int m = 0; m < 4; ++m) { const size_t row = (size_t)u.pm * 256 + wr * 64 + fr + ai * 128 + m * 16;
;                 st[m] = *(const float2*)(stats + (row * 4 + head) * 2);
; #pragma unroll
;                 for (int bj = 0; bj < 2; ++bj) ov[m][bj] = *(const u32x4*)(o + row * 2048 + col0 + bj * 128); }
; #pragma unroll
;             for (int m = 0; m < 4; ++m) { const size_t row = (size_t)u.pm * 256 + wr * 64 + fr + ai * 128 + m * 16;
;                 const float mean = st[m].x * (1.f / 512.f), var = fmaxf(st[m].y * (1.f / 512.f) - mean * mean, 0.f), rstd = rsqrtf(var + 1e-5f);
; #pragma unroll
;                 for (int bj = 0; bj < 2; ++bj) { bf16_t* op = o + row * 2048 + col0 + bj * 128; const u32x4 w = ov[m][bj];
;                     const f32x4 s0 = silu4(acc[ai][bj][m][0]), s1 = silu4(acc[ai][bj][m][1]);
;                     f32x4 y0, y1;
;                     y0[0] = (bflo(w[0]) - mean) * rstd * g0[bj][0] * s0[0]; y0[1] = (bfhi(w[0]) - mean) * rstd * g0[bj][1] * s0[1];
;                     y0[2] = (bflo(w[1]) - mean) * rstd * g0[bj][2] * s0[2]; y0[3] = (bfhi(w[1]) - mean) * rstd * g0[bj][3] * s0[3];
;                     y1[0] = (bflo(w[2]) - mean) * rstd * g1[bj][0] * s1[0]; y1[1] = (bfhi(w[2]) - mean) * rstd * g1[bj][1] * s1[1];
;                     y1[2] = (bflo(w[3]) - mean) * rstd * g1[bj][2] * s1[2]; y1[3] = (bfhi(w[3]) - mean) * rstd * g1[bj][3] * s1[3];
;                     store8(op, y0, y1); } } }
	v_mul_f32_e32 v91, 0xbfb8aa3b, v80
	v_add_f32_e32 v88, 1.0, v92
	v_rcp_f32_e32 v92, v89
	v_add_f32_e32 v89, 1.0, v93
	v_exp_f32_e32 v91, v91
	v_mul_f32_e32 v93, 0xbfb8aa3b, v81
	v_exp_f32_e32 v93, v93
	v_rcp_f32_e32 v94, v89
	v_add_f32_e32 v89, 1.0, v91
	v_mul_f32_e32 v91, 0xbfb8aa3b, v82
	v_rcp_f32_e32 v100, v89
	v_add_f32_e32 v89, 1.0, v93
	v_exp_f32_e32 v91, v91
	v_mul_f32_e32 v93, 0xbfb8aa3b, v83
	v_exp_f32_e32 v93, v93
	v_rcp_f32_e32 v102, v89
	v_add_f32_e32 v89, 1.0, v91
	v_rcp_f32_e32 v88, v88
	v_rcp_f32_e32 v104, v89
	v_add_f32_e32 v89, 1.0, v93
	v_rcp_f32_e32 v106, v89
	v_lshlrev_b32_e32 v89, 16, v128
	v_and_b32_e32 v84, 0xffff0000, v128
	v_sub_f32_e32 v89, v89, v96
	v_sub_f32_e32 v84, v84, v96
	v_mul_f32_e32 v89, v89, v97
	v_mul_f32_e32 v91, v84, v97
	v_mov_b32_e32 v84, v85
	v_mov_b32_e32 v85, v57
	v_pk_mul_f32 v[88:89], v[108:109], v[88:89]
	v_pk_mul_f32 v[84:85], v[84:85], v[90:91]
	v_mul_f32_e32 v88, v88, v89
	v_mul_f32_e32 v89, v84, v85
	v_lshlrev_b32_e32 v84, 16, v129
	v_sub_f32_e32 v84, v84, v96
	v_mul_f32_e32 v93, v84, v97
	v_mov_b32_e32 v84, v86
	v_mov_b32_e32 v85, v58
	v_pk_mul_f32 v[84:85], v[84:85], v[92:93]
	v_mul_f32_e32 v128, 0xbfb8aa3b, v78
	v_mul_f32_e32 v86, v84, v85
	v_and_b32_e32 v84, 0xffff0000, v129
	v_sub_f32_e32 v84, v84, v96
	v_mul_f32_e32 v95, v84, v97
	v_mov_b32_e32 v84, v87
	v_mov_b32_e32 v85, v59
	v_pk_mul_f32 v[84:85], v[84:85], v[94:95]
	v_exp_f32_e32 v129, v128
	v_mul_f32_e32 v87, v84, v85
	v_lshlrev_b32_e32 v84, 16, v130
	v_sub_f32_e32 v84, v84, v96
	v_mul_f32_e32 v101, v84, v97
	v_mov_b32_e32 v84, v80
	v_and_b32_e32 v80, 0xffff0000, v130
	v_sub_f32_e32 v80, v80, v96
	v_mov_b32_e32 v85, v48
	v_mul_f32_e32 v103, v80, v97
	v_mov_b32_e32 v80, v81
	v_mov_b32_e32 v81, v49
	v_pk_mul_f32 v[84:85], v[84:85], v[100:101]
	v_pk_mul_f32 v[80:81], v[80:81], v[102:103]
	v_mul_f32_e32 v84, v84, v85
	v_mul_f32_e32 v85, v80, v81
	v_lshlrev_b32_e32 v80, 16, v131
	v_sub_f32_e32 v80, v80, v96
	v_mul_f32_e32 v105, v80, v97
	v_mov_b32_e32 v80, v82
	v_mov_b32_e32 v81, v50
	v_pk_mul_f32 v[80:81], v[80:81], v[104:105]
	v_mul_f32_e32 v128, 0xbfb8aa3b, v79
	v_mul_f32_e32 v90, v80, v81
	v_and_b32_e32 v80, 0xffff0000, v131
	v_sub_f32_e32 v80, v80, v96
	v_mul_f32_e32 v107, v80, v97
	v_mov_b32_e32 v80, v83
	v_mov_b32_e32 v81, v51
	v_pk_mul_f32 v[80:81], v[80:81], v[106:107]
	v_exp_f32_e32 v131, v128
	v_mul_f32_e32 v83, v80, v81
	v_cvt_pk_bf16_f32 v80, v88, v89
	v_cvt_pk_bf16_f32 v81, v86, v87
	v_cvt_pk_bf16_f32 v82, v84, v85
	v_cvt_pk_bf16_f32 v83, v90, v83
	global_store_dwordx4 v[98:99], v[80:83], off offset:256
	v_rcp_f32_e32 v128, v127
	v_add_f32_e32 v127, 1.0, v129
	v_lshl_add_u64 v[80:81], v[188:189], 0, s[38:39]
	v_lshlrev_b64 v[82:83], 5, v[80:81]
	v_lshl_add_u64 v[82:83], s[16:17], 0, v[82:83]
	global_load_dwordx2 v[82:83], v[82:83], off
	v_lshlrev_b64 v[106:107], 12, v[80:81]
	v_lshl_add_u64 v[80:81], v[186:187], 0, v[106:107]
	global_load_dwordx4 v[122:125], v[80:81], off
	global_load_dwordx4 v[100:103], v[80:81], off offset:256
	v_lshl_add_u64 v[80:81], v[188:189], 0, s[20:21]
	v_lshlrev_b64 v[116:117], 12, v[80:81]
	v_lshlrev_b64 v[84:85], 5, v[80:81]
	v_lshl_add_u64 v[80:81], v[186:187], 0, v[116:117]
	s_mov_b64 s[20:21], 0xa0
	global_load_dwordx4 v[96:99], v[80:81], off
	global_load_dwordx4 v[92:95], v[80:81], off offset:256
	v_lshl_add_u64 v[80:81], v[188:189], 0, s[20:21]
	s_mov_b64 s[20:21], 0xb0
	v_lshl_add_u64 v[120:121], s[16:17], 0, v[84:85]
	v_lshlrev_b64 v[84:85], 5, v[80:81]
	v_lshlrev_b64 v[110:111], 12, v[80:81]
	v_lshl_add_u64 v[80:81], v[188:189], 0, s[20:21]
	v_lshl_add_u64 v[112:113], s[16:17], 0, v[84:85]
	v_lshlrev_b64 v[84:85], 5, v[80:81]
	v_lshlrev_b64 v[104:105], 12, v[80:81]
	v_lshl_add_u64 v[114:115], v[186:187], 0, v[110:111]
	global_load_dwordx4 v[88:91], v[114:115], off offset:256
	v_lshl_add_u64 v[108:109], s[16:17], 0, v[84:85]
	v_mul_f32_e32 v129, 0xbfb8aa3b, v72
	v_rcp_f32_e32 v130, v127
	v_add_f32_e32 v127, 1.0, v131
	v_exp_f32_e32 v129, v129
	v_mul_f32_e32 v131, 0xbfb8aa3b, v73
	v_exp_f32_e32 v131, v131
	v_rcp_f32_e32 v132, v127
	v_add_f32_e32 v127, 1.0, v129
	v_mul_f32_e32 v129, 0xbfb8aa3b, v74
	v_rcp_f32_e32 v134, v127
	v_add_f32_e32 v127, 1.0, v131
	v_exp_f32_e32 v129, v129
	v_mul_f32_e32 v131, 0xbfb8aa3b, v75
	v_exp_f32_e32 v131, v131
	v_rcp_f32_e32 v136, v127
	v_add_f32_e32 v127, 1.0, v129
	v_rcp_f32_e32 v138, v127
	v_add_f32_e32 v127, 1.0, v131
	v_rcp_f32_e32 v140, v127
	v_mov_b32_e32 v142, v76
	v_mov_b32_e32 v143, v60
	v_lshl_add_u64 v[106:107], s[96:97], 0, v[106:107]
	v_lshl_add_u64 v[106:107], v[106:107], 0, v[184:185]
	s_mov_b32 s16, s10
	s_mov_b64 s[20:21], s[12:13]
	s_waitcnt vmcnt(0)
; DI float bflo(unsigned w) { return __uint_as_float(w << 16); }
; DI float bfhi(unsigned w) { return __uint_as_float(w & 0xffff0000u); }
; DI void store8(bf16_t* p, f32x4 a, f32x4 b) { u32x4 w = {cvt_pk_bf16(a[0], a[1]), cvt_pk_bf16(a[2], a[3]), cvt_pk_bf16(b[0], b[1]), cvt_pk_bf16(b[2], b[3])}; *(u32x4*)p = w; }
; DI f32x4 silu4(f32x4 v) { f32x4 r; r[0] = silu_f(v[0]); r[1] = silu_f(v[1]); r[2] = silu_f(v[2]); r[3] = silu_f(v[3]); return r; }
;     DI void operator()(const AccT& acc, const pg8::Unit& u, int wr, int wc, int fr, int fq) const {
;     ...
;             for (int m = 0; m < 4; ++m) { const size_t row = (size_t)u.pm * 256 + wr * 64 + fr + ai * 128 + m * 16;
;                 st[m] = *(const float2*)(stats + (row * 4 + head) * 2);
; #pragma unroll
;                 for (int bj = 0; bj < 2; ++bj) ov[m][bj] = *(const u32x4*)(o + row * 2048 + col0 + bj * 128); }
; #pragma unroll
;             for (int m = 0; m < 4; ++m) { const size_t row = (size_t)u.pm * 256 + wr * 64 + fr + ai * 128 + m * 16;
;                 const float mean = st[m].x * (1.f / 512.f), var = fmaxf(st[m].y * (1.f / 512.f) - mean * mean, 0.f), rstd = rsqrtf(var + 1e-5f);
; #pragma unroll
;                 for (int bj = 0; bj < 2; ++bj) { bf16_t* op = o + row * 2048 + col0 + bj * 128; const u32x4 w = ov[m][bj];
;                     const f32x4 s0 = silu4(acc[ai][bj][m][0]), s1 = silu4(acc[ai][bj][m][1]);
;                     f32x4 y0, y1;
;                     y0[0] = (bflo(w[0]) - mean) * rstd * g0[bj][0] * s0[0]; y0[1] = (bfhi(w[0]) - mean) * rstd * g0[bj][1] * s0[1];
;                     y0[2] = (bflo(w[1]) - mean) * rstd * g0[bj][2] * s0[2]; y0[3] = (bfhi(w[1]) - mean) * rstd * g0[bj][3] * s0[3];
;                     y1[0] = (bflo(w[2]) - mean) * rstd * g1[bj][0] * s1[0]; y1[1] = (bfhi(w[2]) - mean) * rstd * g1[bj][1] * s1[1];
;                     y1[2] = (bflo(w[3]) - mean) * rstd * g1[bj][2] * s1[2]; y1[3] = (bfhi(w[3]) - mean) * rstd * g1[bj][3] * s1[3];
;                     store8(op, y0, y1); } } }
	v_pk_mul_f32 v[118:119], v[82:83], s[54:55] op_sel_hi:[1,0]
	s_nop 0
	v_fma_f32 v80, -v118, v118, v119
	v_max_f32_e32 v80, 0, v80
	v_add_f32_e32 v80, 0x3727c5ac, v80
	v_mul_f32_e32 v81, 0x4b800000, v80
	v_cmp_gt_f32_e32 vcc, s94, v80
	v_lshlrev_b32_e32 v127, 16, v122
	v_and_b32_e32 v122, 0xffff0000, v122
	v_cndmask_b32_e32 v80, v80, v81, vcc
	v_rsq_f32_e32 v119, v80
	v_lshl_add_u64 v[80:81], v[186:187], 0, v[104:105]
	global_load_dwordx4 v[84:87], v[80:81], off
	s_nop 0
	global_load_dwordx4 v[80:83], v[80:81], off offset:256
	v_sub_f32_e32 v122, v122, v118
	global_load_dwordx2 v[120:121], v[120:121], off
	v_mul_f32_e32 v126, 0x45800000, v119
	v_cndmask_b32_e32 v119, v119, v126, vcc
	v_mul_f32_e32 v129, v122, v119
	v_lshlrev_b32_e32 v122, 16, v123
	v_sub_f32_e32 v122, v122, v118
	v_mul_f32_e32 v131, v122, v119
	v_and_b32_e32 v122, 0xffff0000, v123
	v_sub_f32_e32 v122, v122, v118
	v_mul_f32_e32 v133, v122, v119
	v_mov_b32_e32 v122, v79
	v_mov_b32_e32 v123, v63
	v_pk_mul_f32 v[122:123], v[122:123], v[132:133]
	v_mul_f32_e32 v126, 0xbfb8aa3b, v76
	v_mul_f32_e32 v79, v122, v123
	v_lshlrev_b32_e32 v122, 16, v124
	v_sub_f32_e32 v122, v122, v118
	v_mul_f32_e32 v135, v122, v119
	v_mov_b32_e32 v122, v72
	v_mov_b32_e32 v123, v68
	v_pk_mul_f32 v[122:123], v[122:123], v[134:135]
	v_exp_f32_e32 v126, v126
	v_mul_f32_e32 v72, v122, v123
	v_and_b32_e32 v122, 0xffff0000, v124
	v_sub_f32_e32 v122, v122, v118
	v_mul_f32_e32 v137, v122, v119
	v_mov_b32_e32 v122, v73
	v_mov_b32_e32 v123, v69
	v_pk_mul_f32 v[122:123], v[122:123], v[136:137]
	v_add_f32_e32 v126, 1.0, v126
	v_mul_f32_e32 v73, v122, v123
	v_lshlrev_b32_e32 v122, 16, v125
	v_sub_f32_e32 v122, v122, v118
	v_mul_f32_e32 v139, v122, v119
	v_mov_b32_e32 v122, v74
	v_mov_b32_e32 v123, v70
	v_pk_mul_f32 v[122:123], v[122:123], v[138:139]
	v_rcp_f32_e32 v126, v126
	v_mul_f32_e32 v74, v122, v123
	v_and_b32_e32 v122, 0xffff0000, v125
	v_sub_f32_e32 v122, v122, v118
	v_sub_f32_e32 v127, v127, v118
	v_mul_f32_e32 v141, v122, v119
	v_mov_b32_e32 v122, v75
	v_mul_f32_e32 v75, 0xbfb8aa3b, v64
	v_mul_f32_e32 v127, v127, v119
	v_exp_f32_e32 v124, v75
	v_pk_mul_f32 v[126:127], v[142:143], v[126:127]
	v_mov_b32_e32 v123, v71
	v_mul_f32_e32 v76, v126, v127
	v_mov_b32_e32 v126, v77
	v_mov_b32_e32 v127, v61
	v_pk_mul_f32 v[122:123], v[122:123], v[140:141]
	v_pk_mul_f32 v[126:127], v[126:127], v[128:129]
	v_mul_f32_e32 v75, v122, v123
	v_mul_f32_e32 v122, 0xbfb8aa3b, v65
	v_mul_f32_e32 v77, v126, v127
	v_mov_b32_e32 v126, v78
	v_mov_b32_e32 v127, v62
	v_exp_f32_e32 v123, v122
	v_add_f32_e32 v122, 1.0, v124
	v_mul_f32_e32 v124, 0xbfb8aa3b, v66
	v_pk_mul_f32 v[126:127], v[126:127], v[130:131]
	v_exp_f32_e32 v125, v124
	v_mul_f32_e32 v124, 0xbfb8aa3b, v67
	v_mul_f32_e32 v78, v126, v127
	v_exp_f32_e32 v127, v124
	v_add_f32_e32 v123, 1.0, v123
	v_rcp_f32_e32 v124, v123
	v_add_f32_e32 v123, 1.0, v125
	v_mul_f32_e32 v125, 0xbfb8aa3b, v52
	v_rcp_f32_e32 v126, v123
	v_add_f32_e32 v123, 1.0, v127
	v_exp_f32_e32 v125, v125
	v_mul_f32_e32 v127, 0xbfb8aa3b, v53
	v_exp_f32_e32 v127, v127
	v_rcp_f32_e32 v128, v123
	v_add_f32_e32 v123, 1.0, v125
	v_mul_f32_e32 v125, 0xbfb8aa3b, v54
	v_rcp_f32_e32 v130, v123
	v_add_f32_e32 v123, 1.0, v127
	v_exp_f32_e32 v125, v125
	v_mul_f32_e32 v127, 0xbfb8aa3b, v55
	v_exp_f32_e32 v127, v127
	v_rcp_f32_e32 v132, v123
	v_add_f32_e32 v123, 1.0, v125
	v_rcp_f32_e32 v134, v123
	v_add_f32_e32 v123, 1.0, v127
	v_rcp_f32_e32 v136, v123
	v_lshlrev_b32_e32 v123, 16, v100
	v_and_b32_e32 v100, 0xffff0000, v100
	v_sub_f32_e32 v100, v100, v118
	v_mul_f32_e32 v125, v100, v119
	v_lshlrev_b32_e32 v100, 16, v101
	v_sub_f32_e32 v100, v100, v118
	v_mul_f32_e32 v127, v100, v119
	v_and_b32_e32 v100, 0xffff0000, v101
	v_sub_f32_e32 v100, v100, v118
	v_mul_f32_e32 v129, v100, v119
	v_mov_b32_e32 v100, v67
	v_mov_b32_e32 v101, v59
	v_pk_mul_f32 v[100:101], v[100:101], v[128:129]
	v_sub_f32_e32 v123, v123, v118
	v_mul_f32_e32 v67, v100, v101
	v_lshlrev_b32_e32 v100, 16, v102
	v_sub_f32_e32 v100, v100, v118
	v_mul_f32_e32 v131, v100, v119
	v_mov_b32_e32 v100, v52
	v_and_b32_e32 v52, 0xffff0000, v102
	v_sub_f32_e32 v52, v52, v118
	v_mov_b32_e32 v101, v48
	v_mul_f32_e32 v133, v52, v119
	v_mov_b32_e32 v52, v53
	v_mov_b32_e32 v53, v49
	v_pk_mul_f32 v[100:101], v[100:101], v[130:131]
	v_pk_mul_f32 v[52:53], v[52:53], v[132:133]
	v_mul_f32_e32 v100, v100, v101
	v_mul_f32_e32 v101, v52, v53
	v_lshlrev_b32_e32 v52, 16, v103
	v_sub_f32_e32 v52, v52, v118
	v_mul_f32_e32 v135, v52, v119
	v_mov_b32_e32 v52, v54
	v_mov_b32_e32 v53, v50
	v_pk_mul_f32 v[52:53], v[52:53], v[134:135]
	v_rcp_f32_e32 v122, v122
	v_mul_f32_e32 v102, v52, v53
	v_and_b32_e32 v52, 0xffff0000, v103
	v_sub_f32_e32 v52, v52, v118
	v_mul_f32_e32 v137, v52, v119
	v_mov_b32_e32 v52, v55
	s_waitcnt vmcnt(0)
; DI float bflo(unsigned w) { return __uint_as_float(w << 16); }
; DI float bfhi(unsigned w) { return __uint_as_float(w & 0xffff0000u); }
; DI void store8(bf16_t* p, f32x4 a, f32x4 b) { u32x4 w = {cvt_pk_bf16(a[0], a[1]), cvt_pk_bf16(a[2], a[3]), cvt_pk_bf16(b[0], b[1]), cvt_pk_bf16(b[2], b[3])}; *(u32x4*)p = w; }
; DI f32x4 silu4(f32x4 v) { f32x4 r; r[0] = silu_f(v[0]); r[1] = silu_f(v[1]); r[2] = silu_f(v[2]); r[3] = silu_f(v[3]); return r; }
;     DI void operator()(const AccT& acc, const pg8::Unit& u, int wr, int wc, int fr, int fq) const {
;     ...
;             for (int m = 0; m < 4; ++m) { const size_t row = (size_t)u.pm * 256 + wr * 64 + fr + ai * 128 + m * 16;
;                 st[m] = *(const float2*)(stats + (row * 4 + head) * 2);
; #pragma unroll
;                 for (int bj = 0; bj < 2; ++bj) ov[m][bj] = *(const u32x4*)(o + row * 2048 + col0 + bj * 128); }
; #pragma unroll
;             for (int m = 0; m < 4; ++m) { const size_t row = (size_t)u.pm * 256 + wr * 64 + fr + ai * 128 + m * 16;
;                 const float mean = st[m].x * (1.f / 512.f), var = fmaxf(st[m].y * (1.f / 512.f) - mean * mean, 0.f), rstd = rsqrtf(var + 1e-5f);
; #pragma unroll
;                 for (int bj = 0; bj < 2; ++bj) { bf16_t* op = o + row * 2048 + col0 + bj * 128; const u32x4 w = ov[m][bj];
;                     const f32x4 s0 = silu4(acc[ai][bj][m][0]), s1 = silu4(acc[ai][bj][m][1]);
;                     f32x4 y0, y1;
;                     y0[0] = (bflo(w[0]) - mean) * rstd * g0[bj][0] * s0[0]; y0[1] = (bfhi(w[0]) - mean) * rstd * g0[bj][1] * s0[1];
;                     y0[2] = (bflo(w[1]) - mean) * rstd * g0[bj][2] * s0[2]; y0[3] = (bfhi(w[1]) - mean) * rstd * g0[bj][3] * s0[3];
;                     y1[0] = (bflo(w[2]) - mean) * rstd * g1[bj][0] * s1[0]; y1[1] = (bfhi(w[2]) - mean) * rstd * g1[bj][1] * s1[1];
;                     y1[2] = (bflo(w[3]) - mean) * rstd * g1[bj][2] * s1[2]; y1[3] = (bfhi(w[3]) - mean) * rstd * g1[bj][3] * s1[3];
;                     store8(op, y0, y1); } } }
	v_pk_mul_f32 v[54:55], v[120:121], s[54:55] op_sel_hi:[1,0]
	v_mul_f32_e32 v118, 0xbfb8aa3b, v46
	v_fma_f32 v53, -v54, v54, v55
	v_max_f32_e32 v53, 0, v53
	v_add_f32_e32 v53, 0x3727c5ac, v53
	v_mul_f32_e32 v55, 0x4b800000, v53
	v_cmp_gt_f32_e32 vcc, s94, v53
	v_mul_f32_e32 v123, v123, v119
	v_exp_f32_e32 v119, v118
	v_cndmask_b32_e32 v53, v53, v55, vcc
	v_rsq_f32_e32 v103, v53
	v_mov_b32_e32 v53, v51
	v_pk_mul_f32 v[52:53], v[52:53], v[136:137]
	v_mul_f32_e32 v118, 0xbfb8aa3b, v47
	v_mul_f32_e32 v55, v52, v53
	v_mul_f32_e32 v52, 0x45800000, v103
	v_cndmask_b32_e32 v103, v103, v52, vcc
	v_lshl_add_u64 v[52:53], s[96:97], 0, v[116:117]
	v_mul_f32_e32 v117, 0xbfb8aa3b, v45
	v_exp_f32_e32 v117, v117
	v_exp_f32_e32 v121, v118
	v_mov_b32_e32 v138, v64
	v_mov_b32_e32 v139, v56
	v_add_f32_e32 v117, 1.0, v117
	v_pk_mul_f32 v[122:123], v[138:139], v[122:123]
	v_rcp_f32_e32 v118, v117
	v_add_f32_e32 v117, 1.0, v119
	v_mul_f32_e32 v119, 0xbfb8aa3b, v40
	v_mul_f32_e32 v64, v122, v123
	v_mov_b32_e32 v122, v65
	v_mov_b32_e32 v123, v57
	v_rcp_f32_e32 v120, v117
	v_add_f32_e32 v117, 1.0, v121
	v_exp_f32_e32 v119, v119
	v_mul_f32_e32 v121, 0xbfb8aa3b, v41
	v_pk_mul_f32 v[122:123], v[122:123], v[124:125]
	v_exp_f32_e32 v121, v121
	v_mul_f32_e32 v65, v122, v123
	v_mov_b32_e32 v122, v66
	v_mov_b32_e32 v123, v58
	v_pk_mul_f32 v[122:123], v[122:123], v[126:127]
	v_mul_f32_e32 v116, 0xbfb8aa3b, v44
	v_mul_f32_e32 v66, v122, v123
	v_rcp_f32_e32 v122, v117
	v_add_f32_e32 v117, 1.0, v119
	v_mul_f32_e32 v119, 0xbfb8aa3b, v42
	v_rcp_f32_e32 v124, v117
	v_add_f32_e32 v117, 1.0, v121
	v_exp_f32_e32 v119, v119
	v_mul_f32_e32 v121, 0xbfb8aa3b, v43
	v_exp_f32_e32 v121, v121
	v_rcp_f32_e32 v126, v117
	v_add_f32_e32 v117, 1.0, v119
	v_rcp_f32_e32 v128, v117
	v_add_f32_e32 v117, 1.0, v121
	v_rcp_f32_e32 v130, v117
	v_lshlrev_b32_e32 v117, 16, v96
	v_and_b32_e32 v96, 0xffff0000, v96
	v_sub_f32_e32 v96, v96, v54
	v_mul_f32_e32 v119, v96, v103
	v_lshlrev_b32_e32 v96, 16, v97
	v_sub_f32_e32 v96, v96, v54
	v_mul_f32_e32 v121, v96, v103
	v_and_b32_e32 v96, 0xffff0000, v97
	v_sub_f32_e32 v96, v96, v54
	v_mul_f32_e32 v123, v96, v103
	v_mov_b32_e32 v96, v47
	v_mov_b32_e32 v97, v63
	v_pk_mul_f32 v[96:97], v[96:97], v[122:123]
	v_exp_f32_e32 v116, v116
	v_mul_f32_e32 v47, v96, v97
	v_lshlrev_b32_e32 v96, 16, v98
	v_sub_f32_e32 v96, v96, v54
	v_mul_f32_e32 v125, v96, v103
	v_mov_b32_e32 v96, v40
	v_and_b32_e32 v40, 0xffff0000, v98
	v_sub_f32_e32 v40, v40, v54
	v_mov_b32_e32 v97, v68
	v_mul_f32_e32 v127, v40, v103
	v_mov_b32_e32 v40, v41
	v_mov_b32_e32 v41, v69
	v_pk_mul_f32 v[96:97], v[96:97], v[124:125]
	v_pk_mul_f32 v[40:41], v[40:41], v[126:127]
	v_add_f32_e32 v116, 1.0, v116
	v_mul_f32_e32 v96, v96, v97
	v_mul_f32_e32 v97, v40, v41
	v_lshlrev_b32_e32 v40, 16, v99
	v_rcp_f32_e32 v116, v116
	v_sub_f32_e32 v40, v40, v54
	v_mul_f32_e32 v129, v40, v103
	v_mov_b32_e32 v40, v42
	v_mov_b32_e32 v41, v70
	v_sub_f32_e32 v117, v117, v54
	v_pk_mul_f32 v[40:41], v[40:41], v[128:129]
	v_mul_f32_e32 v117, v117, v103
	v_mov_b32_e32 v132, v44
	v_mov_b32_e32 v133, v60
	v_mul_f32_e32 v98, v40, v41
	v_mul_f32_e32 v41, 0xbfb8aa3b, v36
	v_pk_mul_f32 v[116:117], v[132:133], v[116:117]
	v_and_b32_e32 v40, 0xffff0000, v99
	v_exp_f32_e32 v42, v41
	v_mul_f32_e32 v44, v116, v117
	v_mov_b32_e32 v116, v45
	v_mov_b32_e32 v117, v61
	v_sub_f32_e32 v40, v40, v54
	v_pk_mul_f32 v[116:117], v[116:117], v[118:119]
	v_mul_f32_e32 v131, v40, v103
	v_mov_b32_e32 v40, v43
	v_mov_b32_e32 v41, v71
	v_mul_f32_e32 v45, v116, v117
	v_mov_b32_e32 v116, v46
	v_mov_b32_e32 v117, v62
	v_pk_mul_f32 v[40:41], v[40:41], v[130:131]
	v_pk_mul_f32 v[116:117], v[116:117], v[120:121]
	v_mul_f32_e32 v99, v40, v41
	v_add_f32_e32 v40, 1.0, v42
	v_mul_f32_e32 v41, 0xbfb8aa3b, v37
	v_mul_f32_e32 v46, v116, v117
	v_exp_f32_e32 v117, v41
	v_rcp_f32_e32 v116, v40
	global_load_dwordx4 v[40:43], v[114:115], off
	s_nop 0
	global_load_dwordx2 v[112:113], v[112:113], off
	v_mul_f32_e32 v115, 0xbfb8aa3b, v38
	v_add_f32_e32 v114, 1.0, v117
	v_exp_f32_e32 v115, v115
	v_mul_f32_e32 v117, 0xbfb8aa3b, v39
	v_exp_f32_e32 v117, v117
	v_mul_f32_e32 v119, 0xbfb8aa3b, v33
	v_add_f32_e32 v115, 1.0, v115
	v_rcp_f32_e32 v118, v115
	v_add_f32_e32 v115, 1.0, v117
	v_mul_f32_e32 v117, 0xbfb8aa3b, v32
	v_exp_f32_e32 v117, v117
	v_exp_f32_e32 v119, v119
	v_rcp_f32_e32 v120, v115
	v_rcp_f32_e32 v114, v114
	v_add_f32_e32 v115, 1.0, v117
	v_mul_f32_e32 v117, 0xbfb8aa3b, v34
	v_rcp_f32_e32 v122, v115
	v_add_f32_e32 v115, 1.0, v119
	v_exp_f32_e32 v117, v117
	v_mul_f32_e32 v119, 0xbfb8aa3b, v35
	v_exp_f32_e32 v119, v119
	v_rcp_f32_e32 v124, v115
	v_add_f32_e32 v115, 1.0, v117
	v_rcp_f32_e32 v126, v115
	v_add_f32_e32 v115, 1.0, v119
	v_rcp_f32_e32 v128, v115
	v_lshlrev_b32_e32 v115, 16, v92
	v_mov_b32_e32 v130, v36
	v_and_b32_e32 v36, 0xffff0000, v92
	v_sub_f32_e32 v115, v115, v54
	v_sub_f32_e32 v36, v36, v54
	v_mul_f32_e32 v117, v115, v103
	v_mul_f32_e32 v115, v36, v103
	v_mov_b32_e32 v36, v37
	v_mov_b32_e32 v37, v57
	v_mov_b32_e32 v131, v56
	v_pk_mul_f32 v[36:37], v[36:37], v[114:115]
	v_pk_mul_f32 v[116:117], v[130:131], v[116:117]
	v_mul_f32_e32 v131, v36, v37
	v_lshlrev_b32_e32 v36, 16, v93
	v_sub_f32_e32 v36, v36, v54
	v_mul_f32_e32 v119, v36, v103
	v_mov_b32_e32 v36, v38
	v_mov_b32_e32 v37, v58
	v_pk_mul_f32 v[36:37], v[36:37], v[118:119]
	v_mul_f32_e32 v38, 0xbfb8aa3b, v30
	v_mul_f32_e32 v132, v36, v37
	v_and_b32_e32 v36, 0xffff0000, v93
	v_sub_f32_e32 v36, v36, v54
	v_mul_f32_e32 v121, v36, v103
	v_mov_b32_e32 v36, v39
	v_mov_b32_e32 v37, v59
	v_pk_mul_f32 v[36:37], v[36:37], v[120:121]
	v_exp_f32_e32 v39, v38
	v_mul_f32_e32 v120, v36, v37
	v_lshlrev_b32_e32 v36, 16, v94
	v_sub_f32_e32 v36, v36, v54
	v_mul_f32_e32 v123, v36, v103
	v_mov_b32_e32 v36, v32
	v_and_b32_e32 v32, 0xffff0000, v94
	v_sub_f32_e32 v32, v32, v54
	v_mul_f32_e32 v125, v32, v103
	v_mov_b32_e32 v32, v33
	v_mov_b32_e32 v33, v49
	v_mov_b32_e32 v37, v48
	v_pk_mul_f32 v[32:33], v[32:33], v[124:125]
	v_pk_mul_f32 v[36:37], v[36:37], v[122:123]
	v_mul_f32_e32 v122, v32, v33
	v_lshlrev_b32_e32 v32, 16, v95
	v_sub_f32_e32 v32, v32, v54
	v_mul_f32_e32 v127, v32, v103
	v_mov_b32_e32 v32, v34
	v_mov_b32_e32 v33, v50
	v_pk_mul_f32 v[32:33], v[32:33], v[126:127]
	v_mul_f32_e32 v121, v36, v37
	v_mul_f32_e32 v123, v32, v33
	v_and_b32_e32 v32, 0xffff0000, v95
	v_sub_f32_e32 v32, v32, v54
	v_mul_f32_e32 v37, 0xbfb8aa3b, v29
	v_mul_f32_e32 v129, v32, v103
	v_mov_b32_e32 v32, v35
	s_waitcnt vmcnt(0)
; DI float bflo(unsigned w) { return __uint_as_float(w << 16); }
; DI float bfhi(unsigned w) { return __uint_as_float(w & 0xffff0000u); }
; DI void store8(bf16_t* p, f32x4 a, f32x4 b) { u32x4 w = {cvt_pk_bf16(a[0], a[1]), cvt_pk_bf16(a[2], a[3]), cvt_pk_bf16(b[0], b[1]), cvt_pk_bf16(b[2], b[3])}; *(u32x4*)p = w; }
; DI f32x4 silu4(f32x4 v) { f32x4 r; r[0] = silu_f(v[0]); r[1] = silu_f(v[1]); r[2] = silu_f(v[2]); r[3] = silu_f(v[3]); return r; }
;     DI void operator()(const AccT& acc, const pg8::Unit& u, int wr, int wc, int fr, int fq) const {
;     ...
;             for (int m = 0; m < 4; ++m) { const size_t row = (size_t)u.pm * 256 + wr * 64 + fr + ai * 128 + m * 16;
;                 st[m] = *(const float2*)(stats + (row * 4 + head) * 2);
; #pragma unroll
;                 for (int bj = 0; bj < 2; ++bj) ov[m][bj] = *(const u32x4*)(o + row * 2048 + col0 + bj * 128); }
; #pragma unroll
;             for (int m = 0; m < 4; ++m) { const size_t row = (size_t)u.pm * 256 + wr * 64 + fr + ai * 128 + m * 16;
;                 const float mean = st[m].x * (1.f / 512.f), var = fmaxf(st[m].y * (1.f / 512.f) - mean * mean, 0.f), rstd = rsqrtf(var + 1e-5f);
; #pragma unroll
;                 for (int bj = 0; bj < 2; ++bj) { bf16_t* op = o + row * 2048 + col0 + bj * 128; const u32x4 w = ov[m][bj];
;                     const f32x4 s0 = silu4(acc[ai][bj][m][0]), s1 = silu4(acc[ai][bj][m][1]);
;                     f32x4 y0, y1;
;                     y0[0] = (bflo(w[0]) - mean) * rstd * g0[bj][0] * s0[0]; y0[1] = (bfhi(w[0]) - mean) * rstd * g0[bj][1] * s0[1];
;                     y0[2] = (bflo(w[1]) - mean) * rstd * g0[bj][2] * s0[2]; y0[3] = (bfhi(w[1]) - mean) * rstd * g0[bj][3] * s0[3];
;                     y1[0] = (bflo(w[2]) - mean) * rstd * g1[bj][0] * s1[0]; y1[1] = (bfhi(w[2]) - mean) * rstd * g1[bj][1] * s1[1];
;                     y1[2] = (bflo(w[3]) - mean) * rstd * g1[bj][2] * s1[2]; y1[3] = (bfhi(w[3]) - mean) * rstd * g1[bj][3] * s1[3];
;                     store8(op, y0, y1); } } }
	v_pk_mul_f32 v[34:35], v[112:113], s[54:55] op_sel_hi:[1,0]
	v_exp_f32_e32 v37, v37
	v_fma_f32 v33, -v34, v34, v35
	v_mul_f32_e32 v38, 0xbfb8aa3b, v31
	v_max_f32_e32 v33, 0, v33
	v_exp_f32_e32 v93, v38
	v_add_f32_e32 v33, 0x3727c5ac, v33
	v_mul_f32_e32 v35, 0x4b800000, v33
	v_cmp_gt_f32_e32 vcc, s94, v33
	v_add_f32_e32 v37, 1.0, v37
	v_rcp_f32_e32 v38, v37
	v_cndmask_b32_e32 v33, v33, v35, vcc
	v_add_f32_e32 v37, 1.0, v39
	v_mul_f32_e32 v39, 0xbfb8aa3b, v24
	v_rsq_f32_e32 v35, v33
	v_rcp_f32_e32 v92, v37
	v_add_f32_e32 v37, 1.0, v93
	v_exp_f32_e32 v39, v39
	v_mul_f32_e32 v93, 0xbfb8aa3b, v25
	v_exp_f32_e32 v93, v93
	v_mov_b32_e32 v33, v51
	v_pk_mul_f32 v[32:33], v[32:33], v[128:129]
	v_mul_f32_e32 v36, 0xbfb8aa3b, v28
	v_mul_f32_e32 v54, v32, v33
	v_mul_f32_e32 v32, 0x45800000, v35
	v_rcp_f32_e32 v94, v37
	v_add_f32_e32 v37, 1.0, v39
	v_mul_f32_e32 v39, 0xbfb8aa3b, v26
	v_cndmask_b32_e32 v35, v35, v32, vcc
	v_lshl_add_u64 v[32:33], s[96:97], 0, v[110:111]
	v_exp_f32_e32 v36, v36
	v_rcp_f32_e32 v110, v37
	v_add_f32_e32 v37, 1.0, v93
	v_exp_f32_e32 v39, v39
	v_mul_f32_e32 v93, 0xbfb8aa3b, v27
	v_exp_f32_e32 v93, v93
	v_add_f32_e32 v36, 1.0, v36
	v_rcp_f32_e32 v112, v37
	v_add_f32_e32 v37, 1.0, v39
	v_rcp_f32_e32 v36, v36
	v_rcp_f32_e32 v114, v37
	v_add_f32_e32 v37, 1.0, v93
	v_mov_b32_e32 v118, v28
	v_and_b32_e32 v28, 0xffff0000, v40
	v_mul_f32_e32 v130, v116, v117
	v_rcp_f32_e32 v116, v37
	v_lshlrev_b32_e32 v37, 16, v40
	v_sub_f32_e32 v28, v28, v34
	v_sub_f32_e32 v37, v37, v34
	v_mul_f32_e32 v39, v28, v35
	v_mov_b32_e32 v28, v29
	v_mov_b32_e32 v29, v61
	v_mul_f32_e32 v37, v37, v35
	v_mov_b32_e32 v119, v60
	v_pk_mul_f32 v[28:29], v[28:29], v[38:39]
	v_pk_mul_f32 v[36:37], v[118:119], v[36:37]
	v_mul_f32_e32 v118, v28, v29
	v_lshlrev_b32_e32 v28, 16, v41
	v_sub_f32_e32 v28, v28, v34
	v_mul_f32_e32 v93, v28, v35
	v_mov_b32_e32 v28, v30
	v_mov_b32_e32 v29, v62
	v_pk_mul_f32 v[28:29], v[28:29], v[92:93]
	global_load_dwordx2 v[92:93], v[108:109], off
	v_mul_f32_e32 v119, v28, v29
	v_and_b32_e32 v28, 0xffff0000, v41
	v_sub_f32_e32 v28, v28, v34
	v_mul_f32_e32 v95, v28, v35
	v_mov_b32_e32 v28, v31
	v_mov_b32_e32 v29, v63
	v_pk_mul_f32 v[28:29], v[28:29], v[94:95]
	v_mul_f32_e32 v103, v36, v37
	v_mul_f32_e32 v124, v28, v29
	v_lshlrev_b32_e32 v28, 16, v42
	v_sub_f32_e32 v28, v28, v34
	v_mul_f32_e32 v111, v28, v35
	v_mov_b32_e32 v28, v24
	v_and_b32_e32 v24, 0xffff0000, v42
	v_sub_f32_e32 v24, v24, v34
	v_mul_f32_e32 v113, v24, v35
	v_mov_b32_e32 v24, v25
	v_mov_b32_e32 v25, v69
	v_mov_b32_e32 v29, v68
	v_pk_mul_f32 v[24:25], v[24:25], v[112:113]
	v_pk_mul_f32 v[28:29], v[28:29], v[110:111]
	v_mul_f32_e32 v111, v24, v25
	v_lshlrev_b32_e32 v24, 16, v43
	v_sub_f32_e32 v24, v24, v34
	v_mul_f32_e32 v115, v24, v35
	v_mov_b32_e32 v24, v26
	v_mov_b32_e32 v25, v70
	v_pk_mul_f32 v[24:25], v[24:25], v[114:115]
	v_mul_f32_e32 v26, 0xbfb8aa3b, v20
	v_mul_f32_e32 v112, v24, v25
	v_and_b32_e32 v24, 0xffff0000, v43
	v_sub_f32_e32 v24, v24, v34
	v_mul_f32_e32 v117, v24, v35
	v_mov_b32_e32 v24, v27
	v_exp_f32_e32 v26, v26
	v_mul_f32_e32 v27, 0xbfb8aa3b, v21
	v_exp_f32_e32 v27, v27
	v_mov_b32_e32 v25, v71
	v_pk_mul_f32 v[24:25], v[24:25], v[116:117]
	v_mul_f32_e32 v110, v28, v29
	v_mul_f32_e32 v113, v24, v25
	v_add_f32_e32 v24, 1.0, v26
	v_mul_f32_e32 v26, 0xbfb8aa3b, v22
	v_add_f32_e32 v25, 1.0, v27
	v_exp_f32_e32 v27, v26
	v_mul_f32_e32 v26, 0xbfb8aa3b, v23
	v_exp_f32_e32 v29, v26
	v_rcp_f32_e32 v26, v25
	v_add_f32_e32 v25, 1.0, v27
	v_mul_f32_e32 v27, 0xbfb8aa3b, v16
	v_rcp_f32_e32 v28, v25
	v_add_f32_e32 v25, 1.0, v29
	v_exp_f32_e32 v27, v27
	v_mul_f32_e32 v29, 0xbfb8aa3b, v17
	v_exp_f32_e32 v29, v29
	v_rcp_f32_e32 v30, v25
	v_add_f32_e32 v25, 1.0, v27
	v_mul_f32_e32 v27, 0xbfb8aa3b, v18
	v_rcp_f32_e32 v36, v25
	v_add_f32_e32 v25, 1.0, v29
	v_exp_f32_e32 v27, v27
	v_mul_f32_e32 v29, 0xbfb8aa3b, v19
	v_exp_f32_e32 v29, v29
	v_rcp_f32_e32 v38, v25
	v_add_f32_e32 v25, 1.0, v27
	v_rcp_f32_e32 v24, v24
	v_rcp_f32_e32 v40, v25
	v_add_f32_e32 v25, 1.0, v29
	v_rcp_f32_e32 v42, v25
	v_lshlrev_b32_e32 v25, 16, v88
	v_mov_b32_e32 v94, v20
	v_and_b32_e32 v20, 0xffff0000, v88
	v_sub_f32_e32 v25, v25, v34
	v_sub_f32_e32 v20, v20, v34
	v_mul_f32_e32 v25, v25, v35
	v_mov_b32_e32 v95, v56
	v_mul_f32_e32 v27, v20, v35
	v_mov_b32_e32 v20, v21
	v_mov_b32_e32 v21, v57
	v_pk_mul_f32 v[24:25], v[94:95], v[24:25]
	v_pk_mul_f32 v[20:21], v[20:21], v[26:27]
	v_mul_f32_e32 v24, v24, v25
	v_mul_f32_e32 v25, v20, v21
	v_lshlrev_b32_e32 v20, 16, v89
	v_sub_f32_e32 v20, v20, v34
	v_mul_f32_e32 v29, v20, v35
	v_mov_b32_e32 v20, v22
	v_mov_b32_e32 v21, v58
	v_pk_mul_f32 v[20:21], v[20:21], v[28:29]
	v_lshl_add_u64 v[52:53], v[52:53], 0, v[184:185]
	v_mul_f32_e32 v22, v20, v21
	v_and_b32_e32 v20, 0xffff0000, v89
	v_sub_f32_e32 v20, v20, v34
	v_mul_f32_e32 v31, v20, v35
	v_mov_b32_e32 v20, v23
	v_mov_b32_e32 v21, v59
	v_pk_mul_f32 v[20:21], v[20:21], v[30:31]
	v_lshl_add_u64 v[32:33], v[32:33], 0, v[184:185]
	v_mul_f32_e32 v23, v20, v21
	v_lshlrev_b32_e32 v20, 16, v90
	v_sub_f32_e32 v20, v20, v34
	v_mul_f32_e32 v37, v20, v35
	v_mov_b32_e32 v20, v16
	v_and_b32_e32 v16, 0xffff0000, v90
	v_sub_f32_e32 v16, v16, v34
	v_mov_b32_e32 v21, v48
	v_mul_f32_e32 v39, v16, v35
	v_mov_b32_e32 v16, v17
	v_mov_b32_e32 v17, v49
	v_pk_mul_f32 v[20:21], v[20:21], v[36:37]
	v_pk_mul_f32 v[16:17], v[16:17], v[38:39]
	v_mul_f32_e32 v20, v20, v21
	v_mul_f32_e32 v21, v16, v17
	v_lshlrev_b32_e32 v16, 16, v91
	v_sub_f32_e32 v16, v16, v34
	v_mul_f32_e32 v41, v16, v35
	v_mov_b32_e32 v16, v18
	v_mov_b32_e32 v17, v50
	v_pk_mul_f32 v[16:17], v[16:17], v[40:41]
	v_mov_b32_e32 v36, v12
	v_mul_f32_e32 v26, v16, v17
	v_and_b32_e32 v16, 0xffff0000, v91
	v_sub_f32_e32 v16, v16, v34
	v_mul_f32_e32 v43, v16, v35
	v_mov_b32_e32 v16, v19
	v_mov_b32_e32 v17, v51
	v_pk_mul_f32 v[16:17], v[16:17], v[42:43]
	v_mov_b32_e32 v37, v60
	v_mul_f32_e32 v27, v16, v17
	v_cvt_pk_bf16_f32 v16, v76, v77
	v_cvt_pk_bf16_f32 v17, v78, v79
	v_cvt_pk_bf16_f32 v18, v72, v73
	v_cvt_pk_bf16_f32 v19, v74, v75
	global_store_dwordx4 v[106:107], v[16:19], off
	v_mov_b32_e32 v60, v13
	s_nop 0
	v_cvt_pk_bf16_f32 v16, v64, v65
	v_cvt_pk_bf16_f32 v17, v66, v67
	v_cvt_pk_bf16_f32 v18, v100, v101
	v_cvt_pk_bf16_f32 v19, v102, v55
	global_store_dwordx4 v[106:107], v[16:19], off offset:256
	s_nop 1
	v_cvt_pk_bf16_f32 v16, v44, v45
	v_cvt_pk_bf16_f32 v17, v46, v47
	v_cvt_pk_bf16_f32 v18, v96, v97
	v_cvt_pk_bf16_f32 v19, v98, v99
	global_store_dwordx4 v[52:53], v[16:19], off
	s_nop 1
	v_cvt_pk_bf16_f32 v16, v130, v131
	v_cvt_pk_bf16_f32 v17, v132, v120
	v_cvt_pk_bf16_f32 v18, v121, v122
	v_cvt_pk_bf16_f32 v19, v123, v54
	global_store_dwordx4 v[52:53], v[16:19], off offset:256
	s_nop 1
	v_cvt_pk_bf16_f32 v16, v103, v118
	v_cvt_pk_bf16_f32 v17, v119, v124
	v_cvt_pk_bf16_f32 v18, v110, v111
	v_cvt_pk_bf16_f32 v19, v112, v113
	global_store_dwordx4 v[32:33], v[16:19], off
	s_waitcnt vmcnt(0)
; DI float bflo(unsigned w) { return __uint_as_float(w << 16); }
; DI float bfhi(unsigned w) { return __uint_as_float(w & 0xffff0000u); }
; #define PG8_WAIT_V(n) asm volatile("s_waitcnt vmcnt(" #n ")" ::: "memory")
; #define PG8_BAR __builtin_amdgcn_s_barrier()
; DI void store8(bf16_t* p, f32x4 a, f32x4 b) { u32x4 w = {cvt_pk_bf16(a[0], a[1]), cvt_pk_bf16(a[2], a[3]), cvt_pk_bf16(b[0], b[1]), cvt_pk_bf16(b[2], b[3])}; *(u32x4*)p = w; }
; template <class Epi, class Sched>
; __device__ __forceinline__ void gemm_phase(PG8_LAS unsigned char* lds, const Gemm g, const Sched& S, const Epi& E) {
;     ...
;         E(acc, cur, wr, wc, fr, fq); S.done(cur);
;         if (!has_next) break;
; #pragma unroll
;         for (int a = 0; a < 2; ++a)
; #pragma unroll
;             for (int b = 0; b < 2; ++b)
; #pragma unroll
;                 for (int m = 0; m < 4; ++m)
; #pragma unroll
;                     for (int n = 0; n < 2; ++n) acc[a][b][m][n] = (f32x4){0.f, 0.f, 0.f, 0.f};
;         cur = nxt; cA = nA; cB = nB; ++ui;
;     }
;     PG8_WAIT_V(0);
;     if (wr == 0) PG8_BAR;
;     PG8_BAR;
;     DI void operator()(const AccT& acc, const pg8::Unit& u, int wr, int wc, int fr, int fq) const {
;     ...
;             for (int m = 0; m < 4; ++m) { const size_t row = (size_t)u.pm * 256 + wr * 64 + fr + ai * 128 + m * 16;
;                 const float mean = st[m].x * (1.f / 512.f), var = fmaxf(st[m].y * (1.f / 512.f) - mean * mean, 0.f), rstd = rsqrtf(var + 1e-5f);
; #pragma unroll
;                 for (int bj = 0; bj < 2; ++bj) { bf16_t* op = o + row * 2048 + col0 + bj * 128; const u32x4 w = ov[m][bj];
;                     const f32x4 s0 = silu4(acc[ai][bj][m][0]), s1 = silu4(acc[ai][bj][m][1]);
;                     f32x4 y0, y1;
;                     y0[0] = (bflo(w[0]) - mean) * rstd * g0[bj][0] * s0[0]; y0[1] = (bfhi(w[0]) - mean) * rstd * g0[bj][1] * s0[1];
;                     y0[2] = (bflo(w[1]) - mean) * rstd * g0[bj][2] * s0[2]; y0[3] = (bfhi(w[1]) - mean) * rstd * g0[bj][3] * s0[3];
;                     y1[0] = (bflo(w[2]) - mean) * rstd * g1[bj][0] * s1[0]; y1[1] = (bfhi(w[2]) - mean) * rstd * g1[bj][1] * s1[1];
;                     y1[2] = (bflo(w[3]) - mean) * rstd * g1[bj][2] * s1[2]; y1[3] = (bfhi(w[3]) - mean) * rstd * g1[bj][3] * s1[3];
;                     store8(op, y0, y1); } } }
	s_nop 0
	v_pk_mul_f32 v[16:17], v[92:93], s[54:55] op_sel_hi:[1,0]
	v_cvt_pk_bf16_f32 v18, v24, v25
	v_cvt_pk_bf16_f32 v19, v22, v23
	v_cvt_pk_bf16_f32 v20, v20, v21
	v_cvt_pk_bf16_f32 v21, v26, v27
	global_store_dwordx4 v[32:33], v[18:21], off offset:256
	v_fma_f32 v17, -v16, v16, v17
	v_max_f32_e32 v17, 0, v17
	v_add_f32_e32 v17, 0x3727c5ac, v17
	v_mul_f32_e32 v22, 0x4b800000, v17
	v_cmp_gt_f32_e32 vcc, s94, v17
	v_mul_f32_e32 v21, 0xbfb8aa3b, v13
	v_exp_f32_e32 v21, v21
	v_cndmask_b32_e32 v17, v17, v22, vcc
	v_mul_f32_e32 v22, 0xbfb8aa3b, v14
	v_exp_f32_e32 v23, v22
	v_mul_f32_e32 v22, 0xbfb8aa3b, v15
	v_exp_f32_e32 v25, v22
	v_add_f32_e32 v21, 1.0, v21
	v_rcp_f32_e32 v22, v21
	v_add_f32_e32 v21, 1.0, v23
	v_mul_f32_e32 v23, 0xbfb8aa3b, v8
	v_rcp_f32_e32 v24, v21
	v_add_f32_e32 v21, 1.0, v25
	v_exp_f32_e32 v23, v23
	v_mul_f32_e32 v25, 0xbfb8aa3b, v9
	v_exp_f32_e32 v25, v25
	v_mul_f32_e32 v20, 0xbfb8aa3b, v12
	v_rcp_f32_e32 v26, v21
	v_add_f32_e32 v21, 1.0, v23
	v_mul_f32_e32 v23, 0xbfb8aa3b, v10
	v_exp_f32_e32 v20, v20
	v_rcp_f32_e32 v28, v21
	v_add_f32_e32 v21, 1.0, v25
	v_exp_f32_e32 v23, v23
	v_mul_f32_e32 v25, 0xbfb8aa3b, v11
	v_exp_f32_e32 v25, v25
	v_rsq_f32_e32 v17, v17
	v_add_f32_e32 v20, 1.0, v20
	v_rcp_f32_e32 v30, v21
	v_add_f32_e32 v21, 1.0, v23
	v_rcp_f32_e32 v20, v20
	v_rcp_f32_e32 v32, v21
	v_add_f32_e32 v21, 1.0, v25
	v_mul_f32_e32 v18, 0x45800000, v17
	v_rcp_f32_e32 v34, v21
	v_lshlrev_b32_e32 v21, 16, v84
	v_and_b32_e32 v12, 0xffff0000, v84
	v_cndmask_b32_e32 v17, v17, v18, vcc
	v_sub_f32_e32 v21, v21, v16
	v_sub_f32_e32 v12, v12, v16
	v_mul_f32_e32 v21, v21, v17
	v_mul_f32_e32 v23, v12, v17
	v_pk_mul_f32 v[20:21], v[36:37], v[20:21]
	v_pk_mul_f32 v[12:13], v[60:61], v[22:23]
	v_mul_f32_e32 v20, v20, v21
	v_mul_f32_e32 v21, v12, v13
	v_lshlrev_b32_e32 v12, 16, v85
	v_sub_f32_e32 v12, v12, v16
	v_mul_f32_e32 v25, v12, v17
	v_mov_b32_e32 v12, v14
	v_mov_b32_e32 v13, v62
	v_pk_mul_f32 v[12:13], v[12:13], v[24:25]
	v_mov_b32_e32 v62, v15
	v_mul_f32_e32 v14, v12, v13
	v_and_b32_e32 v12, 0xffff0000, v85
	v_sub_f32_e32 v12, v12, v16
	v_mul_f32_e32 v27, v12, v17
	v_pk_mul_f32 v[12:13], v[62:63], v[26:27]
	v_lshl_add_u64 v[18:19], s[96:97], 0, v[104:105]
	v_mul_f32_e32 v15, v12, v13
	v_lshlrev_b32_e32 v12, 16, v86
	v_sub_f32_e32 v12, v12, v16
	v_mul_f32_e32 v29, v12, v17
	v_mov_b32_e32 v12, v8
	v_and_b32_e32 v8, 0xffff0000, v86
	v_sub_f32_e32 v8, v8, v16
	v_mov_b32_e32 v13, v68
	v_mul_f32_e32 v31, v8, v17
	v_mov_b32_e32 v68, v9
	v_pk_mul_f32 v[12:13], v[12:13], v[28:29]
	v_pk_mul_f32 v[8:9], v[68:69], v[30:31]
	v_mul_f32_e32 v12, v12, v13
	v_mul_f32_e32 v13, v8, v9
	v_lshlrev_b32_e32 v8, 16, v87
	v_sub_f32_e32 v8, v8, v16
	v_mul_f32_e32 v33, v8, v17
	v_mov_b32_e32 v8, v10
	v_mov_b32_e32 v9, v70
	v_pk_mul_f32 v[8:9], v[8:9], v[32:33]
	v_mov_b32_e32 v70, v11
	v_mul_f32_e32 v22, v8, v9
	v_and_b32_e32 v8, 0xffff0000, v87
	v_sub_f32_e32 v8, v8, v16
	v_mul_f32_e32 v35, v8, v17
	v_pk_mul_f32 v[8:9], v[70:71], v[34:35]
	v_lshl_add_u64 v[18:19], v[18:19], 0, v[184:185]
	v_mul_f32_e32 v11, v8, v9
	v_cvt_pk_bf16_f32 v8, v20, v21
	v_cvt_pk_bf16_f32 v9, v14, v15
	v_cvt_pk_bf16_f32 v10, v12, v13
	v_mul_f32_e32 v13, 0xbfb8aa3b, v5
	v_exp_f32_e32 v13, v13
	v_cvt_pk_bf16_f32 v11, v22, v11
	global_store_dwordx4 v[18:19], v[8:11], off
	v_mul_f32_e32 v12, 0xbfb8aa3b, v4
	v_exp_f32_e32 v12, v12
	v_mul_f32_e32 v10, 0xbfb8aa3b, v6
	v_exp_f32_e32 v11, v10
	v_mul_f32_e32 v10, 0xbfb8aa3b, v7
	v_add_f32_e32 v9, 1.0, v13
	v_exp_f32_e32 v13, v10
	v_rcp_f32_e32 v10, v9
	v_add_f32_e32 v9, 1.0, v11
	v_mul_f32_e32 v11, 0xbfb8aa3b, v0
	v_add_f32_e32 v8, 1.0, v12
	v_rcp_f32_e32 v12, v9
	v_add_f32_e32 v9, 1.0, v13
	v_exp_f32_e32 v11, v11
	v_mul_f32_e32 v13, 0xbfb8aa3b, v1
	v_exp_f32_e32 v13, v13
	v_rcp_f32_e32 v14, v9
	v_add_f32_e32 v9, 1.0, v11
	v_mul_f32_e32 v11, 0xbfb8aa3b, v2
	v_rcp_f32_e32 v20, v9
	v_add_f32_e32 v9, 1.0, v13
	v_exp_f32_e32 v11, v11
	v_mul_f32_e32 v13, 0xbfb8aa3b, v3
	v_exp_f32_e32 v13, v13
	v_rcp_f32_e32 v22, v9
	v_add_f32_e32 v9, 1.0, v11
	v_rcp_f32_e32 v8, v8
	v_rcp_f32_e32 v24, v9
	v_add_f32_e32 v9, 1.0, v13
	v_rcp_f32_e32 v26, v9
	v_lshlrev_b32_e32 v9, 16, v80
	v_mov_b32_e32 v28, v4
	v_and_b32_e32 v4, 0xffff0000, v80
	v_sub_f32_e32 v9, v9, v16
	v_sub_f32_e32 v4, v4, v16
	v_mul_f32_e32 v9, v9, v17
	v_mov_b32_e32 v29, v56
	v_mul_f32_e32 v11, v4, v17
	v_mov_b32_e32 v56, v5
	v_pk_mul_f32 v[8:9], v[28:29], v[8:9]
	v_pk_mul_f32 v[4:5], v[56:57], v[10:11]
	v_mul_f32_e32 v8, v8, v9
	v_mul_f32_e32 v9, v4, v5
	v_lshlrev_b32_e32 v4, 16, v81
	v_sub_f32_e32 v4, v4, v16
	v_mul_f32_e32 v13, v4, v17
	v_mov_b32_e32 v4, v6
	v_mov_b32_e32 v5, v58
	v_pk_mul_f32 v[4:5], v[4:5], v[12:13]
	v_mov_b32_e32 v58, v7
	v_mul_f32_e32 v6, v4, v5
	v_and_b32_e32 v4, 0xffff0000, v81
	v_sub_f32_e32 v4, v4, v16
	v_mul_f32_e32 v15, v4, v17
	v_pk_mul_f32 v[4:5], v[58:59], v[14:15]
	s_and_b64 vcc, exec, s[4:5]
	v_mul_f32_e32 v7, v4, v5
	v_lshlrev_b32_e32 v4, 16, v82
	v_sub_f32_e32 v4, v4, v16
	v_mul_f32_e32 v21, v4, v17
	v_mov_b32_e32 v4, v0
	v_and_b32_e32 v0, 0xffff0000, v82
	v_sub_f32_e32 v0, v0, v16
	v_mov_b32_e32 v5, v48
	v_mul_f32_e32 v23, v0, v17
	v_mov_b32_e32 v48, v1
	v_pk_mul_f32 v[4:5], v[4:5], v[20:21]
	v_pk_mul_f32 v[0:1], v[48:49], v[22:23]
	v_mul_f32_e32 v4, v4, v5
	v_mul_f32_e32 v5, v0, v1
	v_lshlrev_b32_e32 v0, 16, v83
	v_sub_f32_e32 v0, v0, v16
	v_mul_f32_e32 v25, v0, v17
	v_mov_b32_e32 v0, v2
	v_mov_b32_e32 v1, v50
	v_pk_mul_f32 v[0:1], v[0:1], v[24:25]
	v_mov_b32_e32 v50, v3
	v_mul_f32_e32 v10, v0, v1
	v_and_b32_e32 v0, 0xffff0000, v83
	v_sub_f32_e32 v0, v0, v16
	v_mul_f32_e32 v27, v0, v17
	v_pk_mul_f32 v[0:1], v[50:51], v[26:27]
	s_nop 0
	v_mul_f32_e32 v3, v0, v1
	v_cvt_pk_bf16_f32 v0, v8, v9
	v_cvt_pk_bf16_f32 v1, v6, v7
	v_cvt_pk_bf16_f32 v2, v4, v5
	v_cvt_pk_bf16_f32 v3, v10, v3
	global_store_dwordx4 v[18:19], v[0:3], off offset:256
	s_cbranch_vccz .LBB0_513
	s_waitcnt vmcnt(0)
	v_readlane_b32 s54, v255, 42
	v_readlane_b32 s52, v255, 44
	v_readlane_b32 s64, v255, 53
	v_readlane_b32 s66, v255, 55
	s_cmpk_gt_u32 s47, 0xff
	v_readlane_b32 s55, v255, 43
	v_readlane_b32 s53, v255, 45
	v_readlane_b32 s56, v255, 46
	v_readlane_b32 s57, v255, 47
	v_readlane_b32 s58, v255, 48
	v_readlane_b32 s59, v255, 49
	v_readlane_b32 s65, v255, 54
	v_readlane_b32 s67, v255, 56
	v_readlane_b32 s63, v255, 57
	s_cbranch_scc1 .LBB0_520
	s_barrier

; #define PG8_STAGE(bufoff, gbase, voff) do { _Pragma("unroll") for (int _i = 0; _i < 2; ++_i) \
;         __builtin_amdgcn_global_load_lds((const unsigned*)((const char*)(gbase) + (voff)[_i]), (PG8_LAS unsigned*)(lds + (bufoff) + ldsw + _i * 8192), 16, 0, 0); } while (0)
; #define PG8_LDA(dst, b, h) do { _Pragma("unroll") for (int m = 0; m < 4; ++m) _Pragma("unroll") for (int k = 0; k < 2; ++k) dst[m][k] = *(const PG8_LAS bf16x8*)(lds + PG8_SA(b, h) + aoff + m * 2048 + k * 1024); } while (0)
; #define PG8_WAIT_V(n) asm volatile("s_waitcnt vmcnt(" #n ")" ::: "memory")
; template <class Epi, class Sched>
; __device__ __forceinline__ void gemm_phase(PG8_LAS unsigned char* lds, const Gemm g, const Sched& S, const Epi& E) {
;     ...
;         for (int t = 0; t < nt; t += 2) {
;             const bool last = (t == nt - 2);
;             const char* a1 = cA + (size_t)(t + 1) * kstep;
;             const char* a2 = last ? nA : cA + (size_t)(t + 2) * kstep; const char* b2 = last ? nB : cB + (size_t)(t + 2) * kstep;
;             const char* a3 = a2 + kstep; const char* b3 = b2 + kstep;
;             if (last && has_next) S.a_ready(nxt);
;             PG8_LDB(B0, 0, 0); PG8_SCHED; PG8_LDA(At, 0, 0); PG8_STAGE(PG8_SA(1, 1), a1 + hstep, voffA);
;             PG8_WAIT_L(8); PG8_BAR; PG8_WAIT_L(0); PG8_MMA(0, 0, At, B0); PG8_BAR; PG8_SCHED;
;             PG8_LDB(B1, 0, 1); PG8_STAGE(PG8_SB(0, 0), b2, voffB);
;             PG8_BAR; PG8_WAIT_L(0); PG8_MMA(0, 1, At, B1); PG8_BAR;
;             PG8_LDA(At, 0, 1); PG8_STAGE(PG8_SA(0, 0), a2, voffA);
;             PG8_BAR; PG8_WAIT_L(0); PG8_MMA(1, 0, At, B0); PG8_BAR; PG8_SCHED;
;             PG8_STAGE(PG8_SB(0, 1), b2 + hstep, voffB);
;             PG8_WAIT_V(6); PG8_BAR; PG8_MMA(1, 1, At, B1); PG8_BAR;
;             PG8_LDB(B0, 1, 0); PG8_SCHED; PG8_LDA(At, 1, 0); PG8_STAGE(PG8_SA(0, 1), a2 + hstep, voffA);
;             PG8_WAIT_L(8); PG8_BAR; PG8_WAIT_L(0); PG8_MMA(0, 0, At, B0); PG8_BAR; PG8_SCHED;
;             PG8_LDB(B1, 1, 1); PG8_STAGE(PG8_SB(1, 0), b3, voffB);
;             PG8_BAR; PG8_WAIT_L(0); PG8_MMA(0, 1, At, B1); PG8_BAR;
;             PG8_LDA(At, 1, 1); PG8_STAGE(PG8_SA(1, 0), a3, voffA);
;             PG8_BAR; PG8_WAIT_L(0); PG8_MMA(1, 0, At, B0); PG8_BAR; PG8_SCHED;
;             PG8_STAGE(PG8_SB(1, 1), b3 + hstep, voffB);
;             PG8_WAIT_V(6); PG8_BAR; PG8_MMA(1, 1, At, B1); PG8_BAR;
.LBB0_580:
	s_add_u32 s20, s18, 0xfff80080
	s_addc_u32 s21, s19, -1
	s_add_i32 s69, 0, 0x10000
	v_add_u32_e32 v142, s69, v144
	ds_read_b128 v[146:149], v142
	ds_read_b128 v[150:153], v142 offset:1024
	ds_read_b128 v[154:157], v142 offset:2048
	ds_read_b128 v[158:161], v142 offset:3072
	s_cmp_eq_u32 s88, 28
	s_cselect_b32 s71, s9, s21
	s_cselect_b32 s70, s11, s20
	s_cselect_b32 s21, s7, s83
	s_cselect_b32 s20, s81, s82
	v_lshl_add_u64 v[142:143], s[18:19], 0, v[138:139]
	s_add_i32 m0, s13, 0xc000
	ds_read_b128 v[162:165], v145
	ds_read_b128 v[166:169], v145 offset:1024
	ds_read_b128 v[170:173], v145 offset:2048
	ds_read_b128 v[174:177], v145 offset:3072
	ds_read_b128 v[184:187], v145 offset:4096
	ds_read_b128 v[188:191], v145 offset:5120
	ds_read_b128 v[192:195], v145 offset:6144
	ds_read_b128 v[196:199], v145 offset:7168
	global_load_lds_dwordx4 v[142:143], off
	v_lshl_add_u64 v[142:143], s[18:19], 0, v[140:141]
	s_add_i32 m0, s13, 0xe000
	s_nop 0
	global_load_lds_dwordx4 v[142:143], off
	s_waitcnt lgkmcnt(8)
	s_barrier
	s_waitcnt lgkmcnt(0)
	s_setprio 0
	s_waitcnt lgkmcnt(0)
	v_mfma_f32_16x16x32_bf16 v[124:127], v[146:149], v[162:165], v[124:127]
	v_mfma_f32_16x16x32_bf16 v[120:123], v[154:157], v[162:165], v[120:123]
	v_mfma_f32_16x16x32_bf16 v[116:119], v[146:149], v[170:173], v[116:119]
	v_mfma_f32_16x16x32_bf16 v[108:111], v[154:157], v[170:173], v[108:111]
	v_mfma_f32_16x16x32_bf16 v[100:103], v[146:149], v[184:187], v[100:103]
	v_mfma_f32_16x16x32_bf16 v[92:95], v[154:157], v[184:187], v[92:95]
	v_mfma_f32_16x16x32_bf16 v[84:87], v[146:149], v[192:195], v[84:87]
	v_mfma_f32_16x16x32_bf16 v[76:79], v[154:157], v[192:195], v[76:79]
	v_mfma_f32_16x16x32_bf16 v[124:127], v[150:153], v[166:169], v[124:127]
	v_mfma_f32_16x16x32_bf16 v[120:123], v[158:161], v[166:169], v[120:123]
	v_mfma_f32_16x16x32_bf16 v[116:119], v[150:153], v[174:177], v[116:119]
	v_mfma_f32_16x16x32_bf16 v[108:111], v[158:161], v[174:177], v[108:111]
	v_mfma_f32_16x16x32_bf16 v[100:103], v[150:153], v[188:191], v[100:103]
	v_mfma_f32_16x16x32_bf16 v[92:95], v[158:161], v[188:191], v[92:95]
	v_mfma_f32_16x16x32_bf16 v[84:87], v[150:153], v[196:199], v[84:87]
	v_mfma_f32_16x16x32_bf16 v[76:79], v[158:161], v[196:199], v[76:79]
	s_setprio 1
	s_barrier
	s_add_i32 s89, 0, 0x14000
	v_add_u32_e32 v142, s89, v144
	s_add_i32 s69, s69, s72
	ds_read_b128 v[200:203], v142
	ds_read_b128 v[204:207], v142 offset:1024
	ds_read_b128 v[208:211], v142 offset:2048
	ds_read_b128 v[212:215], v142 offset:3072
	v_lshl_add_u64 v[142:143], s[20:21], 0, v[180:181]
	s_mov_b32 m0, s69
	v_lshl_add_u64 v[178:179], s[20:21], 0, v[128:129]
	global_load_lds_dwordx4 v[142:143], off
	s_add_i32 m0, s69, 0x2000
	s_nop 0
	global_load_lds_dwordx4 v[178:179], off
	s_barrier
	s_waitcnt lgkmcnt(0)
	s_setprio 0
	s_waitcnt lgkmcnt(0)
	v_mfma_f32_16x16x32_bf16 v[112:115], v[200:203], v[162:165], v[112:115]
	v_mfma_f32_16x16x32_bf16 v[104:107], v[208:211], v[162:165], v[104:107]
	v_mfma_f32_16x16x32_bf16 v[96:99], v[200:203], v[170:173], v[96:99]
	v_mfma_f32_16x16x32_bf16 v[88:91], v[208:211], v[170:173], v[88:91]
	v_mfma_f32_16x16x32_bf16 v[80:83], v[200:203], v[184:187], v[80:83]
	v_mfma_f32_16x16x32_bf16 v[72:75], v[208:211], v[184:187], v[72:75]
	v_mfma_f32_16x16x32_bf16 v[68:71], v[200:203], v[192:195], v[68:71]
	v_mfma_f32_16x16x32_bf16 v[64:67], v[208:211], v[192:195], v[64:67]
	v_mfma_f32_16x16x32_bf16 v[112:115], v[204:207], v[166:169], v[112:115]
	v_mfma_f32_16x16x32_bf16 v[104:107], v[212:215], v[166:169], v[104:107]
	v_mfma_f32_16x16x32_bf16 v[96:99], v[204:207], v[174:177], v[96:99]
	v_mfma_f32_16x16x32_bf16 v[88:91], v[212:215], v[174:177], v[88:91]
	v_mfma_f32_16x16x32_bf16 v[80:83], v[204:207], v[188:191], v[80:83]
	v_mfma_f32_16x16x32_bf16 v[72:75], v[212:215], v[188:191], v[72:75]
	v_mfma_f32_16x16x32_bf16 v[68:71], v[204:207], v[196:199], v[68:71]
	v_mfma_f32_16x16x32_bf16 v[64:67], v[212:215], v[196:199], v[64:67]
	s_setprio 1
	s_mov_b32 m0, s13
	v_lshl_add_u64 v[216:217], s[70:71], 0, v[132:133]
	s_barrier
	ds_read_b128 v[162:165], v145 offset:16384
	ds_read_b128 v[166:169], v145 offset:17408
	ds_read_b128 v[170:173], v145 offset:18432
	ds_read_b128 v[174:177], v145 offset:19456
	ds_read_b128 v[184:187], v145 offset:20480
	ds_read_b128 v[188:191], v145 offset:21504
	ds_read_b128 v[192:195], v145 offset:22528
	ds_read_b128 v[196:199], v145 offset:23552
	global_load_lds_dwordx4 v[216:217], off
	v_lshl_add_u64 v[218:219], s[70:71], 0, v[130:131]
	s_mov_b32 m0, s75
	s_nop 0
	global_load_lds_dwordx4 v[218:219], off
	s_barrier
	s_waitcnt lgkmcnt(0)
	s_setprio 0
	s_waitcnt lgkmcnt(0)
	v_mfma_f32_16x16x32_bf16 v[60:63], v[146:149], v[162:165], v[60:63]
	v_mfma_f32_16x16x32_bf16 v[56:59], v[154:157], v[162:165], v[56:59]
	v_mfma_f32_16x16x32_bf16 v[52:55], v[146:149], v[170:173], v[52:55]
	v_mfma_f32_16x16x32_bf16 v[44:47], v[154:157], v[170:173], v[44:47]
	v_mfma_f32_16x16x32_bf16 v[36:39], v[146:149], v[184:187], v[36:39]
	v_mfma_f32_16x16x32_bf16 v[28:31], v[154:157], v[184:187], v[28:31]
	v_mfma_f32_16x16x32_bf16 v[20:23], v[146:149], v[192:195], v[20:23]
	v_mfma_f32_16x16x32_bf16 v[12:15], v[154:157], v[192:195], v[12:15]
	v_mfma_f32_16x16x32_bf16 v[60:63], v[150:153], v[166:169], v[60:63]
	v_mfma_f32_16x16x32_bf16 v[56:59], v[158:161], v[166:169], v[56:59]
	v_mfma_f32_16x16x32_bf16 v[52:55], v[150:153], v[174:177], v[52:55]
	v_mfma_f32_16x16x32_bf16 v[44:47], v[158:161], v[174:177], v[44:47]
	v_mfma_f32_16x16x32_bf16 v[36:39], v[150:153], v[188:191], v[36:39]
	v_mfma_f32_16x16x32_bf16 v[28:31], v[158:161], v[188:191], v[28:31]
	v_mfma_f32_16x16x32_bf16 v[20:23], v[150:153], v[196:199], v[20:23]
	v_mfma_f32_16x16x32_bf16 v[12:15], v[158:161], v[196:199], v[12:15]
	s_setprio 1
	s_barrier
; #define PG8_STAGE(bufoff, gbase, voff) do { _Pragma("unroll") for (int _i = 0; _i < 2; ++_i) \
;         __builtin_amdgcn_global_load_lds((const unsigned*)((const char*)(gbase) + (voff)[_i]), (PG8_LAS unsigned*)(lds + (bufoff) + ldsw + _i * 8192), 16, 0, 0); } while (0)
; #define PG8_LDA(dst, b, h) do { _Pragma("unroll") for (int m = 0; m < 4; ++m) _Pragma("unroll") for (int k = 0; k < 2; ++k) dst[m][k] = *(const PG8_LAS bf16x8*)(lds + PG8_SA(b, h) + aoff + m * 2048 + k * 1024); } while (0)
; #define PG8_WAIT_V(n) asm volatile("s_waitcnt vmcnt(" #n ")" ::: "memory")
; template <class Epi, class Sched>
; __device__ __forceinline__ void gemm_phase(PG8_LAS unsigned char* lds, const Gemm g, const Sched& S, const Epi& E) {
;     ...
;         for (int t = 0; t < nt; t += 2) {
;             const bool last = (t == nt - 2);
;             const char* a1 = cA + (size_t)(t + 1) * kstep;
;             const char* a2 = last ? nA : cA + (size_t)(t + 2) * kstep; const char* b2 = last ? nB : cB + (size_t)(t + 2) * kstep;
;             const char* a3 = a2 + kstep; const char* b3 = b2 + kstep;
;             if (last && has_next) S.a_ready(nxt);
;             PG8_LDB(B0, 0, 0); PG8_SCHED; PG8_LDA(At, 0, 0); PG8_STAGE(PG8_SA(1, 1), a1 + hstep, voffA);
;             PG8_WAIT_L(8); PG8_BAR; PG8_WAIT_L(0); PG8_MMA(0, 0, At, B0); PG8_BAR; PG8_SCHED;
;             PG8_LDB(B1, 0, 1); PG8_STAGE(PG8_SB(0, 0), b2, voffB);
;             PG8_BAR; PG8_WAIT_L(0); PG8_MMA(0, 1, At, B1); PG8_BAR;
;             PG8_LDA(At, 0, 1); PG8_STAGE(PG8_SA(0, 0), a2, voffA);
;             PG8_BAR; PG8_WAIT_L(0); PG8_MMA(1, 0, At, B0); PG8_BAR; PG8_SCHED;
;             PG8_STAGE(PG8_SB(0, 1), b2 + hstep, voffB);
;             PG8_WAIT_V(6); PG8_BAR; PG8_MMA(1, 1, At, B1); PG8_BAR;
;             PG8_LDB(B0, 1, 0); PG8_SCHED; PG8_LDA(At, 1, 0); PG8_STAGE(PG8_SA(0, 1), a2 + hstep, voffA);
;             PG8_WAIT_L(8); PG8_BAR; PG8_WAIT_L(0); PG8_MMA(0, 0, At, B0); PG8_BAR; PG8_SCHED;
;             PG8_LDB(B1, 1, 1); PG8_STAGE(PG8_SB(1, 0), b3, voffB);
;             PG8_BAR; PG8_WAIT_L(0); PG8_MMA(0, 1, At, B1); PG8_BAR;
;             PG8_LDA(At, 1, 1); PG8_STAGE(PG8_SA(1, 0), a3, voffA);
;             PG8_BAR; PG8_WAIT_L(0); PG8_MMA(1, 0, At, B0); PG8_BAR; PG8_SCHED;
;             PG8_STAGE(PG8_SB(1, 1), b3 + hstep, voffB);
;             PG8_WAIT_V(6); PG8_BAR; PG8_MMA(1, 1, At, B1); PG8_BAR;
	s_add_u32 vcc_lo, s20, 0x80000
	s_addc_u32 vcc_hi, s21, 0
	s_add_i32 s69, s89, s72
	v_lshl_add_u64 v[146:147], vcc, 0, v[180:181]
	s_mov_b32 m0, s69
	s_nop 0
	global_load_lds_dwordx4 v[146:147], off
	v_lshl_add_u64 v[146:147], vcc, 0, v[128:129]
	s_add_i32 m0, s69, 0x2000
	s_nop 0
	global_load_lds_dwordx4 v[146:147], off
	s_waitcnt vmcnt(6)
	s_barrier
	s_setprio 0
	v_mfma_f32_16x16x32_bf16 v[48:51], v[200:203], v[162:165], v[48:51]
	v_mfma_f32_16x16x32_bf16 v[40:43], v[208:211], v[162:165], v[40:43]
	v_mfma_f32_16x16x32_bf16 v[32:35], v[200:203], v[170:173], v[32:35]
	v_mfma_f32_16x16x32_bf16 v[24:27], v[208:211], v[170:173], v[24:27]
	v_mfma_f32_16x16x32_bf16 v[16:19], v[200:203], v[184:187], v[16:19]
	v_mfma_f32_16x16x32_bf16 v[8:11], v[208:211], v[184:187], v[8:11]
	v_mfma_f32_16x16x32_bf16 v[4:7], v[200:203], v[192:195], v[4:7]
	v_mfma_f32_16x16x32_bf16 v[0:3], v[208:211], v[192:195], v[0:3]
	v_mfma_f32_16x16x32_bf16 v[48:51], v[204:207], v[166:169], v[48:51]
	v_mfma_f32_16x16x32_bf16 v[40:43], v[212:215], v[166:169], v[40:43]
	v_mfma_f32_16x16x32_bf16 v[32:35], v[204:207], v[174:177], v[32:35]
	v_mfma_f32_16x16x32_bf16 v[24:27], v[212:215], v[174:177], v[24:27]
	v_mfma_f32_16x16x32_bf16 v[16:19], v[204:207], v[188:191], v[16:19]
	v_mfma_f32_16x16x32_bf16 v[8:11], v[212:215], v[188:191], v[8:11]
	v_mfma_f32_16x16x32_bf16 v[4:7], v[204:207], v[196:199], v[4:7]
	v_mfma_f32_16x16x32_bf16 v[0:3], v[212:215], v[196:199], v[0:3]
	s_setprio 1
	s_add_i32 s69, 0, 0x18000
	v_add_u32_e32 v158, s69, v144
	s_barrier
	ds_read_b128 v[146:149], v158
	ds_read_b128 v[150:153], v158 offset:1024
	ds_read_b128 v[154:157], v158 offset:2048
	ds_read_b128 v[158:161], v158 offset:3072
	s_add_u32 s70, s70, 0x80000
	s_addc_u32 s71, s71, 0
	s_mov_b32 m0, s76
	v_lshl_add_u64 v[200:201], s[70:71], 0, v[132:133]
	ds_read_b128 v[162:165], v145 offset:32768
	ds_read_b128 v[166:169], v145 offset:33792
	ds_read_b128 v[170:173], v145 offset:34816
	ds_read_b128 v[174:177], v145 offset:35840
	ds_read_b128 v[184:187], v145 offset:36864
	ds_read_b128 v[188:191], v145 offset:37888
	ds_read_b128 v[192:195], v145 offset:38912
	ds_read_b128 v[196:199], v145 offset:39936
	global_load_lds_dwordx4 v[200:201], off
	v_lshl_add_u64 v[200:201], s[70:71], 0, v[130:131]
	s_mov_b32 m0, s77
	s_nop 0
	global_load_lds_dwordx4 v[200:201], off
	s_waitcnt lgkmcnt(8)
	s_barrier
	s_waitcnt lgkmcnt(0)
	s_setprio 0
	s_waitcnt lgkmcnt(0)
	v_mfma_f32_16x16x32_bf16 v[124:127], v[146:149], v[162:165], v[124:127]
	v_mfma_f32_16x16x32_bf16 v[120:123], v[154:157], v[162:165], v[120:123]
	v_mfma_f32_16x16x32_bf16 v[116:119], v[146:149], v[170:173], v[116:119]
	v_mfma_f32_16x16x32_bf16 v[108:111], v[154:157], v[170:173], v[108:111]
	v_mfma_f32_16x16x32_bf16 v[100:103], v[146:149], v[184:187], v[100:103]
	v_mfma_f32_16x16x32_bf16 v[92:95], v[154:157], v[184:187], v[92:95]
	v_mfma_f32_16x16x32_bf16 v[84:87], v[146:149], v[192:195], v[84:87]
	v_mfma_f32_16x16x32_bf16 v[76:79], v[154:157], v[192:195], v[76:79]
	v_mfma_f32_16x16x32_bf16 v[124:127], v[150:153], v[166:169], v[124:127]
	v_mfma_f32_16x16x32_bf16 v[120:123], v[158:161], v[166:169], v[120:123]
	v_mfma_f32_16x16x32_bf16 v[116:119], v[150:153], v[174:177], v[116:119]
	v_mfma_f32_16x16x32_bf16 v[108:111], v[158:161], v[174:177], v[108:111]
	v_mfma_f32_16x16x32_bf16 v[100:103], v[150:153], v[188:191], v[100:103]
	v_mfma_f32_16x16x32_bf16 v[92:95], v[158:161], v[188:191], v[92:95]
	v_mfma_f32_16x16x32_bf16 v[84:87], v[150:153], v[196:199], v[84:87]
	v_mfma_f32_16x16x32_bf16 v[76:79], v[158:161], v[196:199], v[76:79]
	s_setprio 1
	s_barrier
	s_add_i32 s70, 0, 0x1c000
	s_add_i32 s69, s69, s72
	v_add_u32_e32 v212, s70, v144
	v_lshl_add_u64 v[142:143], v[142:143], 0, s[38:39]
	s_mov_b32 m0, s69
	ds_read_b128 v[200:203], v212
	ds_read_b128 v[204:207], v212 offset:1024
	ds_read_b128 v[208:211], v212 offset:2048
	ds_read_b128 v[212:215], v212 offset:3072
	global_load_lds_dwordx4 v[142:143], off
	v_lshl_add_u64 v[142:143], v[178:179], 0, s[38:39]
	s_add_i32 m0, s69, 0x2000
	s_nop 0
	global_load_lds_dwordx4 v[142:143], off
	s_barrier
	s_waitcnt lgkmcnt(0)
	s_setprio 0
	s_waitcnt lgkmcnt(0)
	v_mfma_f32_16x16x32_bf16 v[112:115], v[200:203], v[162:165], v[112:115]
	v_mfma_f32_16x16x32_bf16 v[104:107], v[208:211], v[162:165], v[104:107]
	v_mfma_f32_16x16x32_bf16 v[96:99], v[200:203], v[170:173], v[96:99]
	v_mfma_f32_16x16x32_bf16 v[88:91], v[208:211], v[170:173], v[88:91]
	v_mfma_f32_16x16x32_bf16 v[80:83], v[200:203], v[184:187], v[80:83]
	v_mfma_f32_16x16x32_bf16 v[72:75], v[208:211], v[184:187], v[72:75]
	v_mfma_f32_16x16x32_bf16 v[68:71], v[200:203], v[192:195], v[68:71]
	v_mfma_f32_16x16x32_bf16 v[64:67], v[208:211], v[192:195], v[64:67]
	v_mfma_f32_16x16x32_bf16 v[112:115], v[204:207], v[166:169], v[112:115]
	v_mfma_f32_16x16x32_bf16 v[104:107], v[212:215], v[166:169], v[104:107]
	v_mfma_f32_16x16x32_bf16 v[96:99], v[204:207], v[174:177], v[96:99]
	v_mfma_f32_16x16x32_bf16 v[88:91], v[212:215], v[174:177], v[88:91]
	v_mfma_f32_16x16x32_bf16 v[80:83], v[204:207], v[188:191], v[80:83]
	v_mfma_f32_16x16x32_bf16 v[72:75], v[212:215], v[188:191], v[72:75]
	v_mfma_f32_16x16x32_bf16 v[68:71], v[204:207], v[196:199], v[68:71]
	v_mfma_f32_16x16x32_bf16 v[64:67], v[212:215], v[196:199], v[64:67]
	s_setprio 1
	s_mov_b32 m0, s78
	v_lshl_add_u64 v[142:143], v[216:217], 0, s[38:39]
	s_barrier
	ds_read_b128 v[162:165], v145 offset:49152
	ds_read_b128 v[166:169], v145 offset:50176
	ds_read_b128 v[170:173], v145 offset:51200
	ds_read_b128 v[174:177], v145 offset:52224
	ds_read_b128 v[184:187], v145 offset:53248
	ds_read_b128 v[188:191], v145 offset:54272
	ds_read_b128 v[192:195], v145 offset:55296
	ds_read_b128 v[196:199], v145 offset:56320
	global_load_lds_dwordx4 v[142:143], off
	v_lshl_add_u64 v[142:143], v[218:219], 0, s[38:39]
	s_mov_b32 m0, s79
	s_nop 0
	global_load_lds_dwordx4 v[142:143], off
	s_barrier
; #define PG8_STAGE(bufoff, gbase, voff) do { _Pragma("unroll") for (int _i = 0; _i < 2; ++_i) \
;         __builtin_amdgcn_global_load_lds((const unsigned*)((const char*)(gbase) + (voff)[_i]), (PG8_LAS unsigned*)(lds + (bufoff) + ldsw + _i * 8192), 16, 0, 0); } while (0)
; #define PG8_LDA(dst, b, h) do { _Pragma("unroll") for (int m = 0; m < 4; ++m) _Pragma("unroll") for (int k = 0; k < 2; ++k) dst[m][k] = *(const PG8_LAS bf16x8*)(lds + PG8_SA(b, h) + aoff + m * 2048 + k * 1024); } while (0)
; #define PG8_WAIT_V(n) asm volatile("s_waitcnt vmcnt(" #n ")" ::: "memory")
; template <class Epi, class Sched>
; __device__ __forceinline__ void gemm_phase(PG8_LAS unsigned char* lds, const Gemm g, const Sched& S, const Epi& E) {
;     ...
;         for (int t = 0; t < nt; t += 2) {
;             const bool last = (t == nt - 2);
;             const char* a1 = cA + (size_t)(t + 1) * kstep;
;             const char* a2 = last ? nA : cA + (size_t)(t + 2) * kstep; const char* b2 = last ? nB : cB + (size_t)(t + 2) * kstep;
;             const char* a3 = a2 + kstep; const char* b3 = b2 + kstep;
;             if (last && has_next) S.a_ready(nxt);
;             PG8_LDB(B0, 0, 0); PG8_SCHED; PG8_LDA(At, 0, 0); PG8_STAGE(PG8_SA(1, 1), a1 + hstep, voffA);
;             PG8_WAIT_L(8); PG8_BAR; PG8_WAIT_L(0); PG8_MMA(0, 0, At, B0); PG8_BAR; PG8_SCHED;
;             PG8_LDB(B1, 0, 1); PG8_STAGE(PG8_SB(0, 0), b2, voffB);
;             PG8_BAR; PG8_WAIT_L(0); PG8_MMA(0, 1, At, B1); PG8_BAR;
;             PG8_LDA(At, 0, 1); PG8_STAGE(PG8_SA(0, 0), a2, voffA);
;             PG8_BAR; PG8_WAIT_L(0); PG8_MMA(1, 0, At, B0); PG8_BAR; PG8_SCHED;
;             PG8_STAGE(PG8_SB(0, 1), b2 + hstep, voffB);
;             PG8_WAIT_V(6); PG8_BAR; PG8_MMA(1, 1, At, B1); PG8_BAR;
;             PG8_LDB(B0, 1, 0); PG8_SCHED; PG8_LDA(At, 1, 0); PG8_STAGE(PG8_SA(0, 1), a2 + hstep, voffA);
;             PG8_WAIT_L(8); PG8_BAR; PG8_WAIT_L(0); PG8_MMA(0, 0, At, B0); PG8_BAR; PG8_SCHED;
;             PG8_LDB(B1, 1, 1); PG8_STAGE(PG8_SB(1, 0), b3, voffB);
;             PG8_BAR; PG8_WAIT_L(0); PG8_MMA(0, 1, At, B1); PG8_BAR;
;             PG8_LDA(At, 1, 1); PG8_STAGE(PG8_SA(1, 0), a3, voffA);
;             PG8_BAR; PG8_WAIT_L(0); PG8_MMA(1, 0, At, B0); PG8_BAR; PG8_SCHED;
;             PG8_STAGE(PG8_SB(1, 1), b3 + hstep, voffB);
;             PG8_WAIT_V(6); PG8_BAR; PG8_MMA(1, 1, At, B1); PG8_BAR;
	s_waitcnt lgkmcnt(0)
	s_setprio 0
	s_waitcnt lgkmcnt(0)
	v_mfma_f32_16x16x32_bf16 v[60:63], v[146:149], v[162:165], v[60:63]
	v_mfma_f32_16x16x32_bf16 v[56:59], v[154:157], v[162:165], v[56:59]
	v_mfma_f32_16x16x32_bf16 v[52:55], v[146:149], v[170:173], v[52:55]
	v_mfma_f32_16x16x32_bf16 v[44:47], v[154:157], v[170:173], v[44:47]
	v_mfma_f32_16x16x32_bf16 v[36:39], v[146:149], v[184:187], v[36:39]
	v_mfma_f32_16x16x32_bf16 v[28:31], v[154:157], v[184:187], v[28:31]
	v_mfma_f32_16x16x32_bf16 v[20:23], v[146:149], v[192:195], v[20:23]
	v_mfma_f32_16x16x32_bf16 v[12:15], v[154:157], v[192:195], v[12:15]
	v_mfma_f32_16x16x32_bf16 v[60:63], v[150:153], v[166:169], v[60:63]
	v_mfma_f32_16x16x32_bf16 v[56:59], v[158:161], v[166:169], v[56:59]
	v_mfma_f32_16x16x32_bf16 v[52:55], v[150:153], v[174:177], v[52:55]
	v_mfma_f32_16x16x32_bf16 v[44:47], v[158:161], v[174:177], v[44:47]
	v_mfma_f32_16x16x32_bf16 v[36:39], v[150:153], v[188:191], v[36:39]
	v_mfma_f32_16x16x32_bf16 v[28:31], v[158:161], v[188:191], v[28:31]
	v_mfma_f32_16x16x32_bf16 v[20:23], v[150:153], v[196:199], v[20:23]
	v_mfma_f32_16x16x32_bf16 v[12:15], v[158:161], v[196:199], v[12:15]
	s_setprio 1
	s_barrier
	s_add_u32 s20, s20, 0x80080
	s_addc_u32 s21, s21, 0
	s_add_i32 s69, s70, s72
	v_lshl_add_u64 v[142:143], s[20:21], 0, v[180:181]
	s_mov_b32 m0, s69
	s_nop 0
	global_load_lds_dwordx4 v[142:143], off
	v_lshl_add_u64 v[142:143], s[20:21], 0, v[128:129]
	s_add_i32 m0, s69, 0x2000
	s_nop 0
	global_load_lds_dwordx4 v[142:143], off
	s_waitcnt vmcnt(6)
	s_barrier
	s_setprio 0
	v_mfma_f32_16x16x32_bf16 v[48:51], v[200:203], v[162:165], v[48:51]
	v_mfma_f32_16x16x32_bf16 v[40:43], v[208:211], v[162:165], v[40:43]
	v_mfma_f32_16x16x32_bf16 v[32:35], v[200:203], v[170:173], v[32:35]
	v_mfma_f32_16x16x32_bf16 v[24:27], v[208:211], v[170:173], v[24:27]
	v_mfma_f32_16x16x32_bf16 v[16:19], v[200:203], v[184:187], v[16:19]
	v_mfma_f32_16x16x32_bf16 v[8:11], v[208:211], v[184:187], v[8:11]
	v_mfma_f32_16x16x32_bf16 v[4:7], v[200:203], v[192:195], v[4:7]
	v_mfma_f32_16x16x32_bf16 v[0:3], v[208:211], v[192:195], v[0:3]
	v_mfma_f32_16x16x32_bf16 v[48:51], v[204:207], v[166:169], v[48:51]
	v_mfma_f32_16x16x32_bf16 v[40:43], v[212:215], v[166:169], v[40:43]
	v_mfma_f32_16x16x32_bf16 v[32:35], v[204:207], v[174:177], v[32:35]
	v_mfma_f32_16x16x32_bf16 v[24:27], v[212:215], v[174:177], v[24:27]
	v_mfma_f32_16x16x32_bf16 v[16:19], v[204:207], v[188:191], v[16:19]
	v_mfma_f32_16x16x32_bf16 v[8:11], v[212:215], v[188:191], v[8:11]
	v_mfma_f32_16x16x32_bf16 v[4:7], v[204:207], v[196:199], v[4:7]
	v_mfma_f32_16x16x32_bf16 v[0:3], v[212:215], v[196:199], v[0:3]
	s_setprio 1
	s_add_i32 s88, s88, 2
	s_add_u32 s18, s18, 0x100
	s_addc_u32 s19, s19, 0
	s_add_u32 s82, s82, 0x100
	s_addc_u32 s83, s83, 0
	s_cmp_gt_u32 s88, 29
	s_barrier
	s_cbranch_scc0 .LBB0_580
; #define PG8_WAIT_V(n) asm volatile("s_waitcnt vmcnt(" #n ")" ::: "memory")
; #define PG8_BAR __builtin_amdgcn_s_barrier()
; DI void store8(bf16_t* p, f32x4 a, f32x4 b) { u32x4 w = {cvt_pk_bf16(a[0], a[1]), cvt_pk_bf16(a[2], a[3]), cvt_pk_bf16(b[0], b[1]), cvt_pk_bf16(b[2], b[3])}; *(u32x4*)p = w; }
; template <class Epi, class Sched>
; __device__ __forceinline__ void gemm_phase(PG8_LAS unsigned char* lds, const Gemm g, const Sched& S, const Epi& E) {
;     ...
;         E(acc, cur, wr, wc, fr, fq); S.done(cur);
;         if (!has_next) break;
; #pragma unroll
;         for (int a = 0; a < 2; ++a)
; #pragma unroll
;             for (int b = 0; b < 2; ++b)
; #pragma unroll
;                 for (int m = 0; m < 4; ++m)
; #pragma unroll
;                     for (int n = 0; n < 2; ++n) acc[a][b][m][n] = (f32x4){0.f, 0.f, 0.f, 0.f};
;         cur = nxt; cA = nA; cB = nB; ++ui;
;     }
;     PG8_WAIT_V(0);
;     if (wr == 0) PG8_BAR;
;     PG8_BAR;
;     DI void operator()(const AccT& acc, const pg8::Unit& u, int wr, int wc, int fr, int fq) const {
;         bf16_t* dst = o + u.pn * 256 + wc * 32 + 8 * fq;
; #pragma unroll
;         for (int ai = 0; ai < 2; ++ai)
; #pragma unroll
;             for (int m = 0; m < 4; ++m) { const size_t row = (size_t)u.pm * 256 + wr * 64 + fr + ai * 128 + m * 16;
; #pragma unroll
;                 for (int bj = 0; bj < 2; ++bj) store8(dst + row * ldc + bj * 128, acc[ai][bj][m][0], acc[ai][bj][m][1]); }
;     }
	s_lshl_b32 s18, s12, 8
	s_ashr_i32 s19, s18, 31
	s_ashr_i32 s11, s10, 31
	v_lshl_add_u64 v[142:143], s[18:19], 1, v[134:135]
	s_lshl_b64 s[10:11], s[10:11], 19
	v_lshl_add_u64 v[142:143], v[142:143], 0, s[10:11]
	v_lshl_add_u64 v[142:143], v[142:143], 0, v[136:137]
	s_mov_b32 s7, 0x8000
	v_cvt_pk_bf16_f32 v124, v124, v125
	v_cvt_pk_bf16_f32 v125, v126, v127
	v_cvt_pk_bf16_f32 v126, v120, v121
	v_cvt_pk_bf16_f32 v127, v122, v123
	global_store_dwordx4 v[142:143], v[124:127], off
	v_cvt_pk_bf16_f32 v112, v112, v113
	v_cvt_pk_bf16_f32 v113, v114, v115
	v_cvt_pk_bf16_f32 v114, v104, v105
	v_cvt_pk_bf16_f32 v115, v106, v107
	global_store_dwordx4 v[142:143], v[112:115], off offset:256
	v_cvt_pk_bf16_f32 v104, v116, v117
	v_cvt_pk_bf16_f32 v105, v118, v119
	v_cvt_pk_bf16_f32 v106, v108, v109
	v_add_co_u32_e32 v108, vcc, s7, v142
	s_mov_b32 s7, 0x10000
	s_nop 0
	v_addc_co_u32_e32 v109, vcc, 0, v143, vcc
	v_cvt_pk_bf16_f32 v107, v110, v111
	global_store_dwordx4 v[108:109], v[104:107], off
	v_cvt_pk_bf16_f32 v96, v96, v97
	v_cvt_pk_bf16_f32 v97, v98, v99
	v_cvt_pk_bf16_f32 v98, v88, v89
	v_cvt_pk_bf16_f32 v99, v90, v91
	global_store_dwordx4 v[108:109], v[96:99], off offset:256
	v_cvt_pk_bf16_f32 v88, v100, v101
	v_cvt_pk_bf16_f32 v89, v102, v103
	v_cvt_pk_bf16_f32 v90, v92, v93
	v_add_co_u32_e32 v92, vcc, s7, v142
	s_mov_b32 s7, 0x18000
	s_nop 0
	v_addc_co_u32_e32 v93, vcc, 0, v143, vcc
	v_cvt_pk_bf16_f32 v91, v94, v95
	global_store_dwordx4 v[92:93], v[88:91], off
	v_cvt_pk_bf16_f32 v80, v80, v81
	v_cvt_pk_bf16_f32 v81, v82, v83
	v_cvt_pk_bf16_f32 v82, v72, v73
	v_cvt_pk_bf16_f32 v83, v74, v75
	global_store_dwordx4 v[92:93], v[80:83], off offset:256
	v_cvt_pk_bf16_f32 v72, v84, v85
	v_cvt_pk_bf16_f32 v73, v86, v87
	v_cvt_pk_bf16_f32 v74, v76, v77
	v_add_co_u32_e32 v76, vcc, s7, v142
	s_mov_b32 s7, 0x40000
	s_nop 0
	v_addc_co_u32_e32 v77, vcc, 0, v143, vcc
	v_cvt_pk_bf16_f32 v75, v78, v79
	global_store_dwordx4 v[76:77], v[72:75], off
	v_cvt_pk_bf16_f32 v68, v68, v69
	v_cvt_pk_bf16_f32 v69, v70, v71
	v_cvt_pk_bf16_f32 v70, v64, v65
	v_cvt_pk_bf16_f32 v71, v66, v67
	global_store_dwordx4 v[76:77], v[68:71], off offset:256
	v_cvt_pk_bf16_f32 v60, v60, v61
	v_cvt_pk_bf16_f32 v61, v62, v63
	v_cvt_pk_bf16_f32 v62, v56, v57
	v_add_co_u32_e32 v56, vcc, s7, v142
	s_mov_b32 s7, 0x48000
	s_nop 0
	v_addc_co_u32_e32 v57, vcc, 0, v143, vcc
	v_cvt_pk_bf16_f32 v63, v58, v59
	global_store_dwordx4 v[56:57], v[60:63], off
	v_cvt_pk_bf16_f32 v48, v48, v49
	v_cvt_pk_bf16_f32 v49, v50, v51
	v_cvt_pk_bf16_f32 v50, v40, v41
	v_cvt_pk_bf16_f32 v51, v42, v43
	global_store_dwordx4 v[56:57], v[48:51], off offset:256
	v_cvt_pk_bf16_f32 v40, v52, v53
	v_cvt_pk_bf16_f32 v41, v54, v55
	v_cvt_pk_bf16_f32 v42, v44, v45
	v_add_co_u32_e32 v44, vcc, s7, v142
	s_mov_b32 s7, 0x50000
	s_nop 0
	v_addc_co_u32_e32 v45, vcc, 0, v143, vcc
	v_cvt_pk_bf16_f32 v43, v46, v47
	global_store_dwordx4 v[44:45], v[40:43], off
	v_cvt_pk_bf16_f32 v32, v32, v33
	v_cvt_pk_bf16_f32 v33, v34, v35
	v_cvt_pk_bf16_f32 v34, v24, v25
	v_cvt_pk_bf16_f32 v35, v26, v27
	global_store_dwordx4 v[44:45], v[32:35], off offset:256
	v_cvt_pk_bf16_f32 v24, v36, v37
	v_cvt_pk_bf16_f32 v25, v38, v39
	v_cvt_pk_bf16_f32 v26, v28, v29
	v_add_co_u32_e32 v28, vcc, s7, v142
	s_mov_b32 s7, 0x58000
	s_nop 0
	v_addc_co_u32_e32 v29, vcc, 0, v143, vcc
	v_cvt_pk_bf16_f32 v27, v30, v31
	global_store_dwordx4 v[28:29], v[24:27], off
	v_cvt_pk_bf16_f32 v16, v16, v17
	v_cvt_pk_bf16_f32 v17, v18, v19
	v_cvt_pk_bf16_f32 v18, v8, v9
	v_cvt_pk_bf16_f32 v19, v10, v11
	global_store_dwordx4 v[28:29], v[16:19], off offset:256
	v_cvt_pk_bf16_f32 v8, v20, v21
	v_cvt_pk_bf16_f32 v9, v22, v23
	v_cvt_pk_bf16_f32 v10, v12, v13
	v_add_co_u32_e32 v12, vcc, s7, v142
	s_mov_b32 s12, s6
	s_nop 0
	v_addc_co_u32_e32 v13, vcc, 0, v143, vcc
	s_and_b64 vcc, exec, s[0:1]
	s_mov_b32 s10, s8
	s_mov_b64 s[20:21], s[16:17]
	s_mov_b64 s[18:19], s[14:15]
	v_cvt_pk_bf16_f32 v11, v14, v15
	global_store_dwordx4 v[12:13], v[8:11], off
	v_cvt_pk_bf16_f32 v4, v4, v5
	v_cvt_pk_bf16_f32 v5, v6, v7
	v_cvt_pk_bf16_f32 v6, v0, v1
	v_cvt_pk_bf16_f32 v7, v2, v3
	global_store_dwordx4 v[12:13], v[4:7], off offset:256
	s_cbranch_vccz .LBB0_577
	s_waitcnt vmcnt(0)
	s_cmpk_gt_u32 s47, 0xff
	s_cbranch_scc1 .LBB0_584
	s_barrier

; #define PG8_STAGE(bufoff, gbase, voff) do { _Pragma("unroll") for (int _i = 0; _i < 2; ++_i) \
;         __builtin_amdgcn_global_load_lds((const unsigned*)((const char*)(gbase) + (voff)[_i]), (PG8_LAS unsigned*)(lds + (bufoff) + ldsw + _i * 8192), 16, 0, 0); } while (0)
; #define PG8_LDA(dst, b, h) do { _Pragma("unroll") for (int m = 0; m < 4; ++m) _Pragma("unroll") for (int k = 0; k < 2; ++k) dst[m][k] = *(const PG8_LAS bf16x8*)(lds + PG8_SA(b, h) + aoff + m * 2048 + k * 1024); } while (0)
; #define PG8_WAIT_V(n) asm volatile("s_waitcnt vmcnt(" #n ")" ::: "memory")
; template <class Epi, class Sched>
; __device__ __forceinline__ void gemm_phase(PG8_LAS unsigned char* lds, const Gemm g, const Sched& S, const Epi& E) {
;     ...
;         for (int t = 0; t < nt; t += 2) {
;             const bool last = (t == nt - 2);
;             const char* a1 = cA + (size_t)(t + 1) * kstep;
;             const char* a2 = last ? nA : cA + (size_t)(t + 2) * kstep; const char* b2 = last ? nB : cB + (size_t)(t + 2) * kstep;
;             const char* a3 = a2 + kstep; const char* b3 = b2 + kstep;
;             if (last && has_next) S.a_ready(nxt);
;             PG8_LDB(B0, 0, 0); PG8_SCHED; PG8_LDA(At, 0, 0); PG8_STAGE(PG8_SA(1, 1), a1 + hstep, voffA);
;             PG8_WAIT_L(8); PG8_BAR; PG8_WAIT_L(0); PG8_MMA(0, 0, At, B0); PG8_BAR; PG8_SCHED;
;             PG8_LDB(B1, 0, 1); PG8_STAGE(PG8_SB(0, 0), b2, voffB);
;             PG8_BAR; PG8_WAIT_L(0); PG8_MMA(0, 1, At, B1); PG8_BAR;
;             PG8_LDA(At, 0, 1); PG8_STAGE(PG8_SA(0, 0), a2, voffA);
;             PG8_BAR; PG8_WAIT_L(0); PG8_MMA(1, 0, At, B0); PG8_BAR; PG8_SCHED;
;             PG8_STAGE(PG8_SB(0, 1), b2 + hstep, voffB);
;             PG8_WAIT_V(6); PG8_BAR; PG8_MMA(1, 1, At, B1); PG8_BAR;
;             PG8_LDB(B0, 1, 0); PG8_SCHED; PG8_LDA(At, 1, 0); PG8_STAGE(PG8_SA(0, 1), a2 + hstep, voffA);
;             PG8_WAIT_L(8); PG8_BAR; PG8_WAIT_L(0); PG8_MMA(0, 0, At, B0); PG8_BAR; PG8_SCHED;
;             PG8_LDB(B1, 1, 1); PG8_STAGE(PG8_SB(1, 0), b3, voffB);
;             PG8_BAR; PG8_WAIT_L(0); PG8_MMA(0, 1, At, B1); PG8_BAR;
;             PG8_LDA(At, 1, 1); PG8_STAGE(PG8_SA(1, 0), a3, voffA);
;             PG8_BAR; PG8_WAIT_L(0); PG8_MMA(1, 0, At, B0); PG8_BAR; PG8_SCHED;
;             PG8_STAGE(PG8_SB(1, 1), b3 + hstep, voffB);
;             PG8_WAIT_V(6); PG8_BAR; PG8_MMA(1, 1, At, B1); PG8_BAR;
.LBB0_648:
	s_add_u32 s16, s14, 0xfffc0080
	s_addc_u32 s17, s15, -1
	s_add_i32 s80, 0, 0x10000
	v_add_u32_e32 v146, s80, v139
	ds_read_b128 v[150:153], v146
	ds_read_b128 v[154:157], v146 offset:1024
	ds_read_b128 v[158:161], v146 offset:2048
	ds_read_b128 v[162:165], v146 offset:3072
	s_cmp_eq_u32 s79, 12
	s_cselect_b32 s19, s9, s17
	s_cselect_b32 s18, s75, s16
	s_cselect_b32 s17, s1, s78
	s_cselect_b32 s16, s76, s77
	v_lshl_add_u64 v[146:147], s[14:15], 0, v[142:143]
	s_add_i32 m0, s46, 0xc000
	ds_read_b128 v[166:169], v148
	ds_read_b128 v[170:173], v148 offset:1024
	ds_read_b128 v[174:177], v148 offset:2048
	ds_read_b128 v[184:187], v148 offset:3072
	ds_read_b128 v[188:191], v148 offset:4096
	ds_read_b128 v[192:195], v148 offset:5120
	ds_read_b128 v[196:199], v148 offset:6144
	ds_read_b128 v[200:203], v148 offset:7168
	global_load_lds_dwordx4 v[146:147], off
	v_lshl_add_u64 v[146:147], s[14:15], 0, v[144:145]
	s_add_i32 m0, s46, 0xe000
	s_nop 0
	global_load_lds_dwordx4 v[146:147], off
	s_waitcnt lgkmcnt(8)
	s_barrier
	s_waitcnt lgkmcnt(0)
	s_setprio 0
	s_waitcnt lgkmcnt(0)
	v_mfma_f32_16x16x32_bf16 v[124:127], v[150:153], v[166:169], v[124:127]
	v_mfma_f32_16x16x32_bf16 v[120:123], v[158:161], v[166:169], v[120:123]
	v_mfma_f32_16x16x32_bf16 v[108:111], v[150:153], v[174:177], v[108:111]
	v_mfma_f32_16x16x32_bf16 v[104:107], v[158:161], v[174:177], v[104:107]
	v_mfma_f32_16x16x32_bf16 v[92:95], v[150:153], v[188:191], v[92:95]
	v_mfma_f32_16x16x32_bf16 v[88:91], v[158:161], v[188:191], v[88:91]
	v_mfma_f32_16x16x32_bf16 v[76:79], v[150:153], v[196:199], v[76:79]
	v_mfma_f32_16x16x32_bf16 v[72:75], v[158:161], v[196:199], v[72:75]
	v_mfma_f32_16x16x32_bf16 v[124:127], v[154:157], v[170:173], v[124:127]
	v_mfma_f32_16x16x32_bf16 v[120:123], v[162:165], v[170:173], v[120:123]
	v_mfma_f32_16x16x32_bf16 v[108:111], v[154:157], v[184:187], v[108:111]
	v_mfma_f32_16x16x32_bf16 v[104:107], v[162:165], v[184:187], v[104:107]
	v_mfma_f32_16x16x32_bf16 v[92:95], v[154:157], v[192:195], v[92:95]
	v_mfma_f32_16x16x32_bf16 v[88:91], v[162:165], v[192:195], v[88:91]
	v_mfma_f32_16x16x32_bf16 v[76:79], v[154:157], v[200:203], v[76:79]
	v_mfma_f32_16x16x32_bf16 v[72:75], v[162:165], v[200:203], v[72:75]
	s_setprio 1
	s_barrier
	s_add_i32 s82, 0, 0x14000
	v_add_u32_e32 v146, s82, v139
	s_add_i32 s80, s80, s21
	ds_read_b128 v[204:207], v146
	ds_read_b128 v[208:211], v146 offset:1024
	ds_read_b128 v[212:215], v146 offset:2048
	ds_read_b128 v[216:219], v146 offset:3072
	v_lshl_add_u64 v[146:147], s[16:17], 0, v[132:133]
	s_mov_b32 m0, s80
	v_lshl_add_u64 v[178:179], s[16:17], 0, v[128:129]
	global_load_lds_dwordx4 v[146:147], off
	s_add_i32 m0, s80, 0x2000
	s_nop 0
	global_load_lds_dwordx4 v[178:179], off
	s_barrier
	s_waitcnt lgkmcnt(0)
	s_setprio 0
	s_waitcnt lgkmcnt(0)
	v_mfma_f32_16x16x32_bf16 v[116:119], v[204:207], v[166:169], v[116:119]
	v_mfma_f32_16x16x32_bf16 v[112:115], v[212:215], v[166:169], v[112:115]
	v_mfma_f32_16x16x32_bf16 v[100:103], v[204:207], v[174:177], v[100:103]
	v_mfma_f32_16x16x32_bf16 v[96:99], v[212:215], v[174:177], v[96:99]
	v_mfma_f32_16x16x32_bf16 v[84:87], v[204:207], v[188:191], v[84:87]
	v_mfma_f32_16x16x32_bf16 v[80:83], v[212:215], v[188:191], v[80:83]
	v_mfma_f32_16x16x32_bf16 v[68:71], v[204:207], v[196:199], v[68:71]
	v_mfma_f32_16x16x32_bf16 v[64:67], v[212:215], v[196:199], v[64:67]
	v_mfma_f32_16x16x32_bf16 v[116:119], v[208:211], v[170:173], v[116:119]
	v_mfma_f32_16x16x32_bf16 v[112:115], v[216:219], v[170:173], v[112:115]
	v_mfma_f32_16x16x32_bf16 v[100:103], v[208:211], v[184:187], v[100:103]
	v_mfma_f32_16x16x32_bf16 v[96:99], v[216:219], v[184:187], v[96:99]
	v_mfma_f32_16x16x32_bf16 v[84:87], v[208:211], v[192:195], v[84:87]
	v_mfma_f32_16x16x32_bf16 v[80:83], v[216:219], v[192:195], v[80:83]
	v_mfma_f32_16x16x32_bf16 v[68:71], v[208:211], v[200:203], v[68:71]
	v_mfma_f32_16x16x32_bf16 v[64:67], v[216:219], v[200:203], v[64:67]
	s_setprio 1
	s_mov_b32 m0, s46
	v_lshl_add_u64 v[220:221], s[18:19], 0, v[134:135]
	s_barrier
	ds_read_b128 v[166:169], v148 offset:16384
	ds_read_b128 v[170:173], v148 offset:17408
	ds_read_b128 v[174:177], v148 offset:18432
	ds_read_b128 v[184:187], v148 offset:19456
	ds_read_b128 v[188:191], v148 offset:20480
	ds_read_b128 v[192:195], v148 offset:21504
	ds_read_b128 v[196:199], v148 offset:22528
	ds_read_b128 v[200:203], v148 offset:23552
	global_load_lds_dwordx4 v[220:221], off
	v_lshl_add_u64 v[222:223], s[18:19], 0, v[130:131]
	s_mov_b32 m0, s47
	s_nop 0
	global_load_lds_dwordx4 v[222:223], off
	s_barrier
	s_waitcnt lgkmcnt(0)
	s_setprio 0
	s_waitcnt lgkmcnt(0)
	v_mfma_f32_16x16x32_bf16 v[60:63], v[150:153], v[166:169], v[60:63]
	v_mfma_f32_16x16x32_bf16 v[56:59], v[158:161], v[166:169], v[56:59]
	v_mfma_f32_16x16x32_bf16 v[44:47], v[150:153], v[174:177], v[44:47]
	v_mfma_f32_16x16x32_bf16 v[40:43], v[158:161], v[174:177], v[40:43]
	v_mfma_f32_16x16x32_bf16 v[28:31], v[150:153], v[188:191], v[28:31]
	v_mfma_f32_16x16x32_bf16 v[24:27], v[158:161], v[188:191], v[24:27]
	v_mfma_f32_16x16x32_bf16 v[12:15], v[150:153], v[196:199], v[12:15]
	v_mfma_f32_16x16x32_bf16 v[8:11], v[158:161], v[196:199], v[8:11]
	v_mfma_f32_16x16x32_bf16 v[60:63], v[154:157], v[170:173], v[60:63]
	v_mfma_f32_16x16x32_bf16 v[56:59], v[162:165], v[170:173], v[56:59]
	v_mfma_f32_16x16x32_bf16 v[44:47], v[154:157], v[184:187], v[44:47]
	v_mfma_f32_16x16x32_bf16 v[40:43], v[162:165], v[184:187], v[40:43]
	v_mfma_f32_16x16x32_bf16 v[28:31], v[154:157], v[192:195], v[28:31]
	v_mfma_f32_16x16x32_bf16 v[24:27], v[162:165], v[192:195], v[24:27]
	v_mfma_f32_16x16x32_bf16 v[12:15], v[154:157], v[200:203], v[12:15]
	v_mfma_f32_16x16x32_bf16 v[8:11], v[162:165], v[200:203], v[8:11]
	s_setprio 1
	s_barrier
; #define PG8_STAGE(bufoff, gbase, voff) do { _Pragma("unroll") for (int _i = 0; _i < 2; ++_i) \
;         __builtin_amdgcn_global_load_lds((const unsigned*)((const char*)(gbase) + (voff)[_i]), (PG8_LAS unsigned*)(lds + (bufoff) + ldsw + _i * 8192), 16, 0, 0); } while (0)
; #define PG8_LDA(dst, b, h) do { _Pragma("unroll") for (int m = 0; m < 4; ++m) _Pragma("unroll") for (int k = 0; k < 2; ++k) dst[m][k] = *(const PG8_LAS bf16x8*)(lds + PG8_SA(b, h) + aoff + m * 2048 + k * 1024); } while (0)
; #define PG8_WAIT_V(n) asm volatile("s_waitcnt vmcnt(" #n ")" ::: "memory")
; template <class Epi, class Sched>
; __device__ __forceinline__ void gemm_phase(PG8_LAS unsigned char* lds, const Gemm g, const Sched& S, const Epi& E) {
;     ...
;         for (int t = 0; t < nt; t += 2) {
;             const bool last = (t == nt - 2);
;             const char* a1 = cA + (size_t)(t + 1) * kstep;
;             const char* a2 = last ? nA : cA + (size_t)(t + 2) * kstep; const char* b2 = last ? nB : cB + (size_t)(t + 2) * kstep;
;             const char* a3 = a2 + kstep; const char* b3 = b2 + kstep;
;             if (last && has_next) S.a_ready(nxt);
;             PG8_LDB(B0, 0, 0); PG8_SCHED; PG8_LDA(At, 0, 0); PG8_STAGE(PG8_SA(1, 1), a1 + hstep, voffA);
;             PG8_WAIT_L(8); PG8_BAR; PG8_WAIT_L(0); PG8_MMA(0, 0, At, B0); PG8_BAR; PG8_SCHED;
;             PG8_LDB(B1, 0, 1); PG8_STAGE(PG8_SB(0, 0), b2, voffB);
;             PG8_BAR; PG8_WAIT_L(0); PG8_MMA(0, 1, At, B1); PG8_BAR;
;             PG8_LDA(At, 0, 1); PG8_STAGE(PG8_SA(0, 0), a2, voffA);
;             PG8_BAR; PG8_WAIT_L(0); PG8_MMA(1, 0, At, B0); PG8_BAR; PG8_SCHED;
;             PG8_STAGE(PG8_SB(0, 1), b2 + hstep, voffB);
;             PG8_WAIT_V(6); PG8_BAR; PG8_MMA(1, 1, At, B1); PG8_BAR;
;             PG8_LDB(B0, 1, 0); PG8_SCHED; PG8_LDA(At, 1, 0); PG8_STAGE(PG8_SA(0, 1), a2 + hstep, voffA);
;             PG8_WAIT_L(8); PG8_BAR; PG8_WAIT_L(0); PG8_MMA(0, 0, At, B0); PG8_BAR; PG8_SCHED;
;             PG8_LDB(B1, 1, 1); PG8_STAGE(PG8_SB(1, 0), b3, voffB);
;             PG8_BAR; PG8_WAIT_L(0); PG8_MMA(0, 1, At, B1); PG8_BAR;
;             PG8_LDA(At, 1, 1); PG8_STAGE(PG8_SA(1, 0), a3, voffA);
;             PG8_BAR; PG8_WAIT_L(0); PG8_MMA(1, 0, At, B0); PG8_BAR; PG8_SCHED;
;             PG8_STAGE(PG8_SB(1, 1), b3 + hstep, voffB);
;             PG8_WAIT_V(6); PG8_BAR; PG8_MMA(1, 1, At, B1); PG8_BAR;
	s_add_u32 s80, s16, 0x40000
	s_addc_u32 s81, s17, 0
	s_add_i32 s82, s82, s21
	v_lshl_add_u64 v[150:151], s[80:81], 0, v[132:133]
	s_mov_b32 m0, s82
	s_nop 0
	global_load_lds_dwordx4 v[150:151], off
	v_lshl_add_u64 v[150:151], s[80:81], 0, v[128:129]
	s_add_i32 m0, s82, 0x2000
	s_nop 0
	global_load_lds_dwordx4 v[150:151], off
	s_waitcnt vmcnt(6)
	s_barrier
	s_setprio 0
	v_mfma_f32_16x16x32_bf16 v[52:55], v[204:207], v[166:169], v[52:55]
	v_mfma_f32_16x16x32_bf16 v[48:51], v[212:215], v[166:169], v[48:51]
	v_mfma_f32_16x16x32_bf16 v[36:39], v[204:207], v[174:177], v[36:39]
	v_mfma_f32_16x16x32_bf16 v[32:35], v[212:215], v[174:177], v[32:35]
	v_mfma_f32_16x16x32_bf16 v[20:23], v[204:207], v[188:191], v[20:23]
	v_mfma_f32_16x16x32_bf16 v[16:19], v[212:215], v[188:191], v[16:19]
	v_mfma_f32_16x16x32_bf16 v[4:7], v[204:207], v[196:199], v[4:7]
	v_mfma_f32_16x16x32_bf16 v[0:3], v[212:215], v[196:199], v[0:3]
	v_mfma_f32_16x16x32_bf16 v[52:55], v[208:211], v[170:173], v[52:55]
	v_mfma_f32_16x16x32_bf16 v[48:51], v[216:219], v[170:173], v[48:51]
	v_mfma_f32_16x16x32_bf16 v[36:39], v[208:211], v[184:187], v[36:39]
	v_mfma_f32_16x16x32_bf16 v[32:35], v[216:219], v[184:187], v[32:35]
	v_mfma_f32_16x16x32_bf16 v[20:23], v[208:211], v[192:195], v[20:23]
	v_mfma_f32_16x16x32_bf16 v[16:19], v[216:219], v[192:195], v[16:19]
	v_mfma_f32_16x16x32_bf16 v[4:7], v[208:211], v[200:203], v[4:7]
	v_mfma_f32_16x16x32_bf16 v[0:3], v[216:219], v[200:203], v[0:3]
	s_setprio 1
	s_add_i32 s80, 0, 0x18000
	v_add_u32_e32 v149, s80, v139
	s_barrier
	ds_read_b128 v[150:153], v149
	ds_read_b128 v[154:157], v149 offset:1024
	ds_read_b128 v[158:161], v149 offset:2048
	ds_read_b128 v[162:165], v149 offset:3072
	s_add_u32 s18, s18, 0x40000
	s_addc_u32 s19, s19, 0
	s_mov_b32 m0, s70
	v_lshl_add_u64 v[204:205], s[18:19], 0, v[134:135]
	ds_read_b128 v[166:169], v148 offset:32768
	ds_read_b128 v[170:173], v148 offset:33792
	ds_read_b128 v[174:177], v148 offset:34816
	ds_read_b128 v[184:187], v148 offset:35840
	ds_read_b128 v[188:191], v148 offset:36864
	ds_read_b128 v[192:195], v148 offset:37888
	ds_read_b128 v[196:199], v148 offset:38912
	ds_read_b128 v[200:203], v148 offset:39936
	global_load_lds_dwordx4 v[204:205], off
	v_lshl_add_u64 v[204:205], s[18:19], 0, v[130:131]
	s_mov_b32 m0, s71
	s_nop 0
	global_load_lds_dwordx4 v[204:205], off
	s_waitcnt lgkmcnt(8)
	s_barrier
	s_waitcnt lgkmcnt(0)
	s_setprio 0
	s_waitcnt lgkmcnt(0)
	v_mfma_f32_16x16x32_bf16 v[124:127], v[150:153], v[166:169], v[124:127]
	v_mfma_f32_16x16x32_bf16 v[120:123], v[158:161], v[166:169], v[120:123]
	v_mfma_f32_16x16x32_bf16 v[108:111], v[150:153], v[174:177], v[108:111]
	v_mfma_f32_16x16x32_bf16 v[104:107], v[158:161], v[174:177], v[104:107]
	v_mfma_f32_16x16x32_bf16 v[92:95], v[150:153], v[188:191], v[92:95]
	v_mfma_f32_16x16x32_bf16 v[88:91], v[158:161], v[188:191], v[88:91]
	v_mfma_f32_16x16x32_bf16 v[76:79], v[150:153], v[196:199], v[76:79]
	v_mfma_f32_16x16x32_bf16 v[72:75], v[158:161], v[196:199], v[72:75]
	v_mfma_f32_16x16x32_bf16 v[124:127], v[154:157], v[170:173], v[124:127]
	v_mfma_f32_16x16x32_bf16 v[120:123], v[162:165], v[170:173], v[120:123]
	v_mfma_f32_16x16x32_bf16 v[108:111], v[154:157], v[184:187], v[108:111]
	v_mfma_f32_16x16x32_bf16 v[104:107], v[162:165], v[184:187], v[104:107]
	v_mfma_f32_16x16x32_bf16 v[92:95], v[154:157], v[192:195], v[92:95]
	v_mfma_f32_16x16x32_bf16 v[88:91], v[162:165], v[192:195], v[88:91]
	v_mfma_f32_16x16x32_bf16 v[76:79], v[154:157], v[200:203], v[76:79]
	v_mfma_f32_16x16x32_bf16 v[72:75], v[162:165], v[200:203], v[72:75]
	s_setprio 1
	s_barrier
	s_add_i32 s18, 0, 0x1c000
	s_add_i32 s19, s80, s21
	v_add_u32_e32 v149, s18, v139
	v_lshl_add_u64 v[146:147], v[146:147], 0, s[38:39]
	s_mov_b32 m0, s19
	ds_read_b128 v[204:207], v149
	ds_read_b128 v[208:211], v149 offset:1024
	ds_read_b128 v[212:215], v149 offset:2048
	ds_read_b128 v[216:219], v149 offset:3072
	global_load_lds_dwordx4 v[146:147], off
	v_lshl_add_u64 v[146:147], v[178:179], 0, s[38:39]
	s_add_i32 m0, s19, 0x2000
	s_nop 0
	global_load_lds_dwordx4 v[146:147], off
	s_barrier
; template <class Epi, class Sched>
; __device__ __forceinline__ void gemm_phase(PG8_LAS unsigned char* lds, const Gemm g, const Sched& S, const Epi& E) {
;     ...
;         for (int t = 0; t < nt; t += 2) {
;             const bool last = (t == nt - 2);
;             const char* a1 = cA + (size_t)(t + 1) * kstep;
;             const char* a2 = last ? nA : cA + (size_t)(t + 2) * kstep; const char* b2 = last ? nB : cB + (size_t)(t + 2) * kstep;
;             const char* a3 = a2 + kstep; const char* b3 = b2 + kstep;
;             if (last && has_next) S.a_ready(nxt);
;             PG8_LDB(B0, 0, 0); PG8_SCHED; PG8_LDA(At, 0, 0); PG8_STAGE(PG8_SA(1, 1), a1 + hstep, voffA);
;             PG8_WAIT_L(8); PG8_BAR; PG8_WAIT_L(0); PG8_MMA(0, 0, At, B0); PG8_BAR; PG8_SCHED;
;             PG8_LDB(B1, 0, 1); PG8_STAGE(PG8_SB(0, 0), b2, voffB);
;             PG8_BAR; PG8_WAIT_L(0); PG8_MMA(0, 1, At, B1); PG8_BAR;
;             PG8_LDA(At, 0, 1); PG8_STAGE(PG8_SA(0, 0), a2, voffA);
;             PG8_BAR; PG8_WAIT_L(0); PG8_MMA(1, 0, At, B0); PG8_BAR; PG8_SCHED;
;             PG8_STAGE(PG8_SB(0, 1), b2 + hstep, voffB);
;             PG8_WAIT_V(6); PG8_BAR; PG8_MMA(1, 1, At, B1); PG8_BAR;
;             PG8_LDB(B0, 1, 0); PG8_SCHED; PG8_LDA(At, 1, 0); PG8_STAGE(PG8_SA(0, 1), a2 + hstep, voffA);
;             PG8_WAIT_L(8); PG8_BAR; PG8_WAIT_L(0); PG8_MMA(0, 0, At, B0); PG8_BAR; PG8_SCHED;
;             PG8_LDB(B1, 1, 1); PG8_STAGE(PG8_SB(1, 0), b3, voffB);
;             PG8_BAR; PG8_WAIT_L(0); PG8_MMA(0, 1, At, B1); PG8_BAR;
;             PG8_LDA(At, 1, 1); PG8_STAGE(PG8_SA(1, 0), a3, voffA);
;             PG8_BAR; PG8_WAIT_L(0); PG8_MMA(1, 0, At, B0); PG8_BAR; PG8_SCHED;
;             PG8_STAGE(PG8_SB(1, 1), b3 + hstep, voffB);
;             PG8_WAIT_V(6); PG8_BAR; PG8_MMA(1, 1, At, B1); PG8_BAR;
;     DI void operator()(const AccT& acc, const pg8::Unit& u, int wr, int wc, int fr, int fq) const {
;     ...
;         if (pn < 8) {
;             bf16_t* dst = (pn < 4 ? q : sg) + (pn & 3) * 256 + cl; const bool act = pn >= 4;
; #pragma unroll
;             for (int ai = 0; ai < 2; ++ai)
; #pragma unroll
;                 for (int m = 0; m < 4; ++m) { const size_t row = (size_t)pm * 256 + lrow0 + ai * 128 + m * 16;
; #pragma unroll
;                     for (int bj = 0; bj < 2; ++bj) { f32x4 v0 = acc[ai][bj][m][0], v1 = acc[ai][bj][m][1]; if (act) { v0 = silu4(v0); v1 = silu4(v1); }
	s_waitcnt lgkmcnt(0)
	s_setprio 0
	s_waitcnt lgkmcnt(0)
	v_mfma_f32_16x16x32_bf16 v[116:119], v[204:207], v[166:169], v[116:119]
	v_mfma_f32_16x16x32_bf16 v[112:115], v[212:215], v[166:169], v[112:115]
	v_mfma_f32_16x16x32_bf16 v[100:103], v[204:207], v[174:177], v[100:103]
	v_mfma_f32_16x16x32_bf16 v[96:99], v[212:215], v[174:177], v[96:99]
	v_mfma_f32_16x16x32_bf16 v[84:87], v[204:207], v[188:191], v[84:87]
	v_mfma_f32_16x16x32_bf16 v[80:83], v[212:215], v[188:191], v[80:83]
	v_mfma_f32_16x16x32_bf16 v[68:71], v[204:207], v[196:199], v[68:71]
	v_mfma_f32_16x16x32_bf16 v[64:67], v[212:215], v[196:199], v[64:67]
	v_mfma_f32_16x16x32_bf16 v[116:119], v[208:211], v[170:173], v[116:119]
	v_mfma_f32_16x16x32_bf16 v[112:115], v[216:219], v[170:173], v[112:115]
	v_mfma_f32_16x16x32_bf16 v[100:103], v[208:211], v[184:187], v[100:103]
	v_mfma_f32_16x16x32_bf16 v[96:99], v[216:219], v[184:187], v[96:99]
	v_mfma_f32_16x16x32_bf16 v[84:87], v[208:211], v[192:195], v[84:87]
	v_mfma_f32_16x16x32_bf16 v[80:83], v[216:219], v[192:195], v[80:83]
	v_mfma_f32_16x16x32_bf16 v[68:71], v[208:211], v[200:203], v[68:71]
	v_mfma_f32_16x16x32_bf16 v[64:67], v[216:219], v[200:203], v[64:67]
	s_setprio 1
	s_mov_b32 m0, s72
	v_lshl_add_u64 v[146:147], v[220:221], 0, s[38:39]
	s_barrier
	ds_read_b128 v[166:169], v148 offset:49152
	ds_read_b128 v[170:173], v148 offset:50176
	ds_read_b128 v[174:177], v148 offset:51200
	ds_read_b128 v[184:187], v148 offset:52224
	ds_read_b128 v[188:191], v148 offset:53248
	ds_read_b128 v[192:195], v148 offset:54272
	ds_read_b128 v[196:199], v148 offset:55296
	ds_read_b128 v[200:203], v148 offset:56320
	global_load_lds_dwordx4 v[146:147], off
	v_lshl_add_u64 v[146:147], v[222:223], 0, s[38:39]
	s_mov_b32 m0, s73
	s_nop 0
	global_load_lds_dwordx4 v[146:147], off
	s_barrier
	s_waitcnt lgkmcnt(0)
	s_setprio 0
	s_waitcnt lgkmcnt(0)
	v_mfma_f32_16x16x32_bf16 v[60:63], v[150:153], v[166:169], v[60:63]
	v_mfma_f32_16x16x32_bf16 v[56:59], v[158:161], v[166:169], v[56:59]
	v_mfma_f32_16x16x32_bf16 v[44:47], v[150:153], v[174:177], v[44:47]
	v_mfma_f32_16x16x32_bf16 v[40:43], v[158:161], v[174:177], v[40:43]
	v_mfma_f32_16x16x32_bf16 v[28:31], v[150:153], v[188:191], v[28:31]
	v_mfma_f32_16x16x32_bf16 v[24:27], v[158:161], v[188:191], v[24:27]
	v_mfma_f32_16x16x32_bf16 v[12:15], v[150:153], v[196:199], v[12:15]
	v_mfma_f32_16x16x32_bf16 v[8:11], v[158:161], v[196:199], v[8:11]
	v_mfma_f32_16x16x32_bf16 v[60:63], v[154:157], v[170:173], v[60:63]
	v_mfma_f32_16x16x32_bf16 v[56:59], v[162:165], v[170:173], v[56:59]
	v_mfma_f32_16x16x32_bf16 v[44:47], v[154:157], v[184:187], v[44:47]
	v_mfma_f32_16x16x32_bf16 v[40:43], v[162:165], v[184:187], v[40:43]
	v_mfma_f32_16x16x32_bf16 v[28:31], v[154:157], v[192:195], v[28:31]
	v_mfma_f32_16x16x32_bf16 v[24:27], v[162:165], v[192:195], v[24:27]
	v_mfma_f32_16x16x32_bf16 v[12:15], v[154:157], v[200:203], v[12:15]
	v_mfma_f32_16x16x32_bf16 v[8:11], v[162:165], v[200:203], v[8:11]
	s_setprio 1
	s_barrier
	s_add_u32 s16, s16, 0x40080
	s_addc_u32 s17, s17, 0
	s_add_i32 s18, s18, s21
	v_lshl_add_u64 v[146:147], s[16:17], 0, v[132:133]
	s_mov_b32 m0, s18
	s_nop 0
	global_load_lds_dwordx4 v[146:147], off
	v_lshl_add_u64 v[146:147], s[16:17], 0, v[128:129]
	s_add_i32 m0, s18, 0x2000
	s_nop 0
	global_load_lds_dwordx4 v[146:147], off
	s_waitcnt vmcnt(6)
	s_barrier
	s_setprio 0
	v_mfma_f32_16x16x32_bf16 v[52:55], v[204:207], v[166:169], v[52:55]
	v_mfma_f32_16x16x32_bf16 v[48:51], v[212:215], v[166:169], v[48:51]
	v_mfma_f32_16x16x32_bf16 v[36:39], v[204:207], v[174:177], v[36:39]
	v_mfma_f32_16x16x32_bf16 v[32:35], v[212:215], v[174:177], v[32:35]
	v_mfma_f32_16x16x32_bf16 v[20:23], v[204:207], v[188:191], v[20:23]
	v_mfma_f32_16x16x32_bf16 v[16:19], v[212:215], v[188:191], v[16:19]
	v_mfma_f32_16x16x32_bf16 v[4:7], v[204:207], v[196:199], v[4:7]
	v_mfma_f32_16x16x32_bf16 v[0:3], v[212:215], v[196:199], v[0:3]
	v_mfma_f32_16x16x32_bf16 v[52:55], v[208:211], v[170:173], v[52:55]
	v_mfma_f32_16x16x32_bf16 v[48:51], v[216:219], v[170:173], v[48:51]
	v_mfma_f32_16x16x32_bf16 v[36:39], v[208:211], v[184:187], v[36:39]
	v_mfma_f32_16x16x32_bf16 v[32:35], v[216:219], v[184:187], v[32:35]
	v_mfma_f32_16x16x32_bf16 v[20:23], v[208:211], v[192:195], v[20:23]
	v_mfma_f32_16x16x32_bf16 v[16:19], v[216:219], v[192:195], v[16:19]
	v_mfma_f32_16x16x32_bf16 v[4:7], v[208:211], v[200:203], v[4:7]
	v_mfma_f32_16x16x32_bf16 v[0:3], v[216:219], v[200:203], v[0:3]
	s_setprio 1
	s_add_i32 s79, s79, 2
	s_add_u32 s14, s14, 0x100
	s_addc_u32 s15, s15, 0
	s_add_u32 s77, s77, 0x100
	s_addc_u32 s78, s78, 0
	s_cmp_gt_u32 s79, 13
	s_barrier
	s_cbranch_scc0 .LBB0_648
	s_cmp_gt_i32 s7, 7
	s_mov_b64 s[14:15], -1
	s_cbranch_scc0 .LBB0_655
	s_cmpk_gt_i32 s6, 0x7f
	s_mov_b64 s[16:17], -1
	s_cbranch_scc0 .LBB0_652
	s_mul_i32 s1, s6, 0x1100
	s_add_i32 s14, s1, 0xfff79000
	s_mov_b64 s[16:17], 0

; #define PG8_STAGE(bufoff, gbase, voff) do { _Pragma("unroll") for (int _i = 0; _i < 2; ++_i) \
;         __builtin_amdgcn_global_load_lds((const unsigned*)((const char*)(gbase) + (voff)[_i]), (PG8_LAS unsigned*)(lds + (bufoff) + ldsw + _i * 8192), 16, 0, 0); } while (0)
; #define PG8_LDA(dst, b, h) do { _Pragma("unroll") for (int m = 0; m < 4; ++m) _Pragma("unroll") for (int k = 0; k < 2; ++k) dst[m][k] = *(const PG8_LAS bf16x8*)(lds + PG8_SA(b, h) + aoff + m * 2048 + k * 1024); } while (0)
; #define PG8_WAIT_V(n) asm volatile("s_waitcnt vmcnt(" #n ")" ::: "memory")
; template <class Epi, class Sched>
; __device__ __forceinline__ void gemm_phase(PG8_LAS unsigned char* lds, const Gemm g, const Sched& S, const Epi& E) {
;     ...
;         for (int t = 0; t < nt; t += 2) {
;             const bool last = (t == nt - 2);
;             const char* a1 = cA + (size_t)(t + 1) * kstep;
;             const char* a2 = last ? nA : cA + (size_t)(t + 2) * kstep; const char* b2 = last ? nB : cB + (size_t)(t + 2) * kstep;
;             const char* a3 = a2 + kstep; const char* b3 = b2 + kstep;
;             if (last && has_next) S.a_ready(nxt);
;             PG8_LDB(B0, 0, 0); PG8_SCHED; PG8_LDA(At, 0, 0); PG8_STAGE(PG8_SA(1, 1), a1 + hstep, voffA);
;             PG8_WAIT_L(8); PG8_BAR; PG8_WAIT_L(0); PG8_MMA(0, 0, At, B0); PG8_BAR; PG8_SCHED;
;             PG8_LDB(B1, 0, 1); PG8_STAGE(PG8_SB(0, 0), b2, voffB);
;             PG8_BAR; PG8_WAIT_L(0); PG8_MMA(0, 1, At, B1); PG8_BAR;
;             PG8_LDA(At, 0, 1); PG8_STAGE(PG8_SA(0, 0), a2, voffA);
;             PG8_BAR; PG8_WAIT_L(0); PG8_MMA(1, 0, At, B0); PG8_BAR; PG8_SCHED;
;             PG8_STAGE(PG8_SB(0, 1), b2 + hstep, voffB);
;             PG8_WAIT_V(6); PG8_BAR; PG8_MMA(1, 1, At, B1); PG8_BAR;
;             PG8_LDB(B0, 1, 0); PG8_SCHED; PG8_LDA(At, 1, 0); PG8_STAGE(PG8_SA(0, 1), a2 + hstep, voffA);
;             PG8_WAIT_L(8); PG8_BAR; PG8_WAIT_L(0); PG8_MMA(0, 0, At, B0); PG8_BAR; PG8_SCHED;
;             PG8_LDB(B1, 1, 1); PG8_STAGE(PG8_SB(1, 0), b3, voffB);
;             PG8_BAR; PG8_WAIT_L(0); PG8_MMA(0, 1, At, B1); PG8_BAR;
;             PG8_LDA(At, 1, 1); PG8_STAGE(PG8_SA(1, 0), a3, voffA);
;             PG8_BAR; PG8_WAIT_L(0); PG8_MMA(1, 0, At, B0); PG8_BAR; PG8_SCHED;
;             PG8_STAGE(PG8_SB(1, 1), b3 + hstep, voffB);
;             PG8_WAIT_V(6); PG8_BAR; PG8_MMA(1, 1, At, B1); PG8_BAR;
.LBB0_912:
	s_add_u32 s16, s14, 0xfffc0080
	s_addc_u32 s17, s15, -1
	s_add_i32 s79, 0, 0x10000
	v_add_u32_e32 v142, s79, v144
	ds_read_b128 v[146:149], v142
	ds_read_b128 v[150:153], v142 offset:1024
	ds_read_b128 v[154:157], v142 offset:2048
	ds_read_b128 v[158:161], v142 offset:3072
	s_cmp_eq_u32 s78, 12
	s_cselect_b32 s19, s7, s17
	s_cselect_b32 s18, s74, s16
	s_cselect_b32 s17, s5, s77
	s_cselect_b32 s16, s75, s76
	v_lshl_add_u64 v[142:143], s[14:15], 0, v[138:139]
	s_add_i32 m0, s46, 0xc000
	ds_read_b128 v[162:165], v145
	ds_read_b128 v[166:169], v145 offset:1024
	ds_read_b128 v[170:173], v145 offset:2048
	ds_read_b128 v[174:177], v145 offset:3072
	ds_read_b128 v[184:187], v145 offset:4096
	ds_read_b128 v[188:191], v145 offset:5120
	ds_read_b128 v[192:195], v145 offset:6144
	ds_read_b128 v[196:199], v145 offset:7168
	global_load_lds_dwordx4 v[142:143], off
	v_lshl_add_u64 v[142:143], s[14:15], 0, v[140:141]
	s_add_i32 m0, s46, 0xe000
	s_nop 0
	global_load_lds_dwordx4 v[142:143], off
	s_waitcnt lgkmcnt(8)
	s_barrier
	s_waitcnt lgkmcnt(0)
	s_setprio 0
	s_waitcnt lgkmcnt(0)
	v_mfma_f32_16x16x32_bf16 v[124:127], v[146:149], v[162:165], v[124:127]
	v_mfma_f32_16x16x32_bf16 v[120:123], v[154:157], v[162:165], v[120:123]
	v_mfma_f32_16x16x32_bf16 v[116:119], v[146:149], v[170:173], v[116:119]
	v_mfma_f32_16x16x32_bf16 v[108:111], v[154:157], v[170:173], v[108:111]
	v_mfma_f32_16x16x32_bf16 v[100:103], v[146:149], v[184:187], v[100:103]
	v_mfma_f32_16x16x32_bf16 v[92:95], v[154:157], v[184:187], v[92:95]
	v_mfma_f32_16x16x32_bf16 v[84:87], v[146:149], v[192:195], v[84:87]
	v_mfma_f32_16x16x32_bf16 v[76:79], v[154:157], v[192:195], v[76:79]
	v_mfma_f32_16x16x32_bf16 v[124:127], v[150:153], v[166:169], v[124:127]
	v_mfma_f32_16x16x32_bf16 v[120:123], v[158:161], v[166:169], v[120:123]
	v_mfma_f32_16x16x32_bf16 v[116:119], v[150:153], v[174:177], v[116:119]
	v_mfma_f32_16x16x32_bf16 v[108:111], v[158:161], v[174:177], v[108:111]
	v_mfma_f32_16x16x32_bf16 v[100:103], v[150:153], v[188:191], v[100:103]
	v_mfma_f32_16x16x32_bf16 v[92:95], v[158:161], v[188:191], v[92:95]
	v_mfma_f32_16x16x32_bf16 v[84:87], v[150:153], v[196:199], v[84:87]
	v_mfma_f32_16x16x32_bf16 v[76:79], v[158:161], v[196:199], v[76:79]
	s_setprio 1
	s_barrier
	s_add_i32 s82, 0, 0x14000
	v_add_u32_e32 v142, s82, v144
	s_add_i32 s79, s79, s21
	ds_read_b128 v[200:203], v142
	ds_read_b128 v[204:207], v142 offset:1024
	ds_read_b128 v[208:211], v142 offset:2048
	ds_read_b128 v[212:215], v142 offset:3072
	v_lshl_add_u64 v[142:143], s[16:17], 0, v[180:181]
	s_mov_b32 m0, s79
	v_lshl_add_u64 v[178:179], s[16:17], 0, v[128:129]
	global_load_lds_dwordx4 v[142:143], off
	s_add_i32 m0, s79, 0x2000
	s_nop 0
	global_load_lds_dwordx4 v[178:179], off
	s_barrier
	s_waitcnt lgkmcnt(0)
	s_setprio 0
	s_waitcnt lgkmcnt(0)
	v_mfma_f32_16x16x32_bf16 v[112:115], v[200:203], v[162:165], v[112:115]
	v_mfma_f32_16x16x32_bf16 v[104:107], v[208:211], v[162:165], v[104:107]
	v_mfma_f32_16x16x32_bf16 v[96:99], v[200:203], v[170:173], v[96:99]
	v_mfma_f32_16x16x32_bf16 v[88:91], v[208:211], v[170:173], v[88:91]
	v_mfma_f32_16x16x32_bf16 v[80:83], v[200:203], v[184:187], v[80:83]
	v_mfma_f32_16x16x32_bf16 v[72:75], v[208:211], v[184:187], v[72:75]
	v_mfma_f32_16x16x32_bf16 v[68:71], v[200:203], v[192:195], v[68:71]
	v_mfma_f32_16x16x32_bf16 v[64:67], v[208:211], v[192:195], v[64:67]
	v_mfma_f32_16x16x32_bf16 v[112:115], v[204:207], v[166:169], v[112:115]
	v_mfma_f32_16x16x32_bf16 v[104:107], v[212:215], v[166:169], v[104:107]
	v_mfma_f32_16x16x32_bf16 v[96:99], v[204:207], v[174:177], v[96:99]
	v_mfma_f32_16x16x32_bf16 v[88:91], v[212:215], v[174:177], v[88:91]
	v_mfma_f32_16x16x32_bf16 v[80:83], v[204:207], v[188:191], v[80:83]
	v_mfma_f32_16x16x32_bf16 v[72:75], v[212:215], v[188:191], v[72:75]
	v_mfma_f32_16x16x32_bf16 v[68:71], v[204:207], v[196:199], v[68:71]
	v_mfma_f32_16x16x32_bf16 v[64:67], v[212:215], v[196:199], v[64:67]
	s_setprio 1
	s_mov_b32 m0, s46
	v_lshl_add_u64 v[216:217], s[18:19], 0, v[132:133]
	s_barrier
	ds_read_b128 v[162:165], v145 offset:16384
	ds_read_b128 v[166:169], v145 offset:17408
	ds_read_b128 v[170:173], v145 offset:18432
	ds_read_b128 v[174:177], v145 offset:19456
	ds_read_b128 v[184:187], v145 offset:20480
	ds_read_b128 v[188:191], v145 offset:21504
	ds_read_b128 v[192:195], v145 offset:22528
	ds_read_b128 v[196:199], v145 offset:23552
	global_load_lds_dwordx4 v[216:217], off
	v_lshl_add_u64 v[218:219], s[18:19], 0, v[130:131]
	s_mov_b32 m0, s47
	s_nop 0
	global_load_lds_dwordx4 v[218:219], off
	s_barrier
	s_waitcnt lgkmcnt(0)
	s_setprio 0
	s_waitcnt lgkmcnt(0)
	v_mfma_f32_16x16x32_bf16 v[60:63], v[146:149], v[162:165], v[60:63]
	v_mfma_f32_16x16x32_bf16 v[56:59], v[154:157], v[162:165], v[56:59]
	v_mfma_f32_16x16x32_bf16 v[52:55], v[146:149], v[170:173], v[52:55]
	v_mfma_f32_16x16x32_bf16 v[44:47], v[154:157], v[170:173], v[44:47]
	v_mfma_f32_16x16x32_bf16 v[36:39], v[146:149], v[184:187], v[36:39]
	v_mfma_f32_16x16x32_bf16 v[28:31], v[154:157], v[184:187], v[28:31]
	v_mfma_f32_16x16x32_bf16 v[20:23], v[146:149], v[192:195], v[20:23]
	v_mfma_f32_16x16x32_bf16 v[12:15], v[154:157], v[192:195], v[12:15]
	v_mfma_f32_16x16x32_bf16 v[60:63], v[150:153], v[166:169], v[60:63]
	v_mfma_f32_16x16x32_bf16 v[56:59], v[158:161], v[166:169], v[56:59]
	v_mfma_f32_16x16x32_bf16 v[52:55], v[150:153], v[174:177], v[52:55]
	v_mfma_f32_16x16x32_bf16 v[44:47], v[158:161], v[174:177], v[44:47]
	v_mfma_f32_16x16x32_bf16 v[36:39], v[150:153], v[188:191], v[36:39]
	v_mfma_f32_16x16x32_bf16 v[28:31], v[158:161], v[188:191], v[28:31]
	v_mfma_f32_16x16x32_bf16 v[20:23], v[150:153], v[196:199], v[20:23]
	v_mfma_f32_16x16x32_bf16 v[12:15], v[158:161], v[196:199], v[12:15]
	s_setprio 1
	s_barrier
; #define PG8_STAGE(bufoff, gbase, voff) do { _Pragma("unroll") for (int _i = 0; _i < 2; ++_i) \
;         __builtin_amdgcn_global_load_lds((const unsigned*)((const char*)(gbase) + (voff)[_i]), (PG8_LAS unsigned*)(lds + (bufoff) + ldsw + _i * 8192), 16, 0, 0); } while (0)
; #define PG8_LDA(dst, b, h) do { _Pragma("unroll") for (int m = 0; m < 4; ++m) _Pragma("unroll") for (int k = 0; k < 2; ++k) dst[m][k] = *(const PG8_LAS bf16x8*)(lds + PG8_SA(b, h) + aoff + m * 2048 + k * 1024); } while (0)
; #define PG8_WAIT_V(n) asm volatile("s_waitcnt vmcnt(" #n ")" ::: "memory")
; template <class Epi, class Sched>
; __device__ __forceinline__ void gemm_phase(PG8_LAS unsigned char* lds, const Gemm g, const Sched& S, const Epi& E) {
;     ...
;         for (int t = 0; t < nt; t += 2) {
;             const bool last = (t == nt - 2);
;             const char* a1 = cA + (size_t)(t + 1) * kstep;
;             const char* a2 = last ? nA : cA + (size_t)(t + 2) * kstep; const char* b2 = last ? nB : cB + (size_t)(t + 2) * kstep;
;             const char* a3 = a2 + kstep; const char* b3 = b2 + kstep;
;             if (last && has_next) S.a_ready(nxt);
;             PG8_LDB(B0, 0, 0); PG8_SCHED; PG8_LDA(At, 0, 0); PG8_STAGE(PG8_SA(1, 1), a1 + hstep, voffA);
;             PG8_WAIT_L(8); PG8_BAR; PG8_WAIT_L(0); PG8_MMA(0, 0, At, B0); PG8_BAR; PG8_SCHED;
;             PG8_LDB(B1, 0, 1); PG8_STAGE(PG8_SB(0, 0), b2, voffB);
;             PG8_BAR; PG8_WAIT_L(0); PG8_MMA(0, 1, At, B1); PG8_BAR;
;             PG8_LDA(At, 0, 1); PG8_STAGE(PG8_SA(0, 0), a2, voffA);
;             PG8_BAR; PG8_WAIT_L(0); PG8_MMA(1, 0, At, B0); PG8_BAR; PG8_SCHED;
;             PG8_STAGE(PG8_SB(0, 1), b2 + hstep, voffB);
;             PG8_WAIT_V(6); PG8_BAR; PG8_MMA(1, 1, At, B1); PG8_BAR;
;             PG8_LDB(B0, 1, 0); PG8_SCHED; PG8_LDA(At, 1, 0); PG8_STAGE(PG8_SA(0, 1), a2 + hstep, voffA);
;             PG8_WAIT_L(8); PG8_BAR; PG8_WAIT_L(0); PG8_MMA(0, 0, At, B0); PG8_BAR; PG8_SCHED;
;             PG8_LDB(B1, 1, 1); PG8_STAGE(PG8_SB(1, 0), b3, voffB);
;             PG8_BAR; PG8_WAIT_L(0); PG8_MMA(0, 1, At, B1); PG8_BAR;
;             PG8_LDA(At, 1, 1); PG8_STAGE(PG8_SA(1, 0), a3, voffA);
;             PG8_BAR; PG8_WAIT_L(0); PG8_MMA(1, 0, At, B0); PG8_BAR; PG8_SCHED;
;             PG8_STAGE(PG8_SB(1, 1), b3 + hstep, voffB);
;             PG8_WAIT_V(6); PG8_BAR; PG8_MMA(1, 1, At, B1); PG8_BAR;
	s_add_u32 s80, s16, 0x40000
	s_addc_u32 s81, s17, 0
	s_add_i32 s79, s82, s21
	v_lshl_add_u64 v[146:147], s[80:81], 0, v[180:181]
	s_mov_b32 m0, s79
	s_nop 0
	global_load_lds_dwordx4 v[146:147], off
	v_lshl_add_u64 v[146:147], s[80:81], 0, v[128:129]
	s_add_i32 m0, s79, 0x2000
	s_nop 0
	global_load_lds_dwordx4 v[146:147], off
	s_waitcnt vmcnt(6)
	s_barrier
	s_setprio 0
	v_mfma_f32_16x16x32_bf16 v[48:51], v[200:203], v[162:165], v[48:51]
	v_mfma_f32_16x16x32_bf16 v[40:43], v[208:211], v[162:165], v[40:43]
	v_mfma_f32_16x16x32_bf16 v[32:35], v[200:203], v[170:173], v[32:35]
	v_mfma_f32_16x16x32_bf16 v[24:27], v[208:211], v[170:173], v[24:27]
	v_mfma_f32_16x16x32_bf16 v[16:19], v[200:203], v[184:187], v[16:19]
	v_mfma_f32_16x16x32_bf16 v[8:11], v[208:211], v[184:187], v[8:11]
	v_mfma_f32_16x16x32_bf16 v[4:7], v[200:203], v[192:195], v[4:7]
	v_mfma_f32_16x16x32_bf16 v[0:3], v[208:211], v[192:195], v[0:3]
	v_mfma_f32_16x16x32_bf16 v[48:51], v[204:207], v[166:169], v[48:51]
	v_mfma_f32_16x16x32_bf16 v[40:43], v[212:215], v[166:169], v[40:43]
	v_mfma_f32_16x16x32_bf16 v[32:35], v[204:207], v[174:177], v[32:35]
	v_mfma_f32_16x16x32_bf16 v[24:27], v[212:215], v[174:177], v[24:27]
	v_mfma_f32_16x16x32_bf16 v[16:19], v[204:207], v[188:191], v[16:19]
	v_mfma_f32_16x16x32_bf16 v[8:11], v[212:215], v[188:191], v[8:11]
	v_mfma_f32_16x16x32_bf16 v[4:7], v[204:207], v[196:199], v[4:7]
	v_mfma_f32_16x16x32_bf16 v[0:3], v[212:215], v[196:199], v[0:3]
	s_setprio 1
	s_add_i32 s79, 0, 0x18000
	v_add_u32_e32 v158, s79, v144
	s_barrier
	ds_read_b128 v[146:149], v158
	ds_read_b128 v[150:153], v158 offset:1024
	ds_read_b128 v[154:157], v158 offset:2048
	ds_read_b128 v[158:161], v158 offset:3072
	s_add_u32 s18, s18, 0x40000
	s_addc_u32 s19, s19, 0
	s_mov_b32 m0, s69
	v_lshl_add_u64 v[200:201], s[18:19], 0, v[132:133]
	ds_read_b128 v[162:165], v145 offset:32768
	ds_read_b128 v[166:169], v145 offset:33792
	ds_read_b128 v[170:173], v145 offset:34816
	ds_read_b128 v[174:177], v145 offset:35840
	ds_read_b128 v[184:187], v145 offset:36864
	ds_read_b128 v[188:191], v145 offset:37888
	ds_read_b128 v[192:195], v145 offset:38912
	ds_read_b128 v[196:199], v145 offset:39936
	global_load_lds_dwordx4 v[200:201], off
	v_lshl_add_u64 v[200:201], s[18:19], 0, v[130:131]
	s_mov_b32 m0, s70
	s_nop 0
	global_load_lds_dwordx4 v[200:201], off
	s_waitcnt lgkmcnt(8)
	s_barrier
	s_waitcnt lgkmcnt(0)
	s_setprio 0
	s_waitcnt lgkmcnt(0)
	v_mfma_f32_16x16x32_bf16 v[124:127], v[146:149], v[162:165], v[124:127]
	v_mfma_f32_16x16x32_bf16 v[120:123], v[154:157], v[162:165], v[120:123]
	v_mfma_f32_16x16x32_bf16 v[116:119], v[146:149], v[170:173], v[116:119]
	v_mfma_f32_16x16x32_bf16 v[108:111], v[154:157], v[170:173], v[108:111]
	v_mfma_f32_16x16x32_bf16 v[100:103], v[146:149], v[184:187], v[100:103]
	v_mfma_f32_16x16x32_bf16 v[92:95], v[154:157], v[184:187], v[92:95]
	v_mfma_f32_16x16x32_bf16 v[84:87], v[146:149], v[192:195], v[84:87]
	v_mfma_f32_16x16x32_bf16 v[76:79], v[154:157], v[192:195], v[76:79]
	v_mfma_f32_16x16x32_bf16 v[124:127], v[150:153], v[166:169], v[124:127]
	v_mfma_f32_16x16x32_bf16 v[120:123], v[158:161], v[166:169], v[120:123]
	v_mfma_f32_16x16x32_bf16 v[116:119], v[150:153], v[174:177], v[116:119]
	v_mfma_f32_16x16x32_bf16 v[108:111], v[158:161], v[174:177], v[108:111]
	v_mfma_f32_16x16x32_bf16 v[100:103], v[150:153], v[188:191], v[100:103]
	v_mfma_f32_16x16x32_bf16 v[92:95], v[158:161], v[188:191], v[92:95]
	v_mfma_f32_16x16x32_bf16 v[84:87], v[150:153], v[196:199], v[84:87]
	v_mfma_f32_16x16x32_bf16 v[76:79], v[158:161], v[196:199], v[76:79]
	s_setprio 1
	s_barrier
	s_add_i32 s18, 0, 0x1c000
	s_add_i32 s19, s79, s21
	v_add_u32_e32 v212, s18, v144
	v_lshl_add_u64 v[142:143], v[142:143], 0, s[38:39]
	s_mov_b32 m0, s19
	ds_read_b128 v[200:203], v212
	ds_read_b128 v[204:207], v212 offset:1024
	ds_read_b128 v[208:211], v212 offset:2048
	ds_read_b128 v[212:215], v212 offset:3072
	global_load_lds_dwordx4 v[142:143], off
	v_lshl_add_u64 v[142:143], v[178:179], 0, s[38:39]
	s_add_i32 m0, s19, 0x2000
	s_nop 0
	global_load_lds_dwordx4 v[142:143], off
	s_barrier
	s_waitcnt lgkmcnt(0)
	s_setprio 0
	s_waitcnt lgkmcnt(0)
	v_mfma_f32_16x16x32_bf16 v[112:115], v[200:203], v[162:165], v[112:115]
	v_mfma_f32_16x16x32_bf16 v[104:107], v[208:211], v[162:165], v[104:107]
	v_mfma_f32_16x16x32_bf16 v[96:99], v[200:203], v[170:173], v[96:99]
	v_mfma_f32_16x16x32_bf16 v[88:91], v[208:211], v[170:173], v[88:91]
	v_mfma_f32_16x16x32_bf16 v[80:83], v[200:203], v[184:187], v[80:83]
	v_mfma_f32_16x16x32_bf16 v[72:75], v[208:211], v[184:187], v[72:75]
	v_mfma_f32_16x16x32_bf16 v[68:71], v[200:203], v[192:195], v[68:71]
	v_mfma_f32_16x16x32_bf16 v[64:67], v[208:211], v[192:195], v[64:67]
	v_mfma_f32_16x16x32_bf16 v[112:115], v[204:207], v[166:169], v[112:115]
	v_mfma_f32_16x16x32_bf16 v[104:107], v[212:215], v[166:169], v[104:107]
	v_mfma_f32_16x16x32_bf16 v[96:99], v[204:207], v[174:177], v[96:99]
	v_mfma_f32_16x16x32_bf16 v[88:91], v[212:215], v[174:177], v[88:91]
	v_mfma_f32_16x16x32_bf16 v[80:83], v[204:207], v[188:191], v[80:83]
	v_mfma_f32_16x16x32_bf16 v[72:75], v[212:215], v[188:191], v[72:75]
	v_mfma_f32_16x16x32_bf16 v[68:71], v[204:207], v[196:199], v[68:71]
	v_mfma_f32_16x16x32_bf16 v[64:67], v[212:215], v[196:199], v[64:67]
	s_setprio 1
	s_mov_b32 m0, s71
	v_lshl_add_u64 v[142:143], v[216:217], 0, s[38:39]
	s_barrier
	ds_read_b128 v[162:165], v145 offset:49152
	ds_read_b128 v[166:169], v145 offset:50176
	ds_read_b128 v[170:173], v145 offset:51200
	ds_read_b128 v[174:177], v145 offset:52224
	ds_read_b128 v[184:187], v145 offset:53248
	ds_read_b128 v[188:191], v145 offset:54272
	ds_read_b128 v[192:195], v145 offset:55296
	ds_read_b128 v[196:199], v145 offset:56320
	global_load_lds_dwordx4 v[142:143], off
	v_lshl_add_u64 v[142:143], v[218:219], 0, s[38:39]
	s_mov_b32 m0, s72
	s_nop 0
	global_load_lds_dwordx4 v[142:143], off
	s_barrier
; #define PG8_STAGE(bufoff, gbase, voff) do { _Pragma("unroll") for (int _i = 0; _i < 2; ++_i) \
;         __builtin_amdgcn_global_load_lds((const unsigned*)((const char*)(gbase) + (voff)[_i]), (PG8_LAS unsigned*)(lds + (bufoff) + ldsw + _i * 8192), 16, 0, 0); } while (0)
; #define PG8_LDA(dst, b, h) do { _Pragma("unroll") for (int m = 0; m < 4; ++m) _Pragma("unroll") for (int k = 0; k < 2; ++k) dst[m][k] = *(const PG8_LAS bf16x8*)(lds + PG8_SA(b, h) + aoff + m * 2048 + k * 1024); } while (0)
; #define PG8_WAIT_V(n) asm volatile("s_waitcnt vmcnt(" #n ")" ::: "memory")
; template <class Epi, class Sched>
; __device__ __forceinline__ void gemm_phase(PG8_LAS unsigned char* lds, const Gemm g, const Sched& S, const Epi& E) {
;     ...
;         for (int t = 0; t < nt; t += 2) {
;             const bool last = (t == nt - 2);
;             const char* a1 = cA + (size_t)(t + 1) * kstep;
;             const char* a2 = last ? nA : cA + (size_t)(t + 2) * kstep; const char* b2 = last ? nB : cB + (size_t)(t + 2) * kstep;
;             const char* a3 = a2 + kstep; const char* b3 = b2 + kstep;
;             if (last && has_next) S.a_ready(nxt);
;             PG8_LDB(B0, 0, 0); PG8_SCHED; PG8_LDA(At, 0, 0); PG8_STAGE(PG8_SA(1, 1), a1 + hstep, voffA);
;             PG8_WAIT_L(8); PG8_BAR; PG8_WAIT_L(0); PG8_MMA(0, 0, At, B0); PG8_BAR; PG8_SCHED;
;             PG8_LDB(B1, 0, 1); PG8_STAGE(PG8_SB(0, 0), b2, voffB);
;             PG8_BAR; PG8_WAIT_L(0); PG8_MMA(0, 1, At, B1); PG8_BAR;
;             PG8_LDA(At, 0, 1); PG8_STAGE(PG8_SA(0, 0), a2, voffA);
;             PG8_BAR; PG8_WAIT_L(0); PG8_MMA(1, 0, At, B0); PG8_BAR; PG8_SCHED;
;             PG8_STAGE(PG8_SB(0, 1), b2 + hstep, voffB);
;             PG8_WAIT_V(6); PG8_BAR; PG8_MMA(1, 1, At, B1); PG8_BAR;
;             PG8_LDB(B0, 1, 0); PG8_SCHED; PG8_LDA(At, 1, 0); PG8_STAGE(PG8_SA(0, 1), a2 + hstep, voffA);
;             PG8_WAIT_L(8); PG8_BAR; PG8_WAIT_L(0); PG8_MMA(0, 0, At, B0); PG8_BAR; PG8_SCHED;
;             PG8_LDB(B1, 1, 1); PG8_STAGE(PG8_SB(1, 0), b3, voffB);
;             PG8_BAR; PG8_WAIT_L(0); PG8_MMA(0, 1, At, B1); PG8_BAR;
;             PG8_LDA(At, 1, 1); PG8_STAGE(PG8_SA(1, 0), a3, voffA);
;             PG8_BAR; PG8_WAIT_L(0); PG8_MMA(1, 0, At, B0); PG8_BAR; PG8_SCHED;
;             PG8_STAGE(PG8_SB(1, 1), b3 + hstep, voffB);
;             PG8_WAIT_V(6); PG8_BAR; PG8_MMA(1, 1, At, B1); PG8_BAR;
	s_waitcnt lgkmcnt(0)
	s_setprio 0
	s_waitcnt lgkmcnt(0)
	v_mfma_f32_16x16x32_bf16 v[60:63], v[146:149], v[162:165], v[60:63]
	v_mfma_f32_16x16x32_bf16 v[56:59], v[154:157], v[162:165], v[56:59]
	v_mfma_f32_16x16x32_bf16 v[52:55], v[146:149], v[170:173], v[52:55]
	v_mfma_f32_16x16x32_bf16 v[44:47], v[154:157], v[170:173], v[44:47]
	v_mfma_f32_16x16x32_bf16 v[36:39], v[146:149], v[184:187], v[36:39]
	v_mfma_f32_16x16x32_bf16 v[28:31], v[154:157], v[184:187], v[28:31]
	v_mfma_f32_16x16x32_bf16 v[20:23], v[146:149], v[192:195], v[20:23]
	v_mfma_f32_16x16x32_bf16 v[12:15], v[154:157], v[192:195], v[12:15]
	v_mfma_f32_16x16x32_bf16 v[60:63], v[150:153], v[166:169], v[60:63]
	v_mfma_f32_16x16x32_bf16 v[56:59], v[158:161], v[166:169], v[56:59]
	v_mfma_f32_16x16x32_bf16 v[52:55], v[150:153], v[174:177], v[52:55]
	v_mfma_f32_16x16x32_bf16 v[44:47], v[158:161], v[174:177], v[44:47]
	v_mfma_f32_16x16x32_bf16 v[36:39], v[150:153], v[188:191], v[36:39]
	v_mfma_f32_16x16x32_bf16 v[28:31], v[158:161], v[188:191], v[28:31]
	v_mfma_f32_16x16x32_bf16 v[20:23], v[150:153], v[196:199], v[20:23]
	v_mfma_f32_16x16x32_bf16 v[12:15], v[158:161], v[196:199], v[12:15]
	s_setprio 1
	s_barrier
	s_add_u32 s16, s16, 0x40080
	s_addc_u32 s17, s17, 0
	s_add_i32 s18, s18, s21
	v_lshl_add_u64 v[142:143], s[16:17], 0, v[180:181]
	s_mov_b32 m0, s18
	s_nop 0
	global_load_lds_dwordx4 v[142:143], off
	v_lshl_add_u64 v[142:143], s[16:17], 0, v[128:129]
	s_add_i32 m0, s18, 0x2000
	s_nop 0
	global_load_lds_dwordx4 v[142:143], off
	s_waitcnt vmcnt(6)
	s_barrier
	s_setprio 0
	v_mfma_f32_16x16x32_bf16 v[48:51], v[200:203], v[162:165], v[48:51]
	v_mfma_f32_16x16x32_bf16 v[40:43], v[208:211], v[162:165], v[40:43]
	v_mfma_f32_16x16x32_bf16 v[32:35], v[200:203], v[170:173], v[32:35]
	v_mfma_f32_16x16x32_bf16 v[24:27], v[208:211], v[170:173], v[24:27]
	v_mfma_f32_16x16x32_bf16 v[16:19], v[200:203], v[184:187], v[16:19]
	v_mfma_f32_16x16x32_bf16 v[8:11], v[208:211], v[184:187], v[8:11]
	v_mfma_f32_16x16x32_bf16 v[4:7], v[200:203], v[192:195], v[4:7]
	v_mfma_f32_16x16x32_bf16 v[0:3], v[208:211], v[192:195], v[0:3]
	v_mfma_f32_16x16x32_bf16 v[48:51], v[204:207], v[166:169], v[48:51]
	v_mfma_f32_16x16x32_bf16 v[40:43], v[212:215], v[166:169], v[40:43]
	v_mfma_f32_16x16x32_bf16 v[32:35], v[204:207], v[174:177], v[32:35]
	v_mfma_f32_16x16x32_bf16 v[24:27], v[212:215], v[174:177], v[24:27]
	v_mfma_f32_16x16x32_bf16 v[16:19], v[204:207], v[188:191], v[16:19]
	v_mfma_f32_16x16x32_bf16 v[8:11], v[212:215], v[188:191], v[8:11]
	v_mfma_f32_16x16x32_bf16 v[4:7], v[204:207], v[196:199], v[4:7]
	v_mfma_f32_16x16x32_bf16 v[0:3], v[212:215], v[196:199], v[0:3]
	s_setprio 1
	s_add_i32 s78, s78, 2
	s_add_u32 s14, s14, 0x100
	s_addc_u32 s15, s15, 0
	s_add_u32 s76, s76, 0x100
	s_addc_u32 s77, s77, 0
	s_cmp_gt_u32 s78, 13
	s_barrier
	s_cbranch_scc0 .LBB0_912
; #define PG8_WAIT_V(n) asm volatile("s_waitcnt vmcnt(" #n ")" ::: "memory")
; #define PG8_BAR __builtin_amdgcn_s_barrier()
; DI void store8(bf16_t* p, f32x4 a, f32x4 b) { u32x4 w = {cvt_pk_bf16(a[0], a[1]), cvt_pk_bf16(a[2], a[3]), cvt_pk_bf16(b[0], b[1]), cvt_pk_bf16(b[2], b[3])}; *(u32x4*)p = w; }
; template <class Epi, class Sched>
; __device__ __forceinline__ void gemm_phase(PG8_LAS unsigned char* lds, const Gemm g, const Sched& S, const Epi& E) {
;     ...
;         E(acc, cur, wr, wc, fr, fq); S.done(cur);
;         if (!has_next) break;
; #pragma unroll
;         for (int a = 0; a < 2; ++a)
; #pragma unroll
;             for (int b = 0; b < 2; ++b)
; #pragma unroll
;                 for (int m = 0; m < 4; ++m)
; #pragma unroll
;                     for (int n = 0; n < 2; ++n) acc[a][b][m][n] = (f32x4){0.f, 0.f, 0.f, 0.f};
;         cur = nxt; cA = nA; cB = nB; ++ui;
;     }
;     PG8_WAIT_V(0);
;     if (wr == 0) PG8_BAR;
;     PG8_BAR;
;     DI void operator()(const AccT& acc, const pg8::Unit& u, int wr, int wc, int fr, int fq) const {
;         bf16_t* dst = o + u.pn * 256 + wc * 32 + 8 * fq;
; #pragma unroll
;         for (int ai = 0; ai < 2; ++ai)
; #pragma unroll
;             for (int m = 0; m < 4; ++m) { const size_t row = (size_t)u.pm * 256 + wr * 64 + fr + ai * 128 + m * 16;
; #pragma unroll
;                 for (int bj = 0; bj < 2; ++bj) store8(dst + row * ldc + bj * 128, acc[ai][bj][m][0], acc[ai][bj][m][1]); }
;     }
	s_lshl_b32 s14, s13, 8
	s_ashr_i32 s15, s14, 31
	s_ashr_i32 s13, s12, 31
	v_lshl_add_u64 v[142:143], s[14:15], 1, v[134:135]
	s_lshl_b64 s[12:13], s[12:13], 19
	v_lshl_add_u64 v[142:143], v[142:143], 0, s[12:13]
	v_lshl_add_u64 v[142:143], v[142:143], 0, v[136:137]
	s_mov_b32 s5, 0x8000
	v_cvt_pk_bf16_f32 v124, v124, v125
	v_cvt_pk_bf16_f32 v125, v126, v127
	v_cvt_pk_bf16_f32 v126, v120, v121
	v_cvt_pk_bf16_f32 v127, v122, v123
	global_store_dwordx4 v[142:143], v[124:127], off
	v_cvt_pk_bf16_f32 v112, v112, v113
	v_cvt_pk_bf16_f32 v113, v114, v115
	v_cvt_pk_bf16_f32 v114, v104, v105
	v_cvt_pk_bf16_f32 v115, v106, v107
	global_store_dwordx4 v[142:143], v[112:115], off offset:256
	v_cvt_pk_bf16_f32 v104, v116, v117
	v_cvt_pk_bf16_f32 v105, v118, v119
	v_cvt_pk_bf16_f32 v106, v108, v109
	v_add_co_u32_e32 v108, vcc, s5, v142
	s_mov_b32 s5, 0x10000
	s_nop 0
	v_addc_co_u32_e32 v109, vcc, 0, v143, vcc
	v_cvt_pk_bf16_f32 v107, v110, v111
	global_store_dwordx4 v[108:109], v[104:107], off
	v_cvt_pk_bf16_f32 v96, v96, v97
	v_cvt_pk_bf16_f32 v97, v98, v99
	v_cvt_pk_bf16_f32 v98, v88, v89
	v_cvt_pk_bf16_f32 v99, v90, v91
	global_store_dwordx4 v[108:109], v[96:99], off offset:256
	v_cvt_pk_bf16_f32 v88, v100, v101
	v_cvt_pk_bf16_f32 v89, v102, v103
	v_cvt_pk_bf16_f32 v90, v92, v93
	v_add_co_u32_e32 v92, vcc, s5, v142
	s_mov_b32 s5, 0x18000
	s_nop 0
	v_addc_co_u32_e32 v93, vcc, 0, v143, vcc
	v_cvt_pk_bf16_f32 v91, v94, v95
	global_store_dwordx4 v[92:93], v[88:91], off
	v_cvt_pk_bf16_f32 v80, v80, v81
	v_cvt_pk_bf16_f32 v81, v82, v83
	v_cvt_pk_bf16_f32 v82, v72, v73
	v_cvt_pk_bf16_f32 v83, v74, v75
	global_store_dwordx4 v[92:93], v[80:83], off offset:256
	v_cvt_pk_bf16_f32 v72, v84, v85
	v_cvt_pk_bf16_f32 v73, v86, v87
	v_cvt_pk_bf16_f32 v74, v76, v77
	v_add_co_u32_e32 v76, vcc, s5, v142
	s_mov_b32 s5, 0x40000
	s_nop 0
	v_addc_co_u32_e32 v77, vcc, 0, v143, vcc
	v_cvt_pk_bf16_f32 v75, v78, v79
	global_store_dwordx4 v[76:77], v[72:75], off
	v_cvt_pk_bf16_f32 v68, v68, v69
	v_cvt_pk_bf16_f32 v69, v70, v71
	v_cvt_pk_bf16_f32 v70, v64, v65
	v_cvt_pk_bf16_f32 v71, v66, v67
	global_store_dwordx4 v[76:77], v[68:71], off offset:256
	v_cvt_pk_bf16_f32 v60, v60, v61
	v_cvt_pk_bf16_f32 v61, v62, v63
	v_cvt_pk_bf16_f32 v62, v56, v57
	v_add_co_u32_e32 v56, vcc, s5, v142
	s_mov_b32 s5, 0x48000
	s_nop 0
	v_addc_co_u32_e32 v57, vcc, 0, v143, vcc
	v_cvt_pk_bf16_f32 v63, v58, v59
	global_store_dwordx4 v[56:57], v[60:63], off
	v_cvt_pk_bf16_f32 v48, v48, v49
	v_cvt_pk_bf16_f32 v49, v50, v51
	v_cvt_pk_bf16_f32 v50, v40, v41
	v_cvt_pk_bf16_f32 v51, v42, v43
	global_store_dwordx4 v[56:57], v[48:51], off offset:256
	v_cvt_pk_bf16_f32 v40, v52, v53
	v_cvt_pk_bf16_f32 v41, v54, v55
	v_cvt_pk_bf16_f32 v42, v44, v45
	v_add_co_u32_e32 v44, vcc, s5, v142
	s_mov_b32 s5, 0x50000
	s_nop 0
	v_addc_co_u32_e32 v45, vcc, 0, v143, vcc
	v_cvt_pk_bf16_f32 v43, v46, v47
	global_store_dwordx4 v[44:45], v[40:43], off
	v_cvt_pk_bf16_f32 v32, v32, v33
	v_cvt_pk_bf16_f32 v33, v34, v35
	v_cvt_pk_bf16_f32 v34, v24, v25
	v_cvt_pk_bf16_f32 v35, v26, v27
	global_store_dwordx4 v[44:45], v[32:35], off offset:256
	v_cvt_pk_bf16_f32 v24, v36, v37
	v_cvt_pk_bf16_f32 v25, v38, v39
	v_cvt_pk_bf16_f32 v26, v28, v29
	v_add_co_u32_e32 v28, vcc, s5, v142
	s_mov_b32 s5, 0x58000
	s_nop 0
	v_addc_co_u32_e32 v29, vcc, 0, v143, vcc
	v_cvt_pk_bf16_f32 v27, v30, v31
	global_store_dwordx4 v[28:29], v[24:27], off
	v_cvt_pk_bf16_f32 v16, v16, v17
	v_cvt_pk_bf16_f32 v17, v18, v19
	v_cvt_pk_bf16_f32 v18, v8, v9
	v_cvt_pk_bf16_f32 v19, v10, v11
	global_store_dwordx4 v[28:29], v[16:19], off offset:256
	v_cvt_pk_bf16_f32 v8, v20, v21
	v_cvt_pk_bf16_f32 v9, v22, v23
	v_cvt_pk_bf16_f32 v10, v12, v13
	v_add_co_u32_e32 v12, vcc, s5, v142
	s_mov_b32 s13, s4
	s_nop 0
	v_addc_co_u32_e32 v13, vcc, 0, v143, vcc
	s_and_b64 vcc, exec, s[0:1]
	s_mov_b32 s12, s6
	s_mov_b64 s[16:17], s[10:11]
	s_mov_b64 s[14:15], s[8:9]
	v_cvt_pk_bf16_f32 v11, v14, v15
	global_store_dwordx4 v[12:13], v[8:11], off
	v_cvt_pk_bf16_f32 v4, v4, v5
	v_cvt_pk_bf16_f32 v5, v6, v7
	v_cvt_pk_bf16_f32 v6, v0, v1
	v_cvt_pk_bf16_f32 v7, v2, v3
	global_store_dwordx4 v[12:13], v[4:7], off offset:256
	s_cbranch_vccz .LBB0_909
	s_waitcnt vmcnt(0)
	s_cmpk_gt_u32 s20, 0xff
	s_cbranch_scc1 .LBB0_916
	s_barrier
